# previous + mid-block s_setprio 0/1 pairs removed (one setprio 1 per 16-MFMA block)
# baseline (speedup 1.0000x reference)
.LBB0_197:
	s_ashr_i32 s47, s46, 31
	ds_read_b128 v[18:21], v190
	ds_read_b128 v[22:25], v190 offset:1024
	ds_read_b128 v[26:29], v190 offset:2048
	ds_read_b128 v[30:33], v190 offset:3072
	ds_read_b128 v[2:5], v190 offset:16384
	ds_read_b128 v[6:9], v190 offset:17408
	ds_read_b128 v[10:13], v190 offset:18432
	ds_read_b128 v[14:17], v190 offset:19456
	s_lshl_b64 s[8:9], s[46:47], 20
	s_add_u32 s48, s22, s8
	s_addc_u32 s49, s23, s9
	s_and_b64 s[8:9], s[2:3], exec
	s_cselect_b32 s47, s49, s73
	s_cselect_b32 s70, s48, s72
	s_ashr_i32 s45, s44, 31
	s_lshl_b64 s[8:9], s[44:45], 20
	s_add_u32 s50, s27, s8
	s_addc_u32 s51, s68, s9
	s_and_b64 s[8:9], s[2:3], exec
	s_cselect_b32 s45, s51, s55
	s_cselect_b32 s71, s50, s54
	s_add_u32 s8, s72, 0x80080
	s_addc_u32 s9, s73, 0
	s_mov_b32 m0, s92
	v_lshl_add_u64 v[216:217], s[8:9], 0, v[164:165]
	ds_read_b128 v[180:183], v191
	ds_read_b128 v[184:187], v191 offset:1024
	ds_read_b128 v[192:195], v191 offset:2048
	ds_read_b128 v[196:199], v191 offset:3072
	ds_read_b128 v[200:203], v191 offset:4096
	ds_read_b128 v[204:207], v191 offset:5120
	ds_read_b128 v[208:211], v191 offset:6144
	ds_read_b128 v[212:215], v191 offset:7168
	global_load_lds_dwordx4 v[216:217], off
	v_lshl_add_u64 v[216:217], s[8:9], 0, v[168:169]
	s_mov_b32 m0, s93
	s_nop 0
	global_load_lds_dwordx4 v[216:217], off
	s_waitcnt vmcnt(8)
	s_waitcnt lgkmcnt(0)
	s_setprio 1
	s_barrier
	v_mfma_f32_16x16x128_f8f6f4 v[158:161], v[18:25], v[180:187], 0
	v_mfma_f32_16x16x128_f8f6f4 v[154:157], v[26:33], v[180:187], 0
	v_mfma_f32_16x16x128_f8f6f4 v[146:149], v[26:33], v[192:199], 0
	v_mfma_f32_16x16x128_f8f6f4 v[150:153], v[18:25], v[192:199], 0
	v_mfma_f32_16x16x128_f8f6f4 v[142:145], v[18:25], v[200:207], 0
	v_mfma_f32_16x16x128_f8f6f4 v[138:141], v[26:33], v[200:207], 0
	v_mfma_f32_16x16x128_f8f6f4 v[130:133], v[26:33], v[208:215], 0
	v_mfma_f32_16x16x128_f8f6f4 v[134:137], v[18:25], v[208:215], 0
	v_mfma_f32_16x16x128_f8f6f4 v[102:105], v[2:9], v[208:215], 0
	v_mfma_f32_16x16x128_f8f6f4 v[98:101], v[10:17], v[208:215], 0
	v_mfma_f32_16x16x128_f8f6f4 v[106:109], v[10:17], v[200:207], 0
	v_mfma_f32_16x16x128_f8f6f4 v[110:113], v[2:9], v[200:207], 0
	v_mfma_f32_16x16x128_f8f6f4 v[118:121], v[2:9], v[192:199], 0
	v_mfma_f32_16x16x128_f8f6f4 v[114:117], v[10:17], v[192:199], 0
	v_mfma_f32_16x16x128_f8f6f4 v[122:125], v[10:17], v[180:187], 0
	v_mfma_f32_16x16x128_f8f6f4 v[126:129], v[2:9], v[180:187], 0
	s_barrier
	s_setprio 0
	v_lshl_add_u64 v[180:181], s[54:55], 0, v[166:167]
	s_mov_b32 m0, s77
	v_lshl_add_u64 v[182:183], v[180:181], 0, s[16:17]
	ds_read_b128 v[192:195], v191 offset:16384
	ds_read_b128 v[196:199], v191 offset:17408
	ds_read_b128 v[200:203], v191 offset:18432
	ds_read_b128 v[204:207], v191 offset:19456
	ds_read_b128 v[208:211], v191 offset:20480
	ds_read_b128 v[212:215], v191 offset:21504
	ds_read_b128 v[216:219], v191 offset:22528
	ds_read_b128 v[220:223], v191 offset:23552
	global_load_lds_dwordx4 v[182:183], off
	v_lshl_add_u64 v[182:183], s[54:55], 0, v[170:171]
	s_add_u32 s8, s54, 0x80100
	v_lshl_add_u64 v[184:185], v[182:183], 0, s[16:17]
	s_mov_b32 m0, s78
	s_addc_u32 s9, s55, 0
	global_load_lds_dwordx4 v[184:185], off
	v_lshl_add_u64 v[184:185], s[8:9], 0, v[166:167]
	s_mov_b32 m0, s79
	s_nop 0
	global_load_lds_dwordx4 v[184:185], off
	v_lshl_add_u64 v[184:185], s[8:9], 0, v[170:171]
	s_mov_b32 m0, s80
	s_nop 0
	global_load_lds_dwordx4 v[184:185], off
	v_lshl_add_u64 v[184:185], s[72:73], 0, v[164:165]
	v_lshl_add_u64 v[186:187], v[184:185], 0, s[16:17]
	s_mov_b32 m0, s53
	s_nop 0
	global_load_lds_dwordx4 v[186:187], off
	v_lshl_add_u64 v[186:187], s[72:73], 0, v[168:169]
	v_lshl_add_u64 v[224:225], v[186:187], 0, s[16:17]
	s_mov_b32 m0, s81
	s_nop 0
	global_load_lds_dwordx4 v[224:225], off
	s_waitcnt vmcnt(8)
	s_waitcnt lgkmcnt(0)
	s_setprio 1
	s_barrier
	v_mfma_f32_16x16x128_f8f6f4 v[94:97], v[18:25], v[192:199], 0
	v_mfma_f32_16x16x128_f8f6f4 v[90:93], v[26:33], v[192:199], 0
	v_mfma_f32_16x16x128_f8f6f4 v[82:85], v[26:33], v[200:207], 0
	v_mfma_f32_16x16x128_f8f6f4 v[86:89], v[18:25], v[200:207], 0
	v_mfma_f32_16x16x128_f8f6f4 v[78:81], v[18:25], v[208:215], 0
	v_mfma_f32_16x16x128_f8f6f4 v[74:77], v[26:33], v[208:215], 0
	v_mfma_f32_16x16x128_f8f6f4 v[66:69], v[26:33], v[216:223], 0
	v_mfma_f32_16x16x128_f8f6f4 v[70:73], v[18:25], v[216:223], 0
	v_mfma_f32_16x16x128_f8f6f4 v[38:41], v[2:9], v[216:223], 0
	v_mfma_f32_16x16x128_f8f6f4 v[34:37], v[10:17], v[216:223], 0
	v_mfma_f32_16x16x128_f8f6f4 v[42:45], v[10:17], v[208:215], 0
	v_mfma_f32_16x16x128_f8f6f4 v[46:49], v[2:9], v[208:215], 0
	v_mfma_f32_16x16x128_f8f6f4 v[54:57], v[2:9], v[200:207], 0
	v_mfma_f32_16x16x128_f8f6f4 v[50:53], v[10:17], v[200:207], 0
	v_mfma_f32_16x16x128_f8f6f4 v[58:61], v[10:17], v[192:199], 0
	v_mfma_f32_16x16x128_f8f6f4 v[62:65], v[2:9], v[192:199], 0
	s_barrier
	s_setprio 0
	ds_read_b128 v[18:21], v190 offset:32768
	ds_read_b128 v[22:25], v190 offset:33792
	ds_read_b128 v[26:29], v190 offset:34816
	ds_read_b128 v[30:33], v190 offset:35840
	ds_read_b128 v[2:5], v190 offset:49152
	ds_read_b128 v[6:9], v190 offset:50176
	ds_read_b128 v[10:13], v190 offset:51200
	ds_read_b128 v[14:17], v190 offset:52224
	s_add_u32 s8, s72, 0x80100
	s_addc_u32 s9, s73, 0
	s_mov_b32 m0, s82
	v_lshl_add_u64 v[224:225], s[8:9], 0, v[164:165]
	ds_read_b128 v[192:195], v191 offset:32768
	ds_read_b128 v[196:199], v191 offset:33792
	ds_read_b128 v[200:203], v191 offset:34816
	ds_read_b128 v[204:207], v191 offset:35840
	ds_read_b128 v[208:211], v191 offset:36864
	ds_read_b128 v[212:215], v191 offset:37888
	ds_read_b128 v[216:219], v191 offset:38912
	ds_read_b128 v[220:223], v191 offset:39936
	global_load_lds_dwordx4 v[224:225], off
	v_lshl_add_u64 v[224:225], s[8:9], 0, v[168:169]
	s_mov_b32 m0, s83
	s_nop 0
	global_load_lds_dwordx4 v[224:225], off
	s_waitcnt vmcnt(8)
	s_waitcnt lgkmcnt(0)
	s_setprio 1
	s_barrier
	v_mfma_f32_16x16x128_f8f6f4 v[158:161], v[18:25], v[192:199], v[158:161]
	v_mfma_f32_16x16x128_f8f6f4 v[154:157], v[26:33], v[192:199], v[154:157]
	v_mfma_f32_16x16x128_f8f6f4 v[146:149], v[26:33], v[200:207], v[146:149]
	v_mfma_f32_16x16x128_f8f6f4 v[150:153], v[18:25], v[200:207], v[150:153]
	v_mfma_f32_16x16x128_f8f6f4 v[142:145], v[18:25], v[208:215], v[142:145]
	v_mfma_f32_16x16x128_f8f6f4 v[138:141], v[26:33], v[208:215], v[138:141]
	v_mfma_f32_16x16x128_f8f6f4 v[130:133], v[26:33], v[216:223], v[130:133]
	v_mfma_f32_16x16x128_f8f6f4 v[134:137], v[18:25], v[216:223], v[134:137]
	v_mfma_f32_16x16x128_f8f6f4 v[102:105], v[2:9], v[216:223], v[102:105]
	v_mfma_f32_16x16x128_f8f6f4 v[98:101], v[10:17], v[216:223], v[98:101]
	v_mfma_f32_16x16x128_f8f6f4 v[106:109], v[10:17], v[208:215], v[106:109]
	v_mfma_f32_16x16x128_f8f6f4 v[110:113], v[2:9], v[208:215], v[110:113]
	v_mfma_f32_16x16x128_f8f6f4 v[118:121], v[2:9], v[200:207], v[118:121]
	v_mfma_f32_16x16x128_f8f6f4 v[114:117], v[10:17], v[200:207], v[114:117]
	v_mfma_f32_16x16x128_f8f6f4 v[122:125], v[10:17], v[192:199], v[122:125]
	v_mfma_f32_16x16x128_f8f6f4 v[126:129], v[2:9], v[192:199], v[126:129]
	s_barrier
	s_setprio 0
	s_mov_b32 m0, s86
	v_lshl_add_u64 v[180:181], v[180:181], 0, s[20:21]
	s_add_u32 s8, s54, 0x80180
	ds_read_b128 v[192:195], v191 offset:49152
	ds_read_b128 v[196:199], v191 offset:50176
	ds_read_b128 v[200:203], v191 offset:51200
	ds_read_b128 v[204:207], v191 offset:52224
	ds_read_b128 v[208:211], v191 offset:53248
	ds_read_b128 v[212:215], v191 offset:54272
	ds_read_b128 v[216:219], v191 offset:55296
	ds_read_b128 v[220:223], v191 offset:56320
	global_load_lds_dwordx4 v[180:181], off
	v_lshl_add_u64 v[180:181], v[182:183], 0, s[20:21]
	s_mov_b32 m0, s87
	s_addc_u32 s9, s55, 0
	global_load_lds_dwordx4 v[180:181], off
	v_lshl_add_u64 v[180:181], s[8:9], 0, v[166:167]
	s_mov_b32 m0, s90
	s_nop 0
	global_load_lds_dwordx4 v[180:181], off
	v_lshl_add_u64 v[180:181], s[8:9], 0, v[170:171]
	s_mov_b32 m0, s91
	s_nop 0
	global_load_lds_dwordx4 v[180:181], off
	v_lshl_add_u64 v[180:181], v[184:185], 0, s[20:21]
	s_mov_b32 m0, s88
	s_nop 0
	global_load_lds_dwordx4 v[180:181], off
	v_lshl_add_u64 v[180:181], v[186:187], 0, s[20:21]
	s_mov_b32 m0, s89
	s_nop 0
	global_load_lds_dwordx4 v[180:181], off
	s_waitcnt vmcnt(8)
	s_waitcnt lgkmcnt(0)
	s_setprio 1
	s_barrier
	v_mfma_f32_16x16x128_f8f6f4 v[94:97], v[18:25], v[192:199], v[94:97]
	v_mfma_f32_16x16x128_f8f6f4 v[90:93], v[26:33], v[192:199], v[90:93]
	v_mfma_f32_16x16x128_f8f6f4 v[82:85], v[26:33], v[200:207], v[82:85]
	v_mfma_f32_16x16x128_f8f6f4 v[86:89], v[18:25], v[200:207], v[86:89]
	v_mfma_f32_16x16x128_f8f6f4 v[78:81], v[18:25], v[208:215], v[78:81]
	v_mfma_f32_16x16x128_f8f6f4 v[74:77], v[26:33], v[208:215], v[74:77]
	v_mfma_f32_16x16x128_f8f6f4 v[66:69], v[26:33], v[216:223], v[66:69]
	v_mfma_f32_16x16x128_f8f6f4 v[70:73], v[18:25], v[216:223], v[70:73]
	v_mfma_f32_16x16x128_f8f6f4 v[38:41], v[2:9], v[216:223], v[38:41]
	v_mfma_f32_16x16x128_f8f6f4 v[34:37], v[10:17], v[216:223], v[34:37]
	v_mfma_f32_16x16x128_f8f6f4 v[42:45], v[10:17], v[208:215], v[42:45]
	v_mfma_f32_16x16x128_f8f6f4 v[46:49], v[2:9], v[208:215], v[46:49]
	v_mfma_f32_16x16x128_f8f6f4 v[54:57], v[2:9], v[200:207], v[54:57]
	v_mfma_f32_16x16x128_f8f6f4 v[50:53], v[10:17], v[200:207], v[50:53]
	v_mfma_f32_16x16x128_f8f6f4 v[58:61], v[10:17], v[192:199], v[58:61]
	v_mfma_f32_16x16x128_f8f6f4 v[62:65], v[2:9], v[192:199], v[62:65]
	s_barrier
	s_setprio 0
	s_add_u32 s72, s72, 0x80180
	s_addc_u32 s73, s73, 0
	s_add_u32 s8, s54, 0x200
	s_addc_u32 s9, s55, 0
	s_mov_b32 s62, 0
.LBB0_198:
	ds_read_b128 v[2:5], v190
	ds_read_b128 v[6:9], v190 offset:1024
	ds_read_b128 v[18:21], v190 offset:2048
	ds_read_b128 v[22:25], v190 offset:3072
	ds_read_b128 v[26:29], v190 offset:16384
	ds_read_b128 v[30:33], v190 offset:17408
	ds_read_b128 v[180:183], v190 offset:18432
	ds_read_b128 v[184:187], v190 offset:19456
	s_add_u32 s54, s72, 0xfff80080
	s_addc_u32 s55, s73, -1
	s_cmp_eq_u32 s62, 28
	s_cselect_b32 s75, s47, s55
	s_cselect_b32 s74, s70, s54
	s_cselect_b32 s55, s45, s9
	s_cselect_b32 s54, s71, s8
	s_mov_b32 m0, s92
	v_lshl_add_u64 v[216:217], s[72:73], 0, v[172:173]
	ds_read_b128 v[10:13], v191
	ds_read_b128 v[14:17], v191 offset:1024
	ds_read_b128 v[192:195], v191 offset:2048
	ds_read_b128 v[196:199], v191 offset:3072
	ds_read_b128 v[200:203], v191 offset:4096
	ds_read_b128 v[204:207], v191 offset:5120
	ds_read_b128 v[208:211], v191 offset:6144
	ds_read_b128 v[212:215], v191 offset:7168
	global_load_lds_dwordx4 v[216:217], off
	v_lshl_add_u64 v[216:217], s[72:73], 0, v[174:175]
	s_mov_b32 m0, s93
	s_nop 0
	global_load_lds_dwordx4 v[216:217], off
	s_waitcnt vmcnt(8)
	s_waitcnt lgkmcnt(0)
	s_setprio 1
	s_barrier
	v_mfma_f32_16x16x128_f8f6f4 v[158:161], v[2:9], v[10:17], v[158:161]
	v_mfma_f32_16x16x128_f8f6f4 v[154:157], v[18:25], v[10:17], v[154:157]
	v_mfma_f32_16x16x128_f8f6f4 v[146:149], v[18:25], v[192:199], v[146:149]
	v_mfma_f32_16x16x128_f8f6f4 v[150:153], v[2:9], v[192:199], v[150:153]
	v_mfma_f32_16x16x128_f8f6f4 v[142:145], v[2:9], v[200:207], v[142:145]
	v_mfma_f32_16x16x128_f8f6f4 v[138:141], v[18:25], v[200:207], v[138:141]
	v_mfma_f32_16x16x128_f8f6f4 v[130:133], v[18:25], v[208:215], v[130:133]
	v_mfma_f32_16x16x128_f8f6f4 v[134:137], v[2:9], v[208:215], v[134:137]
	v_mfma_f32_16x16x128_f8f6f4 v[102:105], v[26:33], v[208:215], v[102:105]
	v_mfma_f32_16x16x128_f8f6f4 v[98:101], v[180:187], v[208:215], v[98:101]
	v_mfma_f32_16x16x128_f8f6f4 v[106:109], v[180:187], v[200:207], v[106:109]
	v_mfma_f32_16x16x128_f8f6f4 v[110:113], v[26:33], v[200:207], v[110:113]
	v_mfma_f32_16x16x128_f8f6f4 v[118:121], v[26:33], v[192:199], v[118:121]
	v_mfma_f32_16x16x128_f8f6f4 v[114:117], v[180:187], v[192:199], v[114:117]
	v_mfma_f32_16x16x128_f8f6f4 v[122:125], v[180:187], v[10:17], v[122:125]
	v_mfma_f32_16x16x128_f8f6f4 v[126:129], v[26:33], v[10:17], v[126:129]
	s_barrier
	s_setprio 0
	s_mov_b32 m0, s77
	v_lshl_add_u64 v[10:11], s[54:55], 0, v[166:167]
	s_add_u32 vcc_lo, s54, 0x80000
	ds_read_b128 v[192:195], v191 offset:16384
	ds_read_b128 v[196:199], v191 offset:17408
	ds_read_b128 v[200:203], v191 offset:18432
	ds_read_b128 v[204:207], v191 offset:19456
	ds_read_b128 v[208:211], v191 offset:20480
	ds_read_b128 v[212:215], v191 offset:21504
	ds_read_b128 v[216:219], v191 offset:22528
	ds_read_b128 v[220:223], v191 offset:23552
	global_load_lds_dwordx4 v[10:11], off
	v_lshl_add_u64 v[12:13], s[54:55], 0, v[170:171]
	s_mov_b32 m0, s78
	s_addc_u32 vcc_hi, s55, 0
	global_load_lds_dwordx4 v[12:13], off
	v_lshl_add_u64 v[14:15], vcc, 0, v[166:167]
	s_mov_b32 m0, s79
	v_lshl_add_u64 v[16:17], s[74:75], 0, v[168:169]
	global_load_lds_dwordx4 v[14:15], off
	v_lshl_add_u64 v[14:15], vcc, 0, v[170:171]
	s_mov_b32 m0, s80
	s_nop 0
	global_load_lds_dwordx4 v[14:15], off
	v_lshl_add_u64 v[14:15], s[74:75], 0, v[164:165]
	s_mov_b32 m0, s53
	s_nop 0
	global_load_lds_dwordx4 v[14:15], off
	s_mov_b32 m0, s81
	s_nop 0
	global_load_lds_dwordx4 v[16:17], off
	s_waitcnt vmcnt(8)
	s_waitcnt lgkmcnt(0)
	s_setprio 1
	s_barrier
	v_mfma_f32_16x16x128_f8f6f4 v[94:97], v[2:9], v[192:199], v[94:97]
	v_mfma_f32_16x16x128_f8f6f4 v[90:93], v[18:25], v[192:199], v[90:93]
	v_mfma_f32_16x16x128_f8f6f4 v[82:85], v[18:25], v[200:207], v[82:85]
	v_mfma_f32_16x16x128_f8f6f4 v[86:89], v[2:9], v[200:207], v[86:89]
	v_mfma_f32_16x16x128_f8f6f4 v[78:81], v[2:9], v[208:215], v[78:81]
	v_mfma_f32_16x16x128_f8f6f4 v[74:77], v[18:25], v[208:215], v[74:77]
	v_mfma_f32_16x16x128_f8f6f4 v[66:69], v[18:25], v[216:223], v[66:69]
	v_mfma_f32_16x16x128_f8f6f4 v[70:73], v[2:9], v[216:223], v[70:73]
	v_mfma_f32_16x16x128_f8f6f4 v[38:41], v[26:33], v[216:223], v[38:41]
	v_mfma_f32_16x16x128_f8f6f4 v[34:37], v[180:187], v[216:223], v[34:37]
	v_mfma_f32_16x16x128_f8f6f4 v[42:45], v[180:187], v[208:215], v[42:45]
	v_mfma_f32_16x16x128_f8f6f4 v[46:49], v[26:33], v[208:215], v[46:49]
	v_mfma_f32_16x16x128_f8f6f4 v[54:57], v[26:33], v[200:207], v[54:57]
	v_mfma_f32_16x16x128_f8f6f4 v[50:53], v[180:187], v[200:207], v[50:53]
	v_mfma_f32_16x16x128_f8f6f4 v[58:61], v[180:187], v[192:199], v[58:61]
	v_mfma_f32_16x16x128_f8f6f4 v[62:65], v[26:33], v[192:199], v[62:65]
	s_barrier
	s_setprio 0
	ds_read_b128 v[18:21], v190 offset:32768
	ds_read_b128 v[22:25], v190 offset:33792
	ds_read_b128 v[26:29], v190 offset:34816
	ds_read_b128 v[30:33], v190 offset:35840
	ds_read_b128 v[2:5], v190 offset:49152
	ds_read_b128 v[6:9], v190 offset:50176
	ds_read_b128 v[180:183], v190 offset:51200
	ds_read_b128 v[184:187], v190 offset:52224
	s_add_u32 s74, s74, 0x80000
	s_addc_u32 s75, s75, 0
	s_mov_b32 m0, s82
	v_lshl_add_u64 v[224:225], s[74:75], 0, v[164:165]
	ds_read_b128 v[192:195], v191 offset:32768
	ds_read_b128 v[196:199], v191 offset:33792
	ds_read_b128 v[200:203], v191 offset:34816
	ds_read_b128 v[204:207], v191 offset:35840
	ds_read_b128 v[208:211], v191 offset:36864
	ds_read_b128 v[212:215], v191 offset:37888
	ds_read_b128 v[216:219], v191 offset:38912
	ds_read_b128 v[220:223], v191 offset:39936
	global_load_lds_dwordx4 v[224:225], off
	v_lshl_add_u64 v[224:225], s[74:75], 0, v[168:169]
	s_mov_b32 m0, s83
	s_nop 0
	global_load_lds_dwordx4 v[224:225], off
	s_waitcnt vmcnt(8)
	s_waitcnt lgkmcnt(0)
	s_setprio 1
	s_barrier
	v_mfma_f32_16x16x128_f8f6f4 v[158:161], v[18:25], v[192:199], v[158:161]
	v_mfma_f32_16x16x128_f8f6f4 v[154:157], v[26:33], v[192:199], v[154:157]
	v_mfma_f32_16x16x128_f8f6f4 v[146:149], v[26:33], v[200:207], v[146:149]
	v_mfma_f32_16x16x128_f8f6f4 v[150:153], v[18:25], v[200:207], v[150:153]
	v_mfma_f32_16x16x128_f8f6f4 v[142:145], v[18:25], v[208:215], v[142:145]
	v_mfma_f32_16x16x128_f8f6f4 v[138:141], v[26:33], v[208:215], v[138:141]
	v_mfma_f32_16x16x128_f8f6f4 v[130:133], v[26:33], v[216:223], v[130:133]
	v_mfma_f32_16x16x128_f8f6f4 v[134:137], v[18:25], v[216:223], v[134:137]
	v_mfma_f32_16x16x128_f8f6f4 v[102:105], v[2:9], v[216:223], v[102:105]
	v_mfma_f32_16x16x128_f8f6f4 v[98:101], v[180:187], v[216:223], v[98:101]
	v_mfma_f32_16x16x128_f8f6f4 v[106:109], v[180:187], v[208:215], v[106:109]
	v_mfma_f32_16x16x128_f8f6f4 v[110:113], v[2:9], v[208:215], v[110:113]
	v_mfma_f32_16x16x128_f8f6f4 v[118:121], v[2:9], v[200:207], v[118:121]
	v_mfma_f32_16x16x128_f8f6f4 v[114:117], v[180:187], v[200:207], v[114:117]
	v_mfma_f32_16x16x128_f8f6f4 v[122:125], v[180:187], v[192:199], v[122:125]
	v_mfma_f32_16x16x128_f8f6f4 v[126:129], v[2:9], v[192:199], v[126:129]
	s_barrier
	s_setprio 0
	s_mov_b32 m0, s86
	v_lshl_add_u64 v[10:11], v[10:11], 0, s[4:5]
	s_add_u32 s54, s54, 0x80080
	ds_read_b128 v[192:195], v191 offset:49152
	ds_read_b128 v[196:199], v191 offset:50176
	ds_read_b128 v[200:203], v191 offset:51200
	ds_read_b128 v[204:207], v191 offset:52224
	ds_read_b128 v[208:211], v191 offset:53248
	ds_read_b128 v[212:215], v191 offset:54272
	ds_read_b128 v[216:219], v191 offset:55296
	ds_read_b128 v[220:223], v191 offset:56320
	global_load_lds_dwordx4 v[10:11], off
	v_lshl_add_u64 v[10:11], v[12:13], 0, s[4:5]
	s_mov_b32 m0, s87
	s_addc_u32 s55, s55, 0
	global_load_lds_dwordx4 v[10:11], off
	v_lshl_add_u64 v[10:11], s[54:55], 0, v[166:167]
	s_mov_b32 m0, s90
	s_nop 0
	global_load_lds_dwordx4 v[10:11], off
	v_lshl_add_u64 v[10:11], s[54:55], 0, v[170:171]
	s_mov_b32 m0, s91
	s_nop 0
	global_load_lds_dwordx4 v[10:11], off
	v_lshl_add_u64 v[10:11], v[14:15], 0, s[4:5]
	s_mov_b32 m0, s88
	s_nop 0
	global_load_lds_dwordx4 v[10:11], off
	v_lshl_add_u64 v[10:11], v[16:17], 0, s[4:5]
	s_mov_b32 m0, s89
	s_nop 0
	global_load_lds_dwordx4 v[10:11], off
	s_waitcnt vmcnt(8)
	s_waitcnt lgkmcnt(0)
	s_setprio 1
	s_barrier
	v_mfma_f32_16x16x128_f8f6f4 v[94:97], v[18:25], v[192:199], v[94:97]
	v_mfma_f32_16x16x128_f8f6f4 v[90:93], v[26:33], v[192:199], v[90:93]
	v_mfma_f32_16x16x128_f8f6f4 v[82:85], v[26:33], v[200:207], v[82:85]
	v_mfma_f32_16x16x128_f8f6f4 v[86:89], v[18:25], v[200:207], v[86:89]
	v_mfma_f32_16x16x128_f8f6f4 v[78:81], v[18:25], v[208:215], v[78:81]
	v_mfma_f32_16x16x128_f8f6f4 v[74:77], v[26:33], v[208:215], v[74:77]
	v_mfma_f32_16x16x128_f8f6f4 v[66:69], v[26:33], v[216:223], v[66:69]
	v_mfma_f32_16x16x128_f8f6f4 v[70:73], v[18:25], v[216:223], v[70:73]
	v_mfma_f32_16x16x128_f8f6f4 v[38:41], v[2:9], v[216:223], v[38:41]
	v_mfma_f32_16x16x128_f8f6f4 v[34:37], v[180:187], v[216:223], v[34:37]
	v_mfma_f32_16x16x128_f8f6f4 v[42:45], v[180:187], v[208:215], v[42:45]
	v_mfma_f32_16x16x128_f8f6f4 v[46:49], v[2:9], v[208:215], v[46:49]
	v_mfma_f32_16x16x128_f8f6f4 v[54:57], v[2:9], v[200:207], v[54:57]
	v_mfma_f32_16x16x128_f8f6f4 v[50:53], v[180:187], v[200:207], v[50:53]
	v_mfma_f32_16x16x128_f8f6f4 v[58:61], v[180:187], v[192:199], v[58:61]
	v_mfma_f32_16x16x128_f8f6f4 v[62:65], v[2:9], v[192:199], v[62:65]
	s_barrier
	s_setprio 0
	s_add_i32 s62, s62, 2
	s_add_u32 s72, s72, 0x100
	s_addc_u32 s73, s73, 0
	s_add_u32 s8, s8, 0x100
	s_addc_u32 s9, s9, 0
	s_cmp_gt_u32 s62, 29
	s_cbranch_scc0 .LBB0_198
	s_and_b64 vcc, exec, s[6:7]
	s_cbranch_vccz .LBB0_201
	s_barrier

.LBB0_282:
	ds_read_b128 v[2:5], v187
	ds_read_b128 v[6:9], v187 offset:1024
	ds_read_b128 v[174:177], v187 offset:2048
	ds_read_b128 v[178:181], v187 offset:3072
	ds_read_b128 v[190:193], v187 offset:16384
	ds_read_b128 v[194:197], v187 offset:17408
	ds_read_b128 v[198:201], v187 offset:18432
	ds_read_b128 v[202:205], v187 offset:19456
	s_add_u32 s49, s52, 0x100
	s_addc_u32 s71, s53, 0
	s_and_b64 s[62:63], s[54:55], exec
	s_cselect_b32 s73, s1, s71
	s_cselect_b32 s72, s0, s49
	s_add_u32 s49, s50, 0x100
	s_addc_u32 s62, s51, 0
	s_and_b64 s[54:55], s[54:55], exec
	s_cselect_b32 s55, s5, s62
	s_cselect_b32 s54, s4, s49
	s_add_u32 s62, s52, 0x158080
	s_addc_u32 s63, s53, 0
	s_add_i32 s49, s33, 0xc000
	v_lshl_add_u64 v[182:183], s[62:63], 0, v[154:155]
	s_mov_b32 m0, s49
	s_add_i32 s71, s33, 0xe000
	ds_read_b128 v[206:209], v188
	ds_read_b128 v[210:213], v188 offset:1024
	ds_read_b128 v[214:217], v188 offset:2048
	ds_read_b128 v[218:221], v188 offset:3072
	ds_read_b128 v[222:225], v188 offset:4096
	ds_read_b128 v[226:229], v188 offset:5120
	ds_read_b128 v[230:233], v188 offset:6144
	ds_read_b128 v[234:237], v188 offset:7168
	global_load_lds_dwordx4 v[182:183], off
	v_lshl_add_u64 v[182:183], s[62:63], 0, v[158:159]
	s_mov_b32 m0, s71
	s_nop 0
	global_load_lds_dwordx4 v[182:183], off
	s_waitcnt vmcnt(8)
	s_waitcnt lgkmcnt(0)
	s_setprio 1
	s_barrier
	v_mfma_f32_16x16x128_f8f6f4 v[134:137], v[2:9], v[206:213], 0
	v_mfma_f32_16x16x128_f8f6f4 v[130:133], v[174:181], v[206:213], 0
	v_mfma_f32_16x16x128_f8f6f4 v[122:125], v[174:181], v[214:221], 0
	v_mfma_f32_16x16x128_f8f6f4 v[126:129], v[2:9], v[214:221], 0
	v_mfma_f32_16x16x128_f8f6f4 v[118:121], v[2:9], v[222:229], 0
	v_mfma_f32_16x16x128_f8f6f4 v[114:117], v[174:181], v[222:229], 0
	v_mfma_f32_16x16x128_f8f6f4 v[106:109], v[174:181], v[230:237], 0
	v_mfma_f32_16x16x128_f8f6f4 v[110:113], v[2:9], v[230:237], 0
	v_mfma_f32_16x16x128_f8f6f4 v[78:81], v[190:197], v[230:237], 0
	v_mfma_f32_16x16x128_f8f6f4 v[74:77], v[198:205], v[230:237], 0
	v_mfma_f32_16x16x128_f8f6f4 v[82:85], v[198:205], v[222:229], 0
	v_mfma_f32_16x16x128_f8f6f4 v[86:89], v[190:197], v[222:229], 0
	v_mfma_f32_16x16x128_f8f6f4 v[94:97], v[190:197], v[214:221], 0
	v_mfma_f32_16x16x128_f8f6f4 v[90:93], v[198:205], v[214:221], 0
	v_mfma_f32_16x16x128_f8f6f4 v[98:101], v[198:205], v[206:213], 0
	v_mfma_f32_16x16x128_f8f6f4 v[102:105], v[190:197], v[206:213], 0
	s_barrier
	s_setprio 0
	s_mov_b32 m0, s47
	v_lshl_add_u64 v[182:183], s[54:55], 0, v[156:157]
	s_add_u32 s62, s54, 0x158000
	ds_read_b128 v[206:209], v188 offset:16384
	ds_read_b128 v[210:213], v188 offset:17408
	ds_read_b128 v[214:217], v188 offset:18432
	ds_read_b128 v[218:221], v188 offset:19456
	ds_read_b128 v[222:225], v188 offset:20480
	ds_read_b128 v[226:229], v188 offset:21504
	ds_read_b128 v[230:233], v188 offset:22528
	ds_read_b128 v[234:237], v188 offset:23552
	global_load_lds_dwordx4 v[182:183], off
	v_lshl_add_u64 v[238:239], s[54:55], 0, v[160:161]
	s_mov_b32 m0, s68
	s_addc_u32 s63, s55, 0
	global_load_lds_dwordx4 v[238:239], off
	v_lshl_add_u64 v[242:243], s[62:63], 0, v[156:157]
	s_mov_b32 m0, s69
	v_lshl_add_u64 v[244:245], s[72:73], 0, v[158:159]
	global_load_lds_dwordx4 v[242:243], off
	v_lshl_add_u64 v[242:243], s[62:63], 0, v[160:161]
	s_mov_b32 m0, s74
	s_nop 0
	global_load_lds_dwordx4 v[242:243], off
	v_lshl_add_u64 v[242:243], s[72:73], 0, v[154:155]
	s_mov_b32 m0, s33
	s_nop 0
	global_load_lds_dwordx4 v[242:243], off
	s_mov_b32 m0, s75
	s_nop 0
	global_load_lds_dwordx4 v[244:245], off
	s_waitcnt vmcnt(8)
	s_waitcnt lgkmcnt(0)
	s_setprio 1
	s_barrier
	v_mfma_f32_16x16x128_f8f6f4 v[70:73], v[2:9], v[206:213], 0
	v_mfma_f32_16x16x128_f8f6f4 v[66:69], v[174:181], v[206:213], 0
	v_mfma_f32_16x16x128_f8f6f4 v[58:61], v[174:181], v[214:221], 0
	v_mfma_f32_16x16x128_f8f6f4 v[62:65], v[2:9], v[214:221], 0
	v_mfma_f32_16x16x128_f8f6f4 v[54:57], v[2:9], v[222:229], 0
	v_mfma_f32_16x16x128_f8f6f4 v[50:53], v[174:181], v[222:229], 0
	v_mfma_f32_16x16x128_f8f6f4 v[42:45], v[174:181], v[230:237], 0
	v_mfma_f32_16x16x128_f8f6f4 v[46:49], v[2:9], v[230:237], 0
	v_mfma_f32_16x16x128_f8f6f4 v[14:17], v[190:197], v[230:237], 0
	v_mfma_f32_16x16x128_f8f6f4 v[10:13], v[198:205], v[230:237], 0
	v_mfma_f32_16x16x128_f8f6f4 v[18:21], v[198:205], v[222:229], 0
	v_mfma_f32_16x16x128_f8f6f4 v[22:25], v[190:197], v[222:229], 0
	v_mfma_f32_16x16x128_f8f6f4 v[30:33], v[190:197], v[214:221], 0
	v_mfma_f32_16x16x128_f8f6f4 v[26:29], v[198:205], v[214:221], 0
	v_mfma_f32_16x16x128_f8f6f4 v[34:37], v[198:205], v[206:213], 0
	v_mfma_f32_16x16x128_f8f6f4 v[38:41], v[190:197], v[206:213], 0
	s_barrier
	s_setprio 0
	ds_read_b128 v[2:5], v187 offset:32768
	ds_read_b128 v[6:9], v187 offset:33792
	ds_read_b128 v[174:177], v187 offset:34816
	ds_read_b128 v[178:181], v187 offset:35840
	ds_read_b128 v[190:193], v187 offset:49152
	ds_read_b128 v[194:197], v187 offset:50176
	ds_read_b128 v[198:201], v187 offset:51200
	ds_read_b128 v[202:205], v187 offset:52224
	s_add_u32 s62, s72, 0x158000
	s_addc_u32 s63, s73, 0
	s_mov_b32 m0, s76
	v_lshl_add_u64 v[246:247], s[62:63], 0, v[154:155]
	ds_read_b128 v[206:209], v188 offset:32768
	ds_read_b128 v[210:213], v188 offset:33792
	ds_read_b128 v[214:217], v188 offset:34816
	ds_read_b128 v[218:221], v188 offset:35840
	ds_read_b128 v[222:225], v188 offset:36864
	ds_read_b128 v[226:229], v188 offset:37888
	ds_read_b128 v[230:233], v188 offset:38912
	ds_read_b128 v[234:237], v188 offset:39936
	global_load_lds_dwordx4 v[246:247], off
	v_lshl_add_u64 v[246:247], s[62:63], 0, v[158:159]
	s_mov_b32 m0, s77
	s_nop 0
	global_load_lds_dwordx4 v[246:247], off
	s_waitcnt vmcnt(8)
	s_waitcnt lgkmcnt(0)
	s_setprio 1
	s_barrier
	v_mfma_f32_16x16x128_f8f6f4 v[134:137], v[2:9], v[206:213], v[134:137]
	v_mfma_f32_16x16x128_f8f6f4 v[130:133], v[174:181], v[206:213], v[130:133]
	v_mfma_f32_16x16x128_f8f6f4 v[122:125], v[174:181], v[214:221], v[122:125]
	v_mfma_f32_16x16x128_f8f6f4 v[126:129], v[2:9], v[214:221], v[126:129]
	v_mfma_f32_16x16x128_f8f6f4 v[118:121], v[2:9], v[222:229], v[118:121]
	v_mfma_f32_16x16x128_f8f6f4 v[114:117], v[174:181], v[222:229], v[114:117]
	v_mfma_f32_16x16x128_f8f6f4 v[106:109], v[174:181], v[230:237], v[106:109]
	v_mfma_f32_16x16x128_f8f6f4 v[110:113], v[2:9], v[230:237], v[110:113]
	v_mfma_f32_16x16x128_f8f6f4 v[78:81], v[190:197], v[230:237], v[78:81]
	v_mfma_f32_16x16x128_f8f6f4 v[74:77], v[198:205], v[230:237], v[74:77]
	v_mfma_f32_16x16x128_f8f6f4 v[82:85], v[198:205], v[222:229], v[82:85]
	v_mfma_f32_16x16x128_f8f6f4 v[86:89], v[190:197], v[222:229], v[86:89]
	v_mfma_f32_16x16x128_f8f6f4 v[94:97], v[190:197], v[214:221], v[94:97]
	v_mfma_f32_16x16x128_f8f6f4 v[90:93], v[198:205], v[214:221], v[90:93]
	v_mfma_f32_16x16x128_f8f6f4 v[98:101], v[198:205], v[206:213], v[98:101]
	v_mfma_f32_16x16x128_f8f6f4 v[102:105], v[190:197], v[206:213], v[102:105]
	s_barrier
	s_setprio 0
	s_mov_b32 m0, s83
	v_lshl_add_u64 v[182:183], v[182:183], 0, s[26:27]
	s_add_u32 s54, s54, 0x158080
	ds_read_b128 v[206:209], v188 offset:49152
	ds_read_b128 v[210:213], v188 offset:50176
	ds_read_b128 v[214:217], v188 offset:51200
	ds_read_b128 v[218:221], v188 offset:52224
	ds_read_b128 v[222:225], v188 offset:53248
	ds_read_b128 v[226:229], v188 offset:54272
	ds_read_b128 v[230:233], v188 offset:55296
	ds_read_b128 v[234:237], v188 offset:56320
	global_load_lds_dwordx4 v[182:183], off
	v_lshl_add_u64 v[182:183], v[238:239], 0, s[26:27]
	s_mov_b32 m0, s84
	s_addc_u32 s55, s55, 0
	global_load_lds_dwordx4 v[182:183], off
	v_lshl_add_u64 v[182:183], s[54:55], 0, v[156:157]
	s_mov_b32 m0, s87
	s_nop 0
	global_load_lds_dwordx4 v[182:183], off
	v_lshl_add_u64 v[182:183], s[54:55], 0, v[160:161]
	s_mov_b32 m0, s88
	s_nop 0
	global_load_lds_dwordx4 v[182:183], off
	v_lshl_add_u64 v[182:183], v[242:243], 0, s[26:27]
	s_mov_b32 m0, s85
	s_nop 0
	global_load_lds_dwordx4 v[182:183], off
	v_lshl_add_u64 v[182:183], v[244:245], 0, s[26:27]
	s_mov_b32 m0, s86
	s_nop 0
	global_load_lds_dwordx4 v[182:183], off
	s_waitcnt vmcnt(8)
	s_waitcnt lgkmcnt(0)
	s_setprio 1
	s_barrier
	v_mfma_f32_16x16x128_f8f6f4 v[70:73], v[2:9], v[206:213], v[70:73]
	v_mfma_f32_16x16x128_f8f6f4 v[66:69], v[174:181], v[206:213], v[66:69]
	v_mfma_f32_16x16x128_f8f6f4 v[58:61], v[174:181], v[214:221], v[58:61]
	v_mfma_f32_16x16x128_f8f6f4 v[62:65], v[2:9], v[214:221], v[62:65]
	v_mfma_f32_16x16x128_f8f6f4 v[54:57], v[2:9], v[222:229], v[54:57]
	v_mfma_f32_16x16x128_f8f6f4 v[50:53], v[174:181], v[222:229], v[50:53]
	v_mfma_f32_16x16x128_f8f6f4 v[42:45], v[174:181], v[230:237], v[42:45]
	v_mfma_f32_16x16x128_f8f6f4 v[46:49], v[2:9], v[230:237], v[46:49]
	v_mfma_f32_16x16x128_f8f6f4 v[14:17], v[190:197], v[230:237], v[14:17]
	v_mfma_f32_16x16x128_f8f6f4 v[10:13], v[198:205], v[230:237], v[10:13]
	v_mfma_f32_16x16x128_f8f6f4 v[18:21], v[198:205], v[222:229], v[18:21]
	v_mfma_f32_16x16x128_f8f6f4 v[22:25], v[190:197], v[222:229], v[22:25]
	v_mfma_f32_16x16x128_f8f6f4 v[30:33], v[190:197], v[214:221], v[30:33]
	v_mfma_f32_16x16x128_f8f6f4 v[26:29], v[198:205], v[214:221], v[26:29]
	v_mfma_f32_16x16x128_f8f6f4 v[34:37], v[198:205], v[206:213], v[34:37]
	v_mfma_f32_16x16x128_f8f6f4 v[38:41], v[190:197], v[206:213], v[38:41]
	s_barrier
	s_setprio 0
	s_cmp_lt_u32 s95, 3
	s_cbranch_scc1 .LBB0_287
	s_add_u32 s54, s79, s9
	s_addc_u32 s55, s80, s8
	s_add_u32 s52, s52, 0x158180
	s_addc_u32 s53, s53, 0
	s_add_u32 s8, s50, 0x200
	v_lshl_add_u64 v[174:175], v[172:173], 2, s[54:55]
	s_addc_u32 s9, s51, 0
	s_mov_b32 s72, 4
	s_cmp_eq_u32 s95, s72
	s_cselect_b64 s[50:51], -1, 0
	s_cmp_lg_u32 s95, s72
	s_cbranch_scc1 .LBB0_285

.LBB0_285:
	ds_read_b128 v[2:5], v187
	ds_read_b128 v[6:9], v187 offset:1024
	ds_read_b128 v[190:193], v187 offset:2048
	ds_read_b128 v[194:197], v187 offset:3072
	ds_read_b128 v[198:201], v187 offset:16384
	ds_read_b128 v[202:205], v187 offset:17408
	ds_read_b128 v[206:209], v187 offset:18432
	ds_read_b128 v[210:213], v187 offset:19456
	s_add_u32 s54, s52, 0xffea8080
	s_addc_u32 s55, s53, -1
	s_and_b64 s[50:51], s[50:51], exec
	s_cselect_b32 s50, s4, s8
	s_cselect_b32 s55, s1, s55
	s_cselect_b32 s54, s0, s54
	s_cselect_b32 s51, s5, s9
	s_mov_b32 m0, s49
	v_lshl_add_u64 v[238:239], s[52:53], 0, v[162:163]
	ds_read_b128 v[176:179], v188
	ds_read_b128 v[180:183], v188 offset:1024
	ds_read_b128 v[214:217], v188 offset:2048
	ds_read_b128 v[218:221], v188 offset:3072
	ds_read_b128 v[222:225], v188 offset:4096
	ds_read_b128 v[226:229], v188 offset:5120
	ds_read_b128 v[230:233], v188 offset:6144
	ds_read_b128 v[234:237], v188 offset:7168
	global_load_lds_dwordx4 v[238:239], off
	v_lshl_add_u64 v[238:239], s[52:53], 0, v[164:165]
	s_mov_b32 m0, s71
	s_nop 0
	global_load_lds_dwordx4 v[238:239], off
	s_waitcnt vmcnt(8)
	s_waitcnt lgkmcnt(0)
	s_setprio 1
	s_barrier
	v_mfma_f32_16x16x128_f8f6f4 v[134:137], v[2:9], v[176:183], v[134:137]
	v_mfma_f32_16x16x128_f8f6f4 v[130:133], v[190:197], v[176:183], v[130:133]
	v_mfma_f32_16x16x128_f8f6f4 v[122:125], v[190:197], v[214:221], v[122:125]
	v_mfma_f32_16x16x128_f8f6f4 v[126:129], v[2:9], v[214:221], v[126:129]
	v_mfma_f32_16x16x128_f8f6f4 v[118:121], v[2:9], v[222:229], v[118:121]
	v_mfma_f32_16x16x128_f8f6f4 v[114:117], v[190:197], v[222:229], v[114:117]
	v_mfma_f32_16x16x128_f8f6f4 v[106:109], v[190:197], v[230:237], v[106:109]
	v_mfma_f32_16x16x128_f8f6f4 v[110:113], v[2:9], v[230:237], v[110:113]
	v_mfma_f32_16x16x128_f8f6f4 v[78:81], v[198:205], v[230:237], v[78:81]
	v_mfma_f32_16x16x128_f8f6f4 v[74:77], v[206:213], v[230:237], v[74:77]
	v_mfma_f32_16x16x128_f8f6f4 v[82:85], v[206:213], v[222:229], v[82:85]
	v_mfma_f32_16x16x128_f8f6f4 v[86:89], v[198:205], v[222:229], v[86:89]
	v_mfma_f32_16x16x128_f8f6f4 v[94:97], v[198:205], v[214:221], v[94:97]
	v_mfma_f32_16x16x128_f8f6f4 v[90:93], v[206:213], v[214:221], v[90:93]
	v_mfma_f32_16x16x128_f8f6f4 v[98:101], v[206:213], v[176:183], v[98:101]
	v_mfma_f32_16x16x128_f8f6f4 v[102:105], v[198:205], v[176:183], v[102:105]
	s_barrier
	s_setprio 0
	s_mov_b32 m0, s47
	v_lshl_add_u64 v[176:177], s[50:51], 0, v[156:157]
	s_add_u32 s62, s50, 0x158000
	ds_read_b128 v[214:217], v188 offset:16384
	ds_read_b128 v[218:221], v188 offset:17408
	ds_read_b128 v[222:225], v188 offset:18432
	ds_read_b128 v[226:229], v188 offset:19456
	ds_read_b128 v[230:233], v188 offset:20480
	ds_read_b128 v[234:237], v188 offset:21504
	ds_read_b128 v[242:245], v188 offset:22528
	ds_read_b128 v[246:249], v188 offset:23552
	global_load_lds_dwordx4 v[176:177], off
	v_lshl_add_u64 v[178:179], s[50:51], 0, v[160:161]
	s_mov_b32 m0, s68
	s_addc_u32 s63, s51, 0
	global_load_lds_dwordx4 v[178:179], off
	v_lshl_add_u64 v[180:181], s[62:63], 0, v[156:157]
	s_mov_b32 m0, s69
	v_lshl_add_u64 v[182:183], s[54:55], 0, v[158:159]
	global_load_lds_dwordx4 v[180:181], off
	v_lshl_add_u64 v[180:181], s[62:63], 0, v[160:161]
	s_mov_b32 m0, s74
	s_nop 0
	global_load_lds_dwordx4 v[180:181], off
	v_lshl_add_u64 v[180:181], s[54:55], 0, v[154:155]
	s_mov_b32 m0, s33
	s_nop 0
	global_load_lds_dwordx4 v[180:181], off
	s_mov_b32 m0, s75
	s_nop 0
	global_load_lds_dwordx4 v[182:183], off
	s_waitcnt vmcnt(8)
	s_waitcnt lgkmcnt(0)
	s_setprio 1
	s_barrier
	v_mfma_f32_16x16x128_f8f6f4 v[70:73], v[2:9], v[214:221], v[70:73]
	v_mfma_f32_16x16x128_f8f6f4 v[66:69], v[190:197], v[214:221], v[66:69]
	v_mfma_f32_16x16x128_f8f6f4 v[58:61], v[190:197], v[222:229], v[58:61]
	v_mfma_f32_16x16x128_f8f6f4 v[62:65], v[2:9], v[222:229], v[62:65]
	v_mfma_f32_16x16x128_f8f6f4 v[54:57], v[2:9], v[230:237], v[54:57]
	v_mfma_f32_16x16x128_f8f6f4 v[50:53], v[190:197], v[230:237], v[50:53]
	v_mfma_f32_16x16x128_f8f6f4 v[42:45], v[190:197], v[242:249], v[42:45]
	v_mfma_f32_16x16x128_f8f6f4 v[46:49], v[2:9], v[242:249], v[46:49]
	v_mfma_f32_16x16x128_f8f6f4 v[14:17], v[198:205], v[242:249], v[14:17]
	v_mfma_f32_16x16x128_f8f6f4 v[10:13], v[206:213], v[242:249], v[10:13]
	v_mfma_f32_16x16x128_f8f6f4 v[18:21], v[206:213], v[230:237], v[18:21]
	v_mfma_f32_16x16x128_f8f6f4 v[22:25], v[198:205], v[230:237], v[22:25]
	v_mfma_f32_16x16x128_f8f6f4 v[30:33], v[198:205], v[222:229], v[30:33]
	v_mfma_f32_16x16x128_f8f6f4 v[26:29], v[206:213], v[222:229], v[26:29]
	v_mfma_f32_16x16x128_f8f6f4 v[34:37], v[206:213], v[214:221], v[34:37]
	v_mfma_f32_16x16x128_f8f6f4 v[38:41], v[198:205], v[214:221], v[38:41]
	s_barrier
	s_setprio 0
	ds_read_b128 v[190:193], v187 offset:32768
	ds_read_b128 v[194:197], v187 offset:33792
	ds_read_b128 v[198:201], v187 offset:34816
	ds_read_b128 v[202:205], v187 offset:35840
	ds_read_b128 v[2:5], v187 offset:49152
	ds_read_b128 v[6:9], v187 offset:50176
	ds_read_b128 v[206:209], v187 offset:51200
	ds_read_b128 v[210:213], v187 offset:52224
	s_add_u32 s54, s54, 0x158000
	s_addc_u32 s55, s55, 0
	s_mov_b32 m0, s76
	v_lshl_add_u64 v[238:239], s[54:55], 0, v[154:155]
	ds_read_b128 v[214:217], v188 offset:32768
	ds_read_b128 v[218:221], v188 offset:33792
	ds_read_b128 v[222:225], v188 offset:34816
	ds_read_b128 v[226:229], v188 offset:35840
	ds_read_b128 v[230:233], v188 offset:36864
	ds_read_b128 v[234:237], v188 offset:37888
	ds_read_b128 v[242:245], v188 offset:38912
	ds_read_b128 v[246:249], v188 offset:39936
	global_load_lds_dwordx4 v[238:239], off
	v_lshl_add_u64 v[238:239], s[54:55], 0, v[158:159]
	s_mov_b32 m0, s77
	s_nop 0
	global_load_lds_dwordx4 v[238:239], off
	s_waitcnt vmcnt(8)
	s_waitcnt lgkmcnt(0)
	s_setprio 1
	s_barrier
	v_mfma_f32_16x16x128_f8f6f4 v[134:137], v[190:197], v[214:221], v[134:137]
	v_mfma_f32_16x16x128_f8f6f4 v[130:133], v[198:205], v[214:221], v[130:133]
	v_mfma_f32_16x16x128_f8f6f4 v[122:125], v[198:205], v[222:229], v[122:125]
	v_mfma_f32_16x16x128_f8f6f4 v[126:129], v[190:197], v[222:229], v[126:129]
	v_mfma_f32_16x16x128_f8f6f4 v[118:121], v[190:197], v[230:237], v[118:121]
	v_mfma_f32_16x16x128_f8f6f4 v[114:117], v[198:205], v[230:237], v[114:117]
	v_mfma_f32_16x16x128_f8f6f4 v[106:109], v[198:205], v[242:249], v[106:109]
	v_mfma_f32_16x16x128_f8f6f4 v[110:113], v[190:197], v[242:249], v[110:113]
	v_mfma_f32_16x16x128_f8f6f4 v[78:81], v[2:9], v[242:249], v[78:81]
	v_mfma_f32_16x16x128_f8f6f4 v[74:77], v[206:213], v[242:249], v[74:77]
	v_mfma_f32_16x16x128_f8f6f4 v[82:85], v[206:213], v[230:237], v[82:85]
	v_mfma_f32_16x16x128_f8f6f4 v[86:89], v[2:9], v[230:237], v[86:89]
	v_mfma_f32_16x16x128_f8f6f4 v[94:97], v[2:9], v[222:229], v[94:97]
	v_mfma_f32_16x16x128_f8f6f4 v[90:93], v[206:213], v[222:229], v[90:93]
	v_mfma_f32_16x16x128_f8f6f4 v[98:101], v[206:213], v[214:221], v[98:101]
	v_mfma_f32_16x16x128_f8f6f4 v[102:105], v[2:9], v[214:221], v[102:105]
	s_barrier
	s_setprio 0
	s_mov_b32 m0, s83
	v_lshl_add_u64 v[176:177], v[176:177], 0, s[26:27]
	s_add_u32 s50, s50, 0x158080
	ds_read_b128 v[214:217], v188 offset:49152
	ds_read_b128 v[218:221], v188 offset:50176
	ds_read_b128 v[222:225], v188 offset:51200
	ds_read_b128 v[226:229], v188 offset:52224
	ds_read_b128 v[230:233], v188 offset:53248
	ds_read_b128 v[234:237], v188 offset:54272
	ds_read_b128 v[242:245], v188 offset:55296
	ds_read_b128 v[246:249], v188 offset:56320
	global_load_lds_dwordx4 v[176:177], off
	v_lshl_add_u64 v[176:177], v[178:179], 0, s[26:27]
	s_mov_b32 m0, s84
	s_addc_u32 s51, s51, 0
	global_load_lds_dwordx4 v[176:177], off
	v_lshl_add_u64 v[176:177], s[50:51], 0, v[156:157]
	s_mov_b32 m0, s87
	s_nop 0
	global_load_lds_dwordx4 v[176:177], off
	v_lshl_add_u64 v[176:177], s[50:51], 0, v[160:161]
	s_mov_b32 m0, s88
	s_nop 0
	global_load_lds_dwordx4 v[176:177], off
	v_lshl_add_u64 v[176:177], v[180:181], 0, s[26:27]
	s_mov_b32 m0, s85
	s_nop 0
	global_load_lds_dwordx4 v[176:177], off
	v_lshl_add_u64 v[176:177], v[182:183], 0, s[26:27]
	s_mov_b32 m0, s86
	s_nop 0
	global_load_lds_dwordx4 v[176:177], off
	s_waitcnt vmcnt(8)
	s_waitcnt lgkmcnt(0)
	s_setprio 1
	s_barrier
	v_mfma_f32_16x16x128_f8f6f4 v[70:73], v[190:197], v[214:221], v[70:73]
	v_mfma_f32_16x16x128_f8f6f4 v[66:69], v[198:205], v[214:221], v[66:69]
	v_mfma_f32_16x16x128_f8f6f4 v[58:61], v[198:205], v[222:229], v[58:61]
	v_mfma_f32_16x16x128_f8f6f4 v[62:65], v[190:197], v[222:229], v[62:65]
	v_mfma_f32_16x16x128_f8f6f4 v[54:57], v[190:197], v[230:237], v[54:57]
	v_mfma_f32_16x16x128_f8f6f4 v[50:53], v[198:205], v[230:237], v[50:53]
	v_mfma_f32_16x16x128_f8f6f4 v[42:45], v[198:205], v[242:249], v[42:45]
	v_mfma_f32_16x16x128_f8f6f4 v[46:49], v[190:197], v[242:249], v[46:49]
	v_mfma_f32_16x16x128_f8f6f4 v[14:17], v[2:9], v[242:249], v[14:17]
	v_mfma_f32_16x16x128_f8f6f4 v[10:13], v[206:213], v[242:249], v[10:13]
	v_mfma_f32_16x16x128_f8f6f4 v[18:21], v[206:213], v[230:237], v[18:21]
	v_mfma_f32_16x16x128_f8f6f4 v[22:25], v[2:9], v[230:237], v[22:25]
	v_mfma_f32_16x16x128_f8f6f4 v[30:33], v[2:9], v[222:229], v[30:33]
	v_mfma_f32_16x16x128_f8f6f4 v[26:29], v[206:213], v[222:229], v[26:29]
	v_mfma_f32_16x16x128_f8f6f4 v[34:37], v[206:213], v[214:221], v[34:37]
	v_mfma_f32_16x16x128_f8f6f4 v[38:41], v[2:9], v[214:221], v[38:41]
	s_barrier
	s_setprio 0
	s_add_i32 s50, s72, 2
	s_add_u32 s52, s52, 0x100
	s_addc_u32 s53, s53, 0
	s_add_u32 s8, s8, 0x100
	s_addc_u32 s9, s9, 0
	s_cmp_ge_i32 s72, s95
	s_cbranch_scc1 .LBB0_287
	s_mov_b32 s72, s50
	s_cmp_eq_u32 s95, s72
	s_cselect_b64 s[50:51], -1, 0
	s_cmp_lg_u32 s95, s72
	s_cbranch_scc0 .LBB0_284
	s_branch .LBB0_285

.LBB0_437:
	s_ashr_i32 s47, s46, 31
	ds_read_b128 v[18:21], v200
	ds_read_b128 v[22:25], v200 offset:1024
	ds_read_b128 v[26:29], v200 offset:2048
	ds_read_b128 v[30:33], v200 offset:3072
	ds_read_b128 v[2:5], v200 offset:16384
	ds_read_b128 v[6:9], v200 offset:17408
	ds_read_b128 v[10:13], v200 offset:18432
	ds_read_b128 v[14:17], v200 offset:19456
	s_lshl_b64 s[8:9], s[46:47], 20
	s_add_u32 s48, s12, s8
	s_addc_u32 s49, s13, s9
	s_and_b64 s[8:9], s[2:3], exec
	s_cselect_b32 s47, s49, s73
	s_cselect_b32 s71, s48, s72
	s_ashr_i32 s45, s44, 31
	s_lshl_b64 s[8:9], s[44:45], 20
	s_add_u32 s50, s39, s8
	s_addc_u32 s51, s76, s9
	s_and_b64 s[8:9], s[2:3], exec
	s_cselect_b32 s45, s51, s55
	s_cselect_b32 s94, s50, s54
	s_add_u32 s8, s72, 0x80080
	s_addc_u32 s9, s73, 0
	s_mov_b32 m0, s33
	v_lshl_add_u64 v[226:227], s[8:9], 0, v[162:163]
	ds_read_b128 v[180:183], v201
	ds_read_b128 v[184:187], v201 offset:1024
	ds_read_b128 v[202:205], v201 offset:2048
	ds_read_b128 v[206:209], v201 offset:3072
	ds_read_b128 v[210:213], v201 offset:4096
	ds_read_b128 v[214:217], v201 offset:5120
	ds_read_b128 v[218:221], v201 offset:6144
	ds_read_b128 v[222:225], v201 offset:7168
	global_load_lds_dwordx4 v[226:227], off
	v_lshl_add_u64 v[226:227], s[8:9], 0, v[166:167]
	s_mov_b32 m0, s93
	s_nop 0
	global_load_lds_dwordx4 v[226:227], off
	s_waitcnt vmcnt(8)
	s_waitcnt lgkmcnt(0)
	s_setprio 1
	s_barrier
	v_mfma_f32_16x16x128_f8f6f4 v[158:161], v[18:25], v[180:187], 0
	v_mfma_f32_16x16x128_f8f6f4 v[154:157], v[26:33], v[180:187], 0
	v_mfma_f32_16x16x128_f8f6f4 v[146:149], v[26:33], v[202:209], 0
	v_mfma_f32_16x16x128_f8f6f4 v[150:153], v[18:25], v[202:209], 0
	v_mfma_f32_16x16x128_f8f6f4 v[142:145], v[18:25], v[210:217], 0
	v_mfma_f32_16x16x128_f8f6f4 v[138:141], v[26:33], v[210:217], 0
	v_mfma_f32_16x16x128_f8f6f4 v[130:133], v[26:33], v[218:225], 0
	v_mfma_f32_16x16x128_f8f6f4 v[134:137], v[18:25], v[218:225], 0
	v_mfma_f32_16x16x128_f8f6f4 v[102:105], v[2:9], v[218:225], 0
	v_mfma_f32_16x16x128_f8f6f4 v[98:101], v[10:17], v[218:225], 0
	v_mfma_f32_16x16x128_f8f6f4 v[106:109], v[10:17], v[210:217], 0
	v_mfma_f32_16x16x128_f8f6f4 v[110:113], v[2:9], v[210:217], 0
	v_mfma_f32_16x16x128_f8f6f4 v[118:121], v[2:9], v[202:209], 0
	v_mfma_f32_16x16x128_f8f6f4 v[114:117], v[10:17], v[202:209], 0
	v_mfma_f32_16x16x128_f8f6f4 v[122:125], v[10:17], v[180:187], 0
	v_mfma_f32_16x16x128_f8f6f4 v[126:129], v[2:9], v[180:187], 0
	s_barrier
	s_setprio 0
	v_lshl_add_u64 v[180:181], s[54:55], 0, v[164:165]
	s_mov_b32 m0, s78
	v_lshl_add_u64 v[182:183], v[180:181], 0, s[26:27]
	ds_read_b128 v[202:205], v201 offset:16384
	ds_read_b128 v[206:209], v201 offset:17408
	ds_read_b128 v[210:213], v201 offset:18432
	ds_read_b128 v[214:217], v201 offset:19456
	ds_read_b128 v[218:221], v201 offset:20480
	ds_read_b128 v[222:225], v201 offset:21504
	ds_read_b128 v[226:229], v201 offset:22528
	ds_read_b128 v[230:233], v201 offset:23552
	global_load_lds_dwordx4 v[182:183], off
	v_lshl_add_u64 v[182:183], s[54:55], 0, v[168:169]
	s_add_u32 s8, s54, 0x80100
	v_lshl_add_u64 v[184:185], v[182:183], 0, s[26:27]
	s_mov_b32 m0, s79
	s_addc_u32 s9, s55, 0
	global_load_lds_dwordx4 v[184:185], off
	v_lshl_add_u64 v[184:185], s[8:9], 0, v[164:165]
	s_mov_b32 m0, s80
	s_nop 0
	global_load_lds_dwordx4 v[184:185], off
	v_lshl_add_u64 v[184:185], s[8:9], 0, v[168:169]
	s_mov_b32 m0, s81
	s_nop 0
	global_load_lds_dwordx4 v[184:185], off
	v_lshl_add_u64 v[184:185], s[72:73], 0, v[162:163]
	v_lshl_add_u64 v[186:187], v[184:185], 0, s[26:27]
	s_mov_b32 m0, s53
	s_nop 0
	global_load_lds_dwordx4 v[186:187], off
	v_lshl_add_u64 v[186:187], s[72:73], 0, v[166:167]
	v_lshl_add_u64 v[234:235], v[186:187], 0, s[26:27]
	s_mov_b32 m0, s82
	s_nop 0
	global_load_lds_dwordx4 v[234:235], off
	s_waitcnt vmcnt(8)
	s_waitcnt lgkmcnt(0)
	s_setprio 1
	s_barrier
	v_mfma_f32_16x16x128_f8f6f4 v[94:97], v[18:25], v[202:209], 0
	v_mfma_f32_16x16x128_f8f6f4 v[90:93], v[26:33], v[202:209], 0
	v_mfma_f32_16x16x128_f8f6f4 v[82:85], v[26:33], v[210:217], 0
	v_mfma_f32_16x16x128_f8f6f4 v[86:89], v[18:25], v[210:217], 0
	v_mfma_f32_16x16x128_f8f6f4 v[78:81], v[18:25], v[218:225], 0
	v_mfma_f32_16x16x128_f8f6f4 v[74:77], v[26:33], v[218:225], 0
	v_mfma_f32_16x16x128_f8f6f4 v[66:69], v[26:33], v[226:233], 0
	v_mfma_f32_16x16x128_f8f6f4 v[70:73], v[18:25], v[226:233], 0
	v_mfma_f32_16x16x128_f8f6f4 v[38:41], v[2:9], v[226:233], 0
	v_mfma_f32_16x16x128_f8f6f4 v[34:37], v[10:17], v[226:233], 0
	v_mfma_f32_16x16x128_f8f6f4 v[42:45], v[10:17], v[218:225], 0
	v_mfma_f32_16x16x128_f8f6f4 v[46:49], v[2:9], v[218:225], 0
	v_mfma_f32_16x16x128_f8f6f4 v[54:57], v[2:9], v[210:217], 0
	v_mfma_f32_16x16x128_f8f6f4 v[50:53], v[10:17], v[210:217], 0
	v_mfma_f32_16x16x128_f8f6f4 v[58:61], v[10:17], v[202:209], 0
	v_mfma_f32_16x16x128_f8f6f4 v[62:65], v[2:9], v[202:209], 0
	s_barrier
	s_setprio 0
	ds_read_b128 v[18:21], v200 offset:32768
	ds_read_b128 v[22:25], v200 offset:33792
	ds_read_b128 v[26:29], v200 offset:34816
	ds_read_b128 v[30:33], v200 offset:35840
	ds_read_b128 v[2:5], v200 offset:49152
	ds_read_b128 v[6:9], v200 offset:50176
	ds_read_b128 v[10:13], v200 offset:51200
	ds_read_b128 v[14:17], v200 offset:52224
	s_add_u32 s8, s72, 0x80100
	s_addc_u32 s9, s73, 0
	s_mov_b32 m0, s83
	v_lshl_add_u64 v[234:235], s[8:9], 0, v[162:163]
	ds_read_b128 v[202:205], v201 offset:32768
	ds_read_b128 v[206:209], v201 offset:33792
	ds_read_b128 v[210:213], v201 offset:34816
	ds_read_b128 v[214:217], v201 offset:35840
	ds_read_b128 v[218:221], v201 offset:36864
	ds_read_b128 v[222:225], v201 offset:37888
	ds_read_b128 v[226:229], v201 offset:38912
	ds_read_b128 v[230:233], v201 offset:39936
	global_load_lds_dwordx4 v[234:235], off
	v_lshl_add_u64 v[234:235], s[8:9], 0, v[166:167]
	s_mov_b32 m0, s84
	s_nop 0
	global_load_lds_dwordx4 v[234:235], off
	s_waitcnt vmcnt(8)
	s_waitcnt lgkmcnt(0)
	s_setprio 1
	s_barrier
	v_mfma_f32_16x16x128_f8f6f4 v[158:161], v[18:25], v[202:209], v[158:161]
	v_mfma_f32_16x16x128_f8f6f4 v[154:157], v[26:33], v[202:209], v[154:157]
	v_mfma_f32_16x16x128_f8f6f4 v[146:149], v[26:33], v[210:217], v[146:149]
	v_mfma_f32_16x16x128_f8f6f4 v[150:153], v[18:25], v[210:217], v[150:153]
	v_mfma_f32_16x16x128_f8f6f4 v[142:145], v[18:25], v[218:225], v[142:145]
	v_mfma_f32_16x16x128_f8f6f4 v[138:141], v[26:33], v[218:225], v[138:141]
	v_mfma_f32_16x16x128_f8f6f4 v[130:133], v[26:33], v[226:233], v[130:133]
	v_mfma_f32_16x16x128_f8f6f4 v[134:137], v[18:25], v[226:233], v[134:137]
	v_mfma_f32_16x16x128_f8f6f4 v[102:105], v[2:9], v[226:233], v[102:105]
	v_mfma_f32_16x16x128_f8f6f4 v[98:101], v[10:17], v[226:233], v[98:101]
	v_mfma_f32_16x16x128_f8f6f4 v[106:109], v[10:17], v[218:225], v[106:109]
	v_mfma_f32_16x16x128_f8f6f4 v[110:113], v[2:9], v[218:225], v[110:113]
	v_mfma_f32_16x16x128_f8f6f4 v[118:121], v[2:9], v[210:217], v[118:121]
	v_mfma_f32_16x16x128_f8f6f4 v[114:117], v[10:17], v[210:217], v[114:117]
	v_mfma_f32_16x16x128_f8f6f4 v[122:125], v[10:17], v[202:209], v[122:125]
	v_mfma_f32_16x16x128_f8f6f4 v[126:129], v[2:9], v[202:209], v[126:129]
	s_barrier
	s_setprio 0
	s_mov_b32 m0, s87
	v_lshl_add_u64 v[180:181], v[180:181], 0, s[36:37]
	s_add_u32 s8, s54, 0x80180
	ds_read_b128 v[202:205], v201 offset:49152
	ds_read_b128 v[206:209], v201 offset:50176
	ds_read_b128 v[210:213], v201 offset:51200
	ds_read_b128 v[214:217], v201 offset:52224
	ds_read_b128 v[218:221], v201 offset:53248
	ds_read_b128 v[222:225], v201 offset:54272
	ds_read_b128 v[226:229], v201 offset:55296
	ds_read_b128 v[230:233], v201 offset:56320
	global_load_lds_dwordx4 v[180:181], off
	v_lshl_add_u64 v[180:181], v[182:183], 0, s[36:37]
	s_mov_b32 m0, s88
	s_addc_u32 s9, s55, 0
	global_load_lds_dwordx4 v[180:181], off
	v_lshl_add_u64 v[180:181], s[8:9], 0, v[164:165]
	s_mov_b32 m0, s91
	s_nop 0
	global_load_lds_dwordx4 v[180:181], off
	v_lshl_add_u64 v[180:181], s[8:9], 0, v[168:169]
	s_mov_b32 m0, s92
	s_nop 0
	global_load_lds_dwordx4 v[180:181], off
	v_lshl_add_u64 v[180:181], v[184:185], 0, s[36:37]
	s_mov_b32 m0, s89
	s_nop 0
	global_load_lds_dwordx4 v[180:181], off
	v_lshl_add_u64 v[180:181], v[186:187], 0, s[36:37]
	s_mov_b32 m0, s90
	s_nop 0
	global_load_lds_dwordx4 v[180:181], off
	s_waitcnt vmcnt(8)
	s_waitcnt lgkmcnt(0)
	s_setprio 1
	s_barrier
	v_mfma_f32_16x16x128_f8f6f4 v[94:97], v[18:25], v[202:209], v[94:97]
	v_mfma_f32_16x16x128_f8f6f4 v[90:93], v[26:33], v[202:209], v[90:93]
	v_mfma_f32_16x16x128_f8f6f4 v[82:85], v[26:33], v[210:217], v[82:85]
	v_mfma_f32_16x16x128_f8f6f4 v[86:89], v[18:25], v[210:217], v[86:89]
	v_mfma_f32_16x16x128_f8f6f4 v[78:81], v[18:25], v[218:225], v[78:81]
	v_mfma_f32_16x16x128_f8f6f4 v[74:77], v[26:33], v[218:225], v[74:77]
	v_mfma_f32_16x16x128_f8f6f4 v[66:69], v[26:33], v[226:233], v[66:69]
	v_mfma_f32_16x16x128_f8f6f4 v[70:73], v[18:25], v[226:233], v[70:73]
	v_mfma_f32_16x16x128_f8f6f4 v[38:41], v[2:9], v[226:233], v[38:41]
	v_mfma_f32_16x16x128_f8f6f4 v[34:37], v[10:17], v[226:233], v[34:37]
	v_mfma_f32_16x16x128_f8f6f4 v[42:45], v[10:17], v[218:225], v[42:45]
	v_mfma_f32_16x16x128_f8f6f4 v[46:49], v[2:9], v[218:225], v[46:49]
	v_mfma_f32_16x16x128_f8f6f4 v[54:57], v[2:9], v[210:217], v[54:57]
	v_mfma_f32_16x16x128_f8f6f4 v[50:53], v[10:17], v[210:217], v[50:53]
	v_mfma_f32_16x16x128_f8f6f4 v[58:61], v[10:17], v[202:209], v[58:61]
	v_mfma_f32_16x16x128_f8f6f4 v[62:65], v[2:9], v[202:209], v[62:65]
	s_barrier
	s_setprio 0
	s_add_u32 s72, s72, 0x80180
	s_addc_u32 s73, s73, 0
	s_add_u32 s8, s54, 0x200
	s_addc_u32 s9, s55, 0
	s_mov_b32 s62, 0
.LBB0_438:
	ds_read_b128 v[2:5], v200
	ds_read_b128 v[6:9], v200 offset:1024
	ds_read_b128 v[18:21], v200 offset:2048
	ds_read_b128 v[22:25], v200 offset:3072
	ds_read_b128 v[26:29], v200 offset:16384
	ds_read_b128 v[30:33], v200 offset:17408
	ds_read_b128 v[180:183], v200 offset:18432
	ds_read_b128 v[184:187], v200 offset:19456
	s_add_u32 s54, s72, 0xfff80080
	s_addc_u32 s55, s73, -1
	s_cmp_eq_u32 s62, 28
	s_cselect_b32 s75, s47, s55
	s_cselect_b32 s74, s71, s54
	s_cselect_b32 s55, s45, s9
	s_cselect_b32 s54, s94, s8
	s_mov_b32 m0, s33
	v_lshl_add_u64 v[226:227], s[72:73], 0, v[170:171]
	ds_read_b128 v[10:13], v201
	ds_read_b128 v[14:17], v201 offset:1024
	ds_read_b128 v[202:205], v201 offset:2048
	ds_read_b128 v[206:209], v201 offset:3072
	ds_read_b128 v[210:213], v201 offset:4096
	ds_read_b128 v[214:217], v201 offset:5120
	ds_read_b128 v[218:221], v201 offset:6144
	ds_read_b128 v[222:225], v201 offset:7168
	global_load_lds_dwordx4 v[226:227], off
	v_lshl_add_u64 v[226:227], s[72:73], 0, v[172:173]
	s_mov_b32 m0, s93
	s_nop 0
	global_load_lds_dwordx4 v[226:227], off
	s_waitcnt vmcnt(8)
	s_waitcnt lgkmcnt(0)
	s_setprio 1
	s_barrier
	v_mfma_f32_16x16x128_f8f6f4 v[158:161], v[2:9], v[10:17], v[158:161]
	v_mfma_f32_16x16x128_f8f6f4 v[154:157], v[18:25], v[10:17], v[154:157]
	v_mfma_f32_16x16x128_f8f6f4 v[146:149], v[18:25], v[202:209], v[146:149]
	v_mfma_f32_16x16x128_f8f6f4 v[150:153], v[2:9], v[202:209], v[150:153]
	v_mfma_f32_16x16x128_f8f6f4 v[142:145], v[2:9], v[210:217], v[142:145]
	v_mfma_f32_16x16x128_f8f6f4 v[138:141], v[18:25], v[210:217], v[138:141]
	v_mfma_f32_16x16x128_f8f6f4 v[130:133], v[18:25], v[218:225], v[130:133]
	v_mfma_f32_16x16x128_f8f6f4 v[134:137], v[2:9], v[218:225], v[134:137]
	v_mfma_f32_16x16x128_f8f6f4 v[102:105], v[26:33], v[218:225], v[102:105]
	v_mfma_f32_16x16x128_f8f6f4 v[98:101], v[180:187], v[218:225], v[98:101]
	v_mfma_f32_16x16x128_f8f6f4 v[106:109], v[180:187], v[210:217], v[106:109]
	v_mfma_f32_16x16x128_f8f6f4 v[110:113], v[26:33], v[210:217], v[110:113]
	v_mfma_f32_16x16x128_f8f6f4 v[118:121], v[26:33], v[202:209], v[118:121]
	v_mfma_f32_16x16x128_f8f6f4 v[114:117], v[180:187], v[202:209], v[114:117]
	v_mfma_f32_16x16x128_f8f6f4 v[122:125], v[180:187], v[10:17], v[122:125]
	v_mfma_f32_16x16x128_f8f6f4 v[126:129], v[26:33], v[10:17], v[126:129]
	s_barrier
	s_setprio 0
	s_mov_b32 m0, s78
	v_lshl_add_u64 v[10:11], s[54:55], 0, v[164:165]
	s_add_u32 s96, s54, 0x80000
	ds_read_b128 v[202:205], v201 offset:16384
	ds_read_b128 v[206:209], v201 offset:17408
	ds_read_b128 v[210:213], v201 offset:18432
	ds_read_b128 v[214:217], v201 offset:19456
	ds_read_b128 v[218:221], v201 offset:20480
	ds_read_b128 v[222:225], v201 offset:21504
	ds_read_b128 v[226:229], v201 offset:22528
	ds_read_b128 v[230:233], v201 offset:23552
	global_load_lds_dwordx4 v[10:11], off
	v_lshl_add_u64 v[12:13], s[54:55], 0, v[168:169]
	s_mov_b32 m0, s79
	s_addc_u32 s97, s55, 0
	global_load_lds_dwordx4 v[12:13], off
	v_lshl_add_u64 v[14:15], s[96:97], 0, v[164:165]
	s_mov_b32 m0, s80
	v_lshl_add_u64 v[16:17], s[74:75], 0, v[166:167]
	global_load_lds_dwordx4 v[14:15], off
	v_lshl_add_u64 v[14:15], s[96:97], 0, v[168:169]
	s_mov_b32 m0, s81
	s_nop 0
	global_load_lds_dwordx4 v[14:15], off
	v_lshl_add_u64 v[14:15], s[74:75], 0, v[162:163]
	s_mov_b32 m0, s53
	s_nop 0
	global_load_lds_dwordx4 v[14:15], off
	s_mov_b32 m0, s82
	s_nop 0
	global_load_lds_dwordx4 v[16:17], off
	s_waitcnt vmcnt(8)
	s_waitcnt lgkmcnt(0)
	s_setprio 1
	s_barrier
	v_mfma_f32_16x16x128_f8f6f4 v[94:97], v[2:9], v[202:209], v[94:97]
	v_mfma_f32_16x16x128_f8f6f4 v[90:93], v[18:25], v[202:209], v[90:93]
	v_mfma_f32_16x16x128_f8f6f4 v[82:85], v[18:25], v[210:217], v[82:85]
	v_mfma_f32_16x16x128_f8f6f4 v[86:89], v[2:9], v[210:217], v[86:89]
	v_mfma_f32_16x16x128_f8f6f4 v[78:81], v[2:9], v[218:225], v[78:81]
	v_mfma_f32_16x16x128_f8f6f4 v[74:77], v[18:25], v[218:225], v[74:77]
	v_mfma_f32_16x16x128_f8f6f4 v[66:69], v[18:25], v[226:233], v[66:69]
	v_mfma_f32_16x16x128_f8f6f4 v[70:73], v[2:9], v[226:233], v[70:73]
	v_mfma_f32_16x16x128_f8f6f4 v[38:41], v[26:33], v[226:233], v[38:41]
	v_mfma_f32_16x16x128_f8f6f4 v[34:37], v[180:187], v[226:233], v[34:37]
	v_mfma_f32_16x16x128_f8f6f4 v[42:45], v[180:187], v[218:225], v[42:45]
	v_mfma_f32_16x16x128_f8f6f4 v[46:49], v[26:33], v[218:225], v[46:49]
	v_mfma_f32_16x16x128_f8f6f4 v[54:57], v[26:33], v[210:217], v[54:57]
	v_mfma_f32_16x16x128_f8f6f4 v[50:53], v[180:187], v[210:217], v[50:53]
	v_mfma_f32_16x16x128_f8f6f4 v[58:61], v[180:187], v[202:209], v[58:61]
	v_mfma_f32_16x16x128_f8f6f4 v[62:65], v[26:33], v[202:209], v[62:65]
	s_barrier
	s_setprio 0
	ds_read_b128 v[18:21], v200 offset:32768
	ds_read_b128 v[22:25], v200 offset:33792
	ds_read_b128 v[26:29], v200 offset:34816
	ds_read_b128 v[30:33], v200 offset:35840
	ds_read_b128 v[2:5], v200 offset:49152
	ds_read_b128 v[6:9], v200 offset:50176
	ds_read_b128 v[180:183], v200 offset:51200
	ds_read_b128 v[184:187], v200 offset:52224
	s_add_u32 s74, s74, 0x80000
	s_addc_u32 s75, s75, 0
	s_mov_b32 m0, s83
	v_lshl_add_u64 v[234:235], s[74:75], 0, v[162:163]
	ds_read_b128 v[202:205], v201 offset:32768
	ds_read_b128 v[206:209], v201 offset:33792
	ds_read_b128 v[210:213], v201 offset:34816
	ds_read_b128 v[214:217], v201 offset:35840
	ds_read_b128 v[218:221], v201 offset:36864
	ds_read_b128 v[222:225], v201 offset:37888
	ds_read_b128 v[226:229], v201 offset:38912
	ds_read_b128 v[230:233], v201 offset:39936
	global_load_lds_dwordx4 v[234:235], off
	v_lshl_add_u64 v[234:235], s[74:75], 0, v[166:167]
	s_mov_b32 m0, s84
	s_nop 0
	global_load_lds_dwordx4 v[234:235], off
	s_waitcnt vmcnt(8)
	s_waitcnt lgkmcnt(0)
	s_setprio 1
	s_barrier
	v_mfma_f32_16x16x128_f8f6f4 v[158:161], v[18:25], v[202:209], v[158:161]
	v_mfma_f32_16x16x128_f8f6f4 v[154:157], v[26:33], v[202:209], v[154:157]
	v_mfma_f32_16x16x128_f8f6f4 v[146:149], v[26:33], v[210:217], v[146:149]
	v_mfma_f32_16x16x128_f8f6f4 v[150:153], v[18:25], v[210:217], v[150:153]
	v_mfma_f32_16x16x128_f8f6f4 v[142:145], v[18:25], v[218:225], v[142:145]
	v_mfma_f32_16x16x128_f8f6f4 v[138:141], v[26:33], v[218:225], v[138:141]
	v_mfma_f32_16x16x128_f8f6f4 v[130:133], v[26:33], v[226:233], v[130:133]
	v_mfma_f32_16x16x128_f8f6f4 v[134:137], v[18:25], v[226:233], v[134:137]
	v_mfma_f32_16x16x128_f8f6f4 v[102:105], v[2:9], v[226:233], v[102:105]
	v_mfma_f32_16x16x128_f8f6f4 v[98:101], v[180:187], v[226:233], v[98:101]
	v_mfma_f32_16x16x128_f8f6f4 v[106:109], v[180:187], v[218:225], v[106:109]
	v_mfma_f32_16x16x128_f8f6f4 v[110:113], v[2:9], v[218:225], v[110:113]
	v_mfma_f32_16x16x128_f8f6f4 v[118:121], v[2:9], v[210:217], v[118:121]
	v_mfma_f32_16x16x128_f8f6f4 v[114:117], v[180:187], v[210:217], v[114:117]
	v_mfma_f32_16x16x128_f8f6f4 v[122:125], v[180:187], v[202:209], v[122:125]
	v_mfma_f32_16x16x128_f8f6f4 v[126:129], v[2:9], v[202:209], v[126:129]
	s_barrier
	s_setprio 0
	s_mov_b32 m0, s87
	v_lshl_add_u64 v[10:11], v[10:11], 0, s[4:5]
	s_add_u32 s54, s54, 0x80080
	ds_read_b128 v[202:205], v201 offset:49152
	ds_read_b128 v[206:209], v201 offset:50176
	ds_read_b128 v[210:213], v201 offset:51200
	ds_read_b128 v[214:217], v201 offset:52224
	ds_read_b128 v[218:221], v201 offset:53248
	ds_read_b128 v[222:225], v201 offset:54272
	ds_read_b128 v[226:229], v201 offset:55296
	ds_read_b128 v[230:233], v201 offset:56320
	global_load_lds_dwordx4 v[10:11], off
	v_lshl_add_u64 v[10:11], v[12:13], 0, s[4:5]
	s_mov_b32 m0, s88
	s_addc_u32 s55, s55, 0
	global_load_lds_dwordx4 v[10:11], off
	v_lshl_add_u64 v[10:11], s[54:55], 0, v[164:165]
	s_mov_b32 m0, s91
	s_nop 0
	global_load_lds_dwordx4 v[10:11], off
	v_lshl_add_u64 v[10:11], s[54:55], 0, v[168:169]
	s_mov_b32 m0, s92
	s_nop 0
	global_load_lds_dwordx4 v[10:11], off
	v_lshl_add_u64 v[10:11], v[14:15], 0, s[4:5]
	s_mov_b32 m0, s89
	s_nop 0
	global_load_lds_dwordx4 v[10:11], off
	v_lshl_add_u64 v[10:11], v[16:17], 0, s[4:5]
	s_mov_b32 m0, s90
	s_nop 0
	global_load_lds_dwordx4 v[10:11], off
	s_waitcnt vmcnt(8)
	s_waitcnt lgkmcnt(0)
	s_setprio 1
	s_barrier
	v_mfma_f32_16x16x128_f8f6f4 v[94:97], v[18:25], v[202:209], v[94:97]
	v_mfma_f32_16x16x128_f8f6f4 v[90:93], v[26:33], v[202:209], v[90:93]
	v_mfma_f32_16x16x128_f8f6f4 v[82:85], v[26:33], v[210:217], v[82:85]
	v_mfma_f32_16x16x128_f8f6f4 v[86:89], v[18:25], v[210:217], v[86:89]
	v_mfma_f32_16x16x128_f8f6f4 v[78:81], v[18:25], v[218:225], v[78:81]
	v_mfma_f32_16x16x128_f8f6f4 v[74:77], v[26:33], v[218:225], v[74:77]
	v_mfma_f32_16x16x128_f8f6f4 v[66:69], v[26:33], v[226:233], v[66:69]
	v_mfma_f32_16x16x128_f8f6f4 v[70:73], v[18:25], v[226:233], v[70:73]
	v_mfma_f32_16x16x128_f8f6f4 v[38:41], v[2:9], v[226:233], v[38:41]
	v_mfma_f32_16x16x128_f8f6f4 v[34:37], v[180:187], v[226:233], v[34:37]
	v_mfma_f32_16x16x128_f8f6f4 v[42:45], v[180:187], v[218:225], v[42:45]
	v_mfma_f32_16x16x128_f8f6f4 v[46:49], v[2:9], v[218:225], v[46:49]
	v_mfma_f32_16x16x128_f8f6f4 v[54:57], v[2:9], v[210:217], v[54:57]
	v_mfma_f32_16x16x128_f8f6f4 v[50:53], v[180:187], v[210:217], v[50:53]
	v_mfma_f32_16x16x128_f8f6f4 v[58:61], v[180:187], v[202:209], v[58:61]
	v_mfma_f32_16x16x128_f8f6f4 v[62:65], v[2:9], v[202:209], v[62:65]
	s_barrier
	s_setprio 0
	s_add_i32 s62, s62, 2
	s_add_u32 s72, s72, 0x100
	s_addc_u32 s73, s73, 0
	s_add_u32 s8, s8, 0x100
	s_addc_u32 s9, s9, 0
	s_cmp_gt_u32 s62, 29
	s_cbranch_scc0 .LBB0_438
	s_and_b64 vcc, exec, s[6:7]
	s_cbranch_vccz .LBB0_441
	s_barrier

.LBB0_452:
	ds_read_b128 v[146:149], v143
	ds_read_b128 v[150:153], v143 offset:1024
	ds_read_b128 v[154:157], v143 offset:2048
	ds_read_b128 v[158:161], v143 offset:3072
	ds_read_b128 v[162:165], v143 offset:16384
	ds_read_b128 v[166:169], v143 offset:17408
	ds_read_b128 v[170:173], v143 offset:18432
	ds_read_b128 v[174:177], v143 offset:19456
	s_add_u32 s8, s52, 0xfff00080
	s_addc_u32 s9, s53, -1
	s_cmp_eq_u32 s91, 28
	s_cselect_b32 s73, s27, s9
	s_cselect_b32 s72, s37, s8
	s_cselect_b32 s55, s39, s90
	s_cselect_b32 s54, s45, s89
	v_lshl_add_u64 v[140:141], s[52:53], 0, v[136:137]
	s_add_i32 m0, s47, 0xc000
	ds_read_b128 v[180:183], v144
	ds_read_b128 v[184:187], v144 offset:1024
	ds_read_b128 v[188:191], v144 offset:2048
	ds_read_b128 v[192:195], v144 offset:3072
	ds_read_b128 v[196:199], v144 offset:4096
	ds_read_b128 v[200:203], v144 offset:5120
	ds_read_b128 v[204:207], v144 offset:6144
	ds_read_b128 v[208:211], v144 offset:7168
	global_load_lds_dwordx4 v[140:141], off
	v_lshl_add_u64 v[140:141], s[52:53], 0, v[138:139]
	s_add_i32 m0, s47, 0xe000
	s_nop 0
	global_load_lds_dwordx4 v[140:141], off
	s_waitcnt vmcnt(8)
	s_waitcnt lgkmcnt(0)
	s_setprio 1
	s_barrier
	v_mfma_f32_16x16x32_bf16 v[126:129], v[146:149], v[180:183], v[126:129]
	v_mfma_f32_16x16x32_bf16 v[122:125], v[154:157], v[180:183], v[122:125]
	v_mfma_f32_16x16x32_bf16 v[118:121], v[146:149], v[188:191], v[118:121]
	v_mfma_f32_16x16x32_bf16 v[114:117], v[154:157], v[188:191], v[114:117]
	v_mfma_f32_16x16x32_bf16 v[110:113], v[146:149], v[196:199], v[110:113]
	v_mfma_f32_16x16x32_bf16 v[106:109], v[154:157], v[196:199], v[106:109]
	v_mfma_f32_16x16x32_bf16 v[102:105], v[146:149], v[204:207], v[102:105]
	v_mfma_f32_16x16x32_bf16 v[98:101], v[154:157], v[204:207], v[98:101]
	v_mfma_f32_16x16x32_bf16 v[126:129], v[150:153], v[184:187], v[126:129]
	v_mfma_f32_16x16x32_bf16 v[122:125], v[158:161], v[184:187], v[122:125]
	v_mfma_f32_16x16x32_bf16 v[118:121], v[150:153], v[192:195], v[118:121]
	v_mfma_f32_16x16x32_bf16 v[114:117], v[158:161], v[192:195], v[114:117]
	v_mfma_f32_16x16x32_bf16 v[110:113], v[150:153], v[200:203], v[110:113]
	v_mfma_f32_16x16x32_bf16 v[106:109], v[158:161], v[200:203], v[106:109]
	v_mfma_f32_16x16x32_bf16 v[102:105], v[150:153], v[208:211], v[102:105]
	v_mfma_f32_16x16x32_bf16 v[98:101], v[158:161], v[208:211], v[98:101]
	v_mfma_f32_16x16x32_bf16 v[90:93], v[162:165], v[180:183], v[90:93]
	v_mfma_f32_16x16x32_bf16 v[82:85], v[170:173], v[180:183], v[82:85]
	v_mfma_f32_16x16x32_bf16 v[74:77], v[162:165], v[188:191], v[74:77]
	v_mfma_f32_16x16x32_bf16 v[66:69], v[170:173], v[188:191], v[66:69]
	v_mfma_f32_16x16x32_bf16 v[58:61], v[162:165], v[196:199], v[58:61]
	v_mfma_f32_16x16x32_bf16 v[50:53], v[170:173], v[196:199], v[50:53]
	v_mfma_f32_16x16x32_bf16 v[42:45], v[162:165], v[204:207], v[42:45]
	v_mfma_f32_16x16x32_bf16 v[34:37], v[170:173], v[204:207], v[34:37]
	v_mfma_f32_16x16x32_bf16 v[90:93], v[166:169], v[184:187], v[90:93]
	v_mfma_f32_16x16x32_bf16 v[82:85], v[174:177], v[184:187], v[82:85]
	v_mfma_f32_16x16x32_bf16 v[74:77], v[166:169], v[192:195], v[74:77]
	v_mfma_f32_16x16x32_bf16 v[66:69], v[174:177], v[192:195], v[66:69]
	v_mfma_f32_16x16x32_bf16 v[58:61], v[166:169], v[200:203], v[58:61]
	v_mfma_f32_16x16x32_bf16 v[50:53], v[174:177], v[200:203], v[50:53]
	v_mfma_f32_16x16x32_bf16 v[42:45], v[166:169], v[208:211], v[42:45]
	v_mfma_f32_16x16x32_bf16 v[34:37], v[174:177], v[208:211], v[34:37]
	s_barrier
	s_setprio 0
	s_mov_b32 m0, s74
	v_lshl_add_u64 v[140:141], s[54:55], 0, v[132:133]
	s_add_u32 s8, s54, 0x100000
	ds_read_b128 v[180:183], v144 offset:16384
	ds_read_b128 v[184:187], v144 offset:17408
	ds_read_b128 v[188:191], v144 offset:18432
	ds_read_b128 v[192:195], v144 offset:19456
	ds_read_b128 v[196:199], v144 offset:20480
	ds_read_b128 v[200:203], v144 offset:21504
	ds_read_b128 v[204:207], v144 offset:22528
	ds_read_b128 v[208:211], v144 offset:23552
	global_load_lds_dwordx4 v[140:141], off
	v_lshl_add_u64 v[212:213], s[54:55], 0, v[130:131]
	s_mov_b32 m0, s75
	s_addc_u32 s9, s55, 0
	global_load_lds_dwordx4 v[212:213], off
	v_lshl_add_u64 v[214:215], s[8:9], 0, v[132:133]
	s_mov_b32 m0, s76
	v_lshl_add_u64 v[216:217], s[72:73], 0, v[130:131]
	global_load_lds_dwordx4 v[214:215], off
	v_lshl_add_u64 v[214:215], s[8:9], 0, v[130:131]
	s_mov_b32 m0, s77
	s_nop 0
	global_load_lds_dwordx4 v[214:215], off
	v_lshl_add_u64 v[214:215], s[72:73], 0, v[132:133]
	s_mov_b32 m0, s47
	s_nop 0
	global_load_lds_dwordx4 v[214:215], off
	s_mov_b32 m0, s78
	s_nop 0
	global_load_lds_dwordx4 v[216:217], off
	s_waitcnt vmcnt(8)
	s_waitcnt lgkmcnt(0)
	s_setprio 1
	s_barrier
	v_mfma_f32_16x16x32_bf16 v[94:97], v[146:149], v[180:183], v[94:97]
	v_mfma_f32_16x16x32_bf16 v[86:89], v[154:157], v[180:183], v[86:89]
	v_mfma_f32_16x16x32_bf16 v[78:81], v[146:149], v[188:191], v[78:81]
	v_mfma_f32_16x16x32_bf16 v[70:73], v[154:157], v[188:191], v[70:73]
	v_mfma_f32_16x16x32_bf16 v[62:65], v[146:149], v[196:199], v[62:65]
	v_mfma_f32_16x16x32_bf16 v[54:57], v[154:157], v[196:199], v[54:57]
	v_mfma_f32_16x16x32_bf16 v[46:49], v[146:149], v[204:207], v[46:49]
	v_mfma_f32_16x16x32_bf16 v[38:41], v[154:157], v[204:207], v[38:41]
	v_mfma_f32_16x16x32_bf16 v[94:97], v[150:153], v[184:187], v[94:97]
	v_mfma_f32_16x16x32_bf16 v[86:89], v[158:161], v[184:187], v[86:89]
	v_mfma_f32_16x16x32_bf16 v[78:81], v[150:153], v[192:195], v[78:81]
	v_mfma_f32_16x16x32_bf16 v[70:73], v[158:161], v[192:195], v[70:73]
	v_mfma_f32_16x16x32_bf16 v[62:65], v[150:153], v[200:203], v[62:65]
	v_mfma_f32_16x16x32_bf16 v[54:57], v[158:161], v[200:203], v[54:57]
	v_mfma_f32_16x16x32_bf16 v[46:49], v[150:153], v[208:211], v[46:49]
	v_mfma_f32_16x16x32_bf16 v[38:41], v[158:161], v[208:211], v[38:41]
	v_mfma_f32_16x16x32_bf16 v[30:33], v[162:165], v[180:183], v[30:33]
	v_mfma_f32_16x16x32_bf16 v[26:29], v[170:173], v[180:183], v[26:29]
	v_mfma_f32_16x16x32_bf16 v[22:25], v[162:165], v[188:191], v[22:25]
	v_mfma_f32_16x16x32_bf16 v[18:21], v[170:173], v[188:191], v[18:21]
	v_mfma_f32_16x16x32_bf16 v[14:17], v[162:165], v[196:199], v[14:17]
	v_mfma_f32_16x16x32_bf16 v[10:13], v[170:173], v[196:199], v[10:13]
	v_mfma_f32_16x16x32_bf16 v[6:9], v[162:165], v[204:207], v[6:9]
	v_mfma_f32_16x16x32_bf16 v[2:5], v[170:173], v[204:207], v[2:5]
	v_mfma_f32_16x16x32_bf16 v[30:33], v[166:169], v[184:187], v[30:33]
	v_mfma_f32_16x16x32_bf16 v[26:29], v[174:177], v[184:187], v[26:29]
	v_mfma_f32_16x16x32_bf16 v[22:25], v[166:169], v[192:195], v[22:25]
	v_mfma_f32_16x16x32_bf16 v[18:21], v[174:177], v[192:195], v[18:21]
	v_mfma_f32_16x16x32_bf16 v[14:17], v[166:169], v[200:203], v[14:17]
	v_mfma_f32_16x16x32_bf16 v[10:13], v[174:177], v[200:203], v[10:13]
	v_mfma_f32_16x16x32_bf16 v[6:9], v[166:169], v[208:211], v[6:9]
	v_mfma_f32_16x16x32_bf16 v[2:5], v[174:177], v[208:211], v[2:5]
	s_barrier
	s_setprio 0
	ds_read_b128 v[146:149], v143 offset:32768
	ds_read_b128 v[150:153], v143 offset:33792
	ds_read_b128 v[154:157], v143 offset:34816
	ds_read_b128 v[158:161], v143 offset:35840
	ds_read_b128 v[162:165], v143 offset:49152
	ds_read_b128 v[166:169], v143 offset:50176
	ds_read_b128 v[170:173], v143 offset:51200
	ds_read_b128 v[174:177], v143 offset:52224
	s_add_u32 s8, s72, 0x100000
	s_addc_u32 s9, s73, 0
	s_mov_b32 m0, s79
	v_lshl_add_u64 v[218:219], s[8:9], 0, v[132:133]
	ds_read_b128 v[180:183], v144 offset:32768
	ds_read_b128 v[184:187], v144 offset:33792
	ds_read_b128 v[188:191], v144 offset:34816
	ds_read_b128 v[192:195], v144 offset:35840
	ds_read_b128 v[196:199], v144 offset:36864
	ds_read_b128 v[200:203], v144 offset:37888
	ds_read_b128 v[204:207], v144 offset:38912
	ds_read_b128 v[208:211], v144 offset:39936
	global_load_lds_dwordx4 v[218:219], off
	v_lshl_add_u64 v[218:219], s[8:9], 0, v[130:131]
	s_mov_b32 m0, s80
	s_nop 0
	global_load_lds_dwordx4 v[218:219], off
	s_waitcnt vmcnt(8)
	s_waitcnt lgkmcnt(0)
	s_setprio 1
	s_barrier
	v_mfma_f32_16x16x32_bf16 v[126:129], v[146:149], v[180:183], v[126:129]
	v_mfma_f32_16x16x32_bf16 v[122:125], v[154:157], v[180:183], v[122:125]
	v_mfma_f32_16x16x32_bf16 v[118:121], v[146:149], v[188:191], v[118:121]
	v_mfma_f32_16x16x32_bf16 v[114:117], v[154:157], v[188:191], v[114:117]
	v_mfma_f32_16x16x32_bf16 v[110:113], v[146:149], v[196:199], v[110:113]
	v_mfma_f32_16x16x32_bf16 v[106:109], v[154:157], v[196:199], v[106:109]
	v_mfma_f32_16x16x32_bf16 v[102:105], v[146:149], v[204:207], v[102:105]
	v_mfma_f32_16x16x32_bf16 v[98:101], v[154:157], v[204:207], v[98:101]
	v_mfma_f32_16x16x32_bf16 v[126:129], v[150:153], v[184:187], v[126:129]
	v_mfma_f32_16x16x32_bf16 v[122:125], v[158:161], v[184:187], v[122:125]
	v_mfma_f32_16x16x32_bf16 v[118:121], v[150:153], v[192:195], v[118:121]
	v_mfma_f32_16x16x32_bf16 v[114:117], v[158:161], v[192:195], v[114:117]
	v_mfma_f32_16x16x32_bf16 v[110:113], v[150:153], v[200:203], v[110:113]
	v_mfma_f32_16x16x32_bf16 v[106:109], v[158:161], v[200:203], v[106:109]
	v_mfma_f32_16x16x32_bf16 v[102:105], v[150:153], v[208:211], v[102:105]
	v_mfma_f32_16x16x32_bf16 v[98:101], v[158:161], v[208:211], v[98:101]
	v_mfma_f32_16x16x32_bf16 v[90:93], v[162:165], v[180:183], v[90:93]
	v_mfma_f32_16x16x32_bf16 v[82:85], v[170:173], v[180:183], v[82:85]
	v_mfma_f32_16x16x32_bf16 v[74:77], v[162:165], v[188:191], v[74:77]
	v_mfma_f32_16x16x32_bf16 v[66:69], v[170:173], v[188:191], v[66:69]
	v_mfma_f32_16x16x32_bf16 v[58:61], v[162:165], v[196:199], v[58:61]
	v_mfma_f32_16x16x32_bf16 v[50:53], v[170:173], v[196:199], v[50:53]
	v_mfma_f32_16x16x32_bf16 v[42:45], v[162:165], v[204:207], v[42:45]
	v_mfma_f32_16x16x32_bf16 v[34:37], v[170:173], v[204:207], v[34:37]
	v_mfma_f32_16x16x32_bf16 v[90:93], v[166:169], v[184:187], v[90:93]
	v_mfma_f32_16x16x32_bf16 v[82:85], v[174:177], v[184:187], v[82:85]
	v_mfma_f32_16x16x32_bf16 v[74:77], v[166:169], v[192:195], v[74:77]
	v_mfma_f32_16x16x32_bf16 v[66:69], v[174:177], v[192:195], v[66:69]
	v_mfma_f32_16x16x32_bf16 v[58:61], v[166:169], v[200:203], v[58:61]
	v_mfma_f32_16x16x32_bf16 v[50:53], v[174:177], v[200:203], v[50:53]
	v_mfma_f32_16x16x32_bf16 v[42:45], v[166:169], v[208:211], v[42:45]
	v_mfma_f32_16x16x32_bf16 v[34:37], v[174:177], v[208:211], v[34:37]
	s_barrier
	s_setprio 0
	s_mov_b32 m0, s81
	v_lshl_add_u64 v[140:141], v[140:141], 0, s[4:5]
	s_add_u32 s8, s54, 0x100080
	ds_read_b128 v[180:183], v144 offset:49152
	ds_read_b128 v[184:187], v144 offset:50176
	ds_read_b128 v[188:191], v144 offset:51200
	ds_read_b128 v[192:195], v144 offset:52224
	ds_read_b128 v[196:199], v144 offset:53248
	ds_read_b128 v[200:203], v144 offset:54272
	ds_read_b128 v[204:207], v144 offset:55296
	ds_read_b128 v[208:211], v144 offset:56320
	global_load_lds_dwordx4 v[140:141], off
	v_lshl_add_u64 v[140:141], v[212:213], 0, s[4:5]
	s_mov_b32 m0, s82
	s_addc_u32 s9, s55, 0
	global_load_lds_dwordx4 v[140:141], off
	v_lshl_add_u64 v[140:141], s[8:9], 0, v[132:133]
	s_mov_b32 m0, s85
	s_nop 0
	global_load_lds_dwordx4 v[140:141], off
	v_lshl_add_u64 v[140:141], s[8:9], 0, v[130:131]
	s_mov_b32 m0, s86
	s_nop 0
	global_load_lds_dwordx4 v[140:141], off
	v_lshl_add_u64 v[140:141], v[214:215], 0, s[4:5]
	s_mov_b32 m0, s83
	s_nop 0
	global_load_lds_dwordx4 v[140:141], off
	v_lshl_add_u64 v[140:141], v[216:217], 0, s[4:5]
	s_mov_b32 m0, s84
	s_nop 0
	global_load_lds_dwordx4 v[140:141], off
	s_waitcnt vmcnt(8)
	s_waitcnt lgkmcnt(0)
	s_setprio 1
	s_barrier
	v_mfma_f32_16x16x32_bf16 v[94:97], v[146:149], v[180:183], v[94:97]
	v_mfma_f32_16x16x32_bf16 v[86:89], v[154:157], v[180:183], v[86:89]
	v_mfma_f32_16x16x32_bf16 v[78:81], v[146:149], v[188:191], v[78:81]
	v_mfma_f32_16x16x32_bf16 v[70:73], v[154:157], v[188:191], v[70:73]
	v_mfma_f32_16x16x32_bf16 v[62:65], v[146:149], v[196:199], v[62:65]
	v_mfma_f32_16x16x32_bf16 v[54:57], v[154:157], v[196:199], v[54:57]
	v_mfma_f32_16x16x32_bf16 v[46:49], v[146:149], v[204:207], v[46:49]
	v_mfma_f32_16x16x32_bf16 v[38:41], v[154:157], v[204:207], v[38:41]
	v_mfma_f32_16x16x32_bf16 v[94:97], v[150:153], v[184:187], v[94:97]
	v_mfma_f32_16x16x32_bf16 v[86:89], v[158:161], v[184:187], v[86:89]
	v_mfma_f32_16x16x32_bf16 v[78:81], v[150:153], v[192:195], v[78:81]
	v_mfma_f32_16x16x32_bf16 v[70:73], v[158:161], v[192:195], v[70:73]
	v_mfma_f32_16x16x32_bf16 v[62:65], v[150:153], v[200:203], v[62:65]
	v_mfma_f32_16x16x32_bf16 v[54:57], v[158:161], v[200:203], v[54:57]
	v_mfma_f32_16x16x32_bf16 v[46:49], v[150:153], v[208:211], v[46:49]
	v_mfma_f32_16x16x32_bf16 v[38:41], v[158:161], v[208:211], v[38:41]
	v_mfma_f32_16x16x32_bf16 v[30:33], v[162:165], v[180:183], v[30:33]
	v_mfma_f32_16x16x32_bf16 v[26:29], v[170:173], v[180:183], v[26:29]
	v_mfma_f32_16x16x32_bf16 v[22:25], v[162:165], v[188:191], v[22:25]
	v_mfma_f32_16x16x32_bf16 v[18:21], v[170:173], v[188:191], v[18:21]
	v_mfma_f32_16x16x32_bf16 v[14:17], v[162:165], v[196:199], v[14:17]
	v_mfma_f32_16x16x32_bf16 v[10:13], v[170:173], v[196:199], v[10:13]
	v_mfma_f32_16x16x32_bf16 v[6:9], v[162:165], v[204:207], v[6:9]
	v_mfma_f32_16x16x32_bf16 v[2:5], v[170:173], v[204:207], v[2:5]
	v_mfma_f32_16x16x32_bf16 v[30:33], v[166:169], v[184:187], v[30:33]
	v_mfma_f32_16x16x32_bf16 v[26:29], v[174:177], v[184:187], v[26:29]
	v_mfma_f32_16x16x32_bf16 v[22:25], v[166:169], v[192:195], v[22:25]
	v_mfma_f32_16x16x32_bf16 v[18:21], v[174:177], v[192:195], v[18:21]
	v_mfma_f32_16x16x32_bf16 v[14:17], v[166:169], v[200:203], v[14:17]
	v_mfma_f32_16x16x32_bf16 v[10:13], v[174:177], v[200:203], v[10:13]
	v_mfma_f32_16x16x32_bf16 v[6:9], v[166:169], v[208:211], v[6:9]
	v_mfma_f32_16x16x32_bf16 v[2:5], v[174:177], v[208:211], v[2:5]
	s_barrier
	s_setprio 0
	s_add_i32 s91, s91, 2
	s_add_u32 s52, s52, 0x100
	s_addc_u32 s53, s53, 0
	s_add_u32 s89, s89, 0x100
	s_addc_u32 s90, s90, 0
	s_cmp_gt_u32 s91, 29
	s_cbranch_scc0 .LBB0_452
	s_and_b64 vcc, exec, s[6:7]
	s_cbranch_vccz .LBB0_455
	s_barrier

.LBB0_600:
	s_ashr_i32 s55, s54, 31
	ds_read_b128 v[18:21], v200
	ds_read_b128 v[22:25], v200 offset:1024
	ds_read_b128 v[26:29], v200 offset:2048
	ds_read_b128 v[30:33], v200 offset:3072
	ds_read_b128 v[2:5], v200 offset:16384
	ds_read_b128 v[6:9], v200 offset:17408
	ds_read_b128 v[10:13], v200 offset:18432
	ds_read_b128 v[14:17], v200 offset:19456
	s_lshl_b64 s[4:5], s[54:55], 18
	s_add_u32 s72, s38, s4
	s_addc_u32 s73, s39, s5
	s_and_b64 s[4:5], s[2:3], exec
	s_cselect_b32 s4, s73, s81
	s_cselect_b32 s5, s72, s80
	s_ashr_i32 s53, s52, 31
	s_lshl_b64 s[8:9], s[52:53], 18
	s_add_u32 s74, s94, s8
	v_readlane_b32 s8, v254, 6
	s_addc_u32 s75, s8, s9
	s_and_b64 s[8:9], s[2:3], exec
	s_cselect_b32 s53, s75, s79
	s_cselect_b32 s55, s74, s78
	s_add_u32 s8, s80, 0x20080
	s_addc_u32 s9, s81, 0
	s_mov_b32 m0, s96
	v_lshl_add_u64 v[226:227], s[8:9], 0, v[162:163]
	ds_read_b128 v[182:185], v201
	ds_read_b128 v[186:189], v201 offset:1024
	ds_read_b128 v[202:205], v201 offset:2048
	ds_read_b128 v[206:209], v201 offset:3072
	ds_read_b128 v[210:213], v201 offset:4096
	ds_read_b128 v[214:217], v201 offset:5120
	ds_read_b128 v[218:221], v201 offset:6144
	ds_read_b128 v[222:225], v201 offset:7168
	global_load_lds_dwordx4 v[226:227], off
	v_lshl_add_u64 v[226:227], s[8:9], 0, v[166:167]
	s_mov_b32 m0, s61
	s_nop 0
	global_load_lds_dwordx4 v[226:227], off
	s_waitcnt vmcnt(8)
	s_waitcnt lgkmcnt(0)
	s_setprio 1
	s_barrier
	v_mfma_f32_16x16x128_f8f6f4 v[158:161], v[18:25], v[182:189], 0
	v_mfma_f32_16x16x128_f8f6f4 v[154:157], v[26:33], v[182:189], 0
	v_mfma_f32_16x16x128_f8f6f4 v[146:149], v[26:33], v[202:209], 0
	v_mfma_f32_16x16x128_f8f6f4 v[150:153], v[18:25], v[202:209], 0
	v_mfma_f32_16x16x128_f8f6f4 v[142:145], v[18:25], v[210:217], 0
	v_mfma_f32_16x16x128_f8f6f4 v[138:141], v[26:33], v[210:217], 0
	v_mfma_f32_16x16x128_f8f6f4 v[130:133], v[26:33], v[218:225], 0
	v_mfma_f32_16x16x128_f8f6f4 v[134:137], v[18:25], v[218:225], 0
	v_mfma_f32_16x16x128_f8f6f4 v[102:105], v[2:9], v[218:225], 0
	v_mfma_f32_16x16x128_f8f6f4 v[98:101], v[10:17], v[218:225], 0
	v_mfma_f32_16x16x128_f8f6f4 v[106:109], v[10:17], v[210:217], 0
	v_mfma_f32_16x16x128_f8f6f4 v[110:113], v[2:9], v[210:217], 0
	v_mfma_f32_16x16x128_f8f6f4 v[118:121], v[2:9], v[202:209], 0
	v_mfma_f32_16x16x128_f8f6f4 v[114:117], v[10:17], v[202:209], 0
	v_mfma_f32_16x16x128_f8f6f4 v[122:125], v[10:17], v[182:189], 0
	v_mfma_f32_16x16x128_f8f6f4 v[126:129], v[2:9], v[182:189], 0
	s_barrier
	s_setprio 0
	v_lshl_add_u64 v[182:183], s[78:79], 0, v[164:165]
	s_mov_b32 m0, s68
	v_lshl_add_u64 v[184:185], v[182:183], 0, s[46:47]
	ds_read_b128 v[202:205], v201 offset:16384
	ds_read_b128 v[206:209], v201 offset:17408
	ds_read_b128 v[210:213], v201 offset:18432
	ds_read_b128 v[214:217], v201 offset:19456
	ds_read_b128 v[218:221], v201 offset:20480
	ds_read_b128 v[222:225], v201 offset:21504
	ds_read_b128 v[226:229], v201 offset:22528
	ds_read_b128 v[230:233], v201 offset:23552
	global_load_lds_dwordx4 v[184:185], off
	v_lshl_add_u64 v[184:185], s[78:79], 0, v[168:169]
	s_add_u32 s8, s78, 0x20100
	v_lshl_add_u64 v[186:187], v[184:185], 0, s[46:47]
	s_mov_b32 m0, s69
	s_addc_u32 s9, s79, 0
	global_load_lds_dwordx4 v[186:187], off
	v_lshl_add_u64 v[186:187], s[8:9], 0, v[164:165]
	s_mov_b32 m0, s77
	s_nop 0
	global_load_lds_dwordx4 v[186:187], off
	v_lshl_add_u64 v[186:187], s[8:9], 0, v[168:169]
	s_mov_b32 m0, s84
	s_nop 0
	global_load_lds_dwordx4 v[186:187], off
	v_lshl_add_u64 v[186:187], s[80:81], 0, v[162:163]
	v_lshl_add_u64 v[188:189], v[186:187], 0, s[46:47]
	s_mov_b32 m0, s33
	s_nop 0
	global_load_lds_dwordx4 v[188:189], off
	v_lshl_add_u64 v[188:189], s[80:81], 0, v[166:167]
	v_lshl_add_u64 v[234:235], v[188:189], 0, s[46:47]
	s_mov_b32 m0, s85
	s_nop 0
	global_load_lds_dwordx4 v[234:235], off
	s_waitcnt vmcnt(8)
	s_waitcnt lgkmcnt(0)
	s_setprio 1
	s_barrier
	v_mfma_f32_16x16x128_f8f6f4 v[94:97], v[18:25], v[202:209], 0
	v_mfma_f32_16x16x128_f8f6f4 v[90:93], v[26:33], v[202:209], 0
	v_mfma_f32_16x16x128_f8f6f4 v[82:85], v[26:33], v[210:217], 0
	v_mfma_f32_16x16x128_f8f6f4 v[86:89], v[18:25], v[210:217], 0
	v_mfma_f32_16x16x128_f8f6f4 v[78:81], v[18:25], v[218:225], 0
	v_mfma_f32_16x16x128_f8f6f4 v[74:77], v[26:33], v[218:225], 0
	v_mfma_f32_16x16x128_f8f6f4 v[66:69], v[26:33], v[226:233], 0
	v_mfma_f32_16x16x128_f8f6f4 v[70:73], v[18:25], v[226:233], 0
	v_mfma_f32_16x16x128_f8f6f4 v[38:41], v[2:9], v[226:233], 0
	v_mfma_f32_16x16x128_f8f6f4 v[34:37], v[10:17], v[226:233], 0
	v_mfma_f32_16x16x128_f8f6f4 v[42:45], v[10:17], v[218:225], 0
	v_mfma_f32_16x16x128_f8f6f4 v[46:49], v[2:9], v[218:225], 0
	v_mfma_f32_16x16x128_f8f6f4 v[54:57], v[2:9], v[210:217], 0
	v_mfma_f32_16x16x128_f8f6f4 v[50:53], v[10:17], v[210:217], 0
	v_mfma_f32_16x16x128_f8f6f4 v[58:61], v[10:17], v[202:209], 0
	v_mfma_f32_16x16x128_f8f6f4 v[62:65], v[2:9], v[202:209], 0
	s_barrier
	s_setprio 0
	ds_read_b128 v[18:21], v200 offset:32768
	ds_read_b128 v[22:25], v200 offset:33792
	ds_read_b128 v[26:29], v200 offset:34816
	ds_read_b128 v[30:33], v200 offset:35840
	ds_read_b128 v[2:5], v200 offset:49152
	ds_read_b128 v[6:9], v200 offset:50176
	ds_read_b128 v[10:13], v200 offset:51200
	ds_read_b128 v[14:17], v200 offset:52224
	s_add_u32 s8, s80, 0x20100
	s_addc_u32 s9, s81, 0
	s_mov_b32 m0, s86
	v_lshl_add_u64 v[234:235], s[8:9], 0, v[162:163]
	ds_read_b128 v[202:205], v201 offset:32768
	ds_read_b128 v[206:209], v201 offset:33792
	ds_read_b128 v[210:213], v201 offset:34816
	ds_read_b128 v[214:217], v201 offset:35840
	ds_read_b128 v[218:221], v201 offset:36864
	ds_read_b128 v[222:225], v201 offset:37888
	ds_read_b128 v[226:229], v201 offset:38912
	ds_read_b128 v[230:233], v201 offset:39936
	global_load_lds_dwordx4 v[234:235], off
	v_lshl_add_u64 v[234:235], s[8:9], 0, v[166:167]
	s_mov_b32 m0, s87
	s_nop 0
	global_load_lds_dwordx4 v[234:235], off
	s_waitcnt vmcnt(8)
	s_waitcnt lgkmcnt(0)
	s_setprio 1
	s_barrier
	v_mfma_f32_16x16x128_f8f6f4 v[158:161], v[18:25], v[202:209], v[158:161]
	v_mfma_f32_16x16x128_f8f6f4 v[154:157], v[26:33], v[202:209], v[154:157]
	v_mfma_f32_16x16x128_f8f6f4 v[146:149], v[26:33], v[210:217], v[146:149]
	v_mfma_f32_16x16x128_f8f6f4 v[150:153], v[18:25], v[210:217], v[150:153]
	v_mfma_f32_16x16x128_f8f6f4 v[142:145], v[18:25], v[218:225], v[142:145]
	v_mfma_f32_16x16x128_f8f6f4 v[138:141], v[26:33], v[218:225], v[138:141]
	v_mfma_f32_16x16x128_f8f6f4 v[130:133], v[26:33], v[226:233], v[130:133]
	v_mfma_f32_16x16x128_f8f6f4 v[134:137], v[18:25], v[226:233], v[134:137]
	v_mfma_f32_16x16x128_f8f6f4 v[102:105], v[2:9], v[226:233], v[102:105]
	v_mfma_f32_16x16x128_f8f6f4 v[98:101], v[10:17], v[226:233], v[98:101]
	v_mfma_f32_16x16x128_f8f6f4 v[106:109], v[10:17], v[218:225], v[106:109]
	v_mfma_f32_16x16x128_f8f6f4 v[110:113], v[2:9], v[218:225], v[110:113]
	v_mfma_f32_16x16x128_f8f6f4 v[118:121], v[2:9], v[210:217], v[118:121]
	v_mfma_f32_16x16x128_f8f6f4 v[114:117], v[10:17], v[210:217], v[114:117]
	v_mfma_f32_16x16x128_f8f6f4 v[122:125], v[10:17], v[202:209], v[122:125]
	v_mfma_f32_16x16x128_f8f6f4 v[126:129], v[2:9], v[202:209], v[126:129]
	s_barrier
	s_setprio 0
	s_mov_b32 m0, s89
	v_lshl_add_u64 v[182:183], v[182:183], 0, s[48:49]
	s_add_u32 s8, s78, 0x20180
	ds_read_b128 v[202:205], v201 offset:49152
	ds_read_b128 v[206:209], v201 offset:50176
	ds_read_b128 v[210:213], v201 offset:51200
	ds_read_b128 v[214:217], v201 offset:52224
	ds_read_b128 v[218:221], v201 offset:53248
	ds_read_b128 v[222:225], v201 offset:54272
	ds_read_b128 v[226:229], v201 offset:55296
	ds_read_b128 v[230:233], v201 offset:56320
	global_load_lds_dwordx4 v[182:183], off
	v_lshl_add_u64 v[182:183], v[184:185], 0, s[48:49]
	s_mov_b32 m0, s90
	s_addc_u32 s9, s79, 0
	global_load_lds_dwordx4 v[182:183], off
	v_lshl_add_u64 v[182:183], s[8:9], 0, v[164:165]
	s_mov_b32 m0, s93
	s_nop 0
	global_load_lds_dwordx4 v[182:183], off
	v_lshl_add_u64 v[182:183], s[8:9], 0, v[168:169]
	s_mov_b32 m0, s95
	s_nop 0
	global_load_lds_dwordx4 v[182:183], off
	v_lshl_add_u64 v[182:183], v[186:187], 0, s[48:49]
	s_mov_b32 m0, s91
	s_nop 0
	global_load_lds_dwordx4 v[182:183], off
	v_lshl_add_u64 v[182:183], v[188:189], 0, s[48:49]
	s_mov_b32 m0, s92
	s_nop 0
	global_load_lds_dwordx4 v[182:183], off
	s_waitcnt vmcnt(8)
	s_waitcnt lgkmcnt(0)
	s_setprio 1
	s_barrier
	v_mfma_f32_16x16x128_f8f6f4 v[94:97], v[18:25], v[202:209], v[94:97]
	v_mfma_f32_16x16x128_f8f6f4 v[90:93], v[26:33], v[202:209], v[90:93]
	v_mfma_f32_16x16x128_f8f6f4 v[82:85], v[26:33], v[210:217], v[82:85]
	v_mfma_f32_16x16x128_f8f6f4 v[86:89], v[18:25], v[210:217], v[86:89]
	v_mfma_f32_16x16x128_f8f6f4 v[78:81], v[18:25], v[218:225], v[78:81]
	v_mfma_f32_16x16x128_f8f6f4 v[74:77], v[26:33], v[218:225], v[74:77]
	v_mfma_f32_16x16x128_f8f6f4 v[66:69], v[26:33], v[226:233], v[66:69]
	v_mfma_f32_16x16x128_f8f6f4 v[70:73], v[18:25], v[226:233], v[70:73]
	v_mfma_f32_16x16x128_f8f6f4 v[38:41], v[2:9], v[226:233], v[38:41]
	v_mfma_f32_16x16x128_f8f6f4 v[34:37], v[10:17], v[226:233], v[34:37]
	v_mfma_f32_16x16x128_f8f6f4 v[42:45], v[10:17], v[218:225], v[42:45]
	v_mfma_f32_16x16x128_f8f6f4 v[46:49], v[2:9], v[218:225], v[46:49]
	v_mfma_f32_16x16x128_f8f6f4 v[54:57], v[2:9], v[210:217], v[54:57]
	v_mfma_f32_16x16x128_f8f6f4 v[50:53], v[10:17], v[210:217], v[50:53]
	v_mfma_f32_16x16x128_f8f6f4 v[58:61], v[10:17], v[202:209], v[58:61]
	v_mfma_f32_16x16x128_f8f6f4 v[62:65], v[2:9], v[202:209], v[62:65]
	s_barrier
	s_setprio 0
	s_add_u32 s80, s80, 0x20180
	s_addc_u32 s81, s81, 0
	s_add_u32 s8, s78, 0x200
	s_addc_u32 s9, s79, 0
	s_mov_b32 s62, 0
.LBB0_601:
	ds_read_b128 v[2:5], v200
	ds_read_b128 v[6:9], v200 offset:1024
	ds_read_b128 v[18:21], v200 offset:2048
	ds_read_b128 v[22:25], v200 offset:3072
	ds_read_b128 v[26:29], v200 offset:16384
	ds_read_b128 v[30:33], v200 offset:17408
	ds_read_b128 v[182:185], v200 offset:18432
	ds_read_b128 v[186:189], v200 offset:19456
	s_add_u32 s63, s80, 0xfffe0080
	s_addc_u32 s71, s81, -1
	s_cmp_eq_u32 s62, 4
	s_cselect_b32 s83, s4, s71
	s_cselect_b32 s82, s5, s63
	s_cselect_b32 s79, s53, s9
	s_cselect_b32 s78, s55, s8
	s_mov_b32 m0, s96
	v_lshl_add_u64 v[226:227], s[80:81], 0, v[170:171]
	ds_read_b128 v[10:13], v201
	ds_read_b128 v[14:17], v201 offset:1024
	ds_read_b128 v[202:205], v201 offset:2048
	ds_read_b128 v[206:209], v201 offset:3072
	ds_read_b128 v[210:213], v201 offset:4096
	ds_read_b128 v[214:217], v201 offset:5120
	ds_read_b128 v[218:221], v201 offset:6144
	ds_read_b128 v[222:225], v201 offset:7168
	global_load_lds_dwordx4 v[226:227], off
	v_lshl_add_u64 v[226:227], s[80:81], 0, v[172:173]
	s_mov_b32 m0, s61
	s_nop 0
	global_load_lds_dwordx4 v[226:227], off
	s_waitcnt vmcnt(8)
	s_waitcnt lgkmcnt(0)
	s_setprio 1
	s_barrier
	v_mfma_f32_16x16x128_f8f6f4 v[158:161], v[2:9], v[10:17], v[158:161]
	v_mfma_f32_16x16x128_f8f6f4 v[154:157], v[18:25], v[10:17], v[154:157]
	v_mfma_f32_16x16x128_f8f6f4 v[146:149], v[18:25], v[202:209], v[146:149]
	v_mfma_f32_16x16x128_f8f6f4 v[150:153], v[2:9], v[202:209], v[150:153]
	v_mfma_f32_16x16x128_f8f6f4 v[142:145], v[2:9], v[210:217], v[142:145]
	v_mfma_f32_16x16x128_f8f6f4 v[138:141], v[18:25], v[210:217], v[138:141]
	v_mfma_f32_16x16x128_f8f6f4 v[130:133], v[18:25], v[218:225], v[130:133]
	v_mfma_f32_16x16x128_f8f6f4 v[134:137], v[2:9], v[218:225], v[134:137]
	v_mfma_f32_16x16x128_f8f6f4 v[102:105], v[26:33], v[218:225], v[102:105]
	v_mfma_f32_16x16x128_f8f6f4 v[98:101], v[182:189], v[218:225], v[98:101]
	v_mfma_f32_16x16x128_f8f6f4 v[106:109], v[182:189], v[210:217], v[106:109]
	v_mfma_f32_16x16x128_f8f6f4 v[110:113], v[26:33], v[210:217], v[110:113]
	v_mfma_f32_16x16x128_f8f6f4 v[118:121], v[26:33], v[202:209], v[118:121]
	v_mfma_f32_16x16x128_f8f6f4 v[114:117], v[182:189], v[202:209], v[114:117]
	v_mfma_f32_16x16x128_f8f6f4 v[122:125], v[182:189], v[10:17], v[122:125]
	v_mfma_f32_16x16x128_f8f6f4 v[126:129], v[26:33], v[10:17], v[126:129]
	s_barrier
	s_setprio 0
	s_mov_b32 m0, s68
	v_lshl_add_u64 v[10:11], s[78:79], 0, v[164:165]
	s_add_u32 vcc_lo, s78, 0x20000
	ds_read_b128 v[202:205], v201 offset:16384
	ds_read_b128 v[206:209], v201 offset:17408
	ds_read_b128 v[210:213], v201 offset:18432
	ds_read_b128 v[214:217], v201 offset:19456
	ds_read_b128 v[218:221], v201 offset:20480
	ds_read_b128 v[222:225], v201 offset:21504
	ds_read_b128 v[226:229], v201 offset:22528
	ds_read_b128 v[230:233], v201 offset:23552
	global_load_lds_dwordx4 v[10:11], off
	v_lshl_add_u64 v[12:13], s[78:79], 0, v[168:169]
	s_mov_b32 m0, s69
	s_addc_u32 vcc_hi, s79, 0
	global_load_lds_dwordx4 v[12:13], off
	v_lshl_add_u64 v[14:15], vcc, 0, v[164:165]
	s_mov_b32 m0, s77
	v_lshl_add_u64 v[16:17], s[82:83], 0, v[166:167]
	global_load_lds_dwordx4 v[14:15], off
	v_lshl_add_u64 v[14:15], vcc, 0, v[168:169]
	s_mov_b32 m0, s84
	s_nop 0
	global_load_lds_dwordx4 v[14:15], off
	v_lshl_add_u64 v[14:15], s[82:83], 0, v[162:163]
	s_mov_b32 m0, s33
	s_nop 0
	global_load_lds_dwordx4 v[14:15], off
	s_mov_b32 m0, s85
	s_nop 0
	global_load_lds_dwordx4 v[16:17], off
	s_waitcnt vmcnt(8)
	s_waitcnt lgkmcnt(0)
	s_setprio 1
	s_barrier
	v_mfma_f32_16x16x128_f8f6f4 v[94:97], v[2:9], v[202:209], v[94:97]
	v_mfma_f32_16x16x128_f8f6f4 v[90:93], v[18:25], v[202:209], v[90:93]
	v_mfma_f32_16x16x128_f8f6f4 v[82:85], v[18:25], v[210:217], v[82:85]
	v_mfma_f32_16x16x128_f8f6f4 v[86:89], v[2:9], v[210:217], v[86:89]
	v_mfma_f32_16x16x128_f8f6f4 v[78:81], v[2:9], v[218:225], v[78:81]
	v_mfma_f32_16x16x128_f8f6f4 v[74:77], v[18:25], v[218:225], v[74:77]
	v_mfma_f32_16x16x128_f8f6f4 v[66:69], v[18:25], v[226:233], v[66:69]
	v_mfma_f32_16x16x128_f8f6f4 v[70:73], v[2:9], v[226:233], v[70:73]
	v_mfma_f32_16x16x128_f8f6f4 v[38:41], v[26:33], v[226:233], v[38:41]
	v_mfma_f32_16x16x128_f8f6f4 v[34:37], v[182:189], v[226:233], v[34:37]
	v_mfma_f32_16x16x128_f8f6f4 v[42:45], v[182:189], v[218:225], v[42:45]
	v_mfma_f32_16x16x128_f8f6f4 v[46:49], v[26:33], v[218:225], v[46:49]
	v_mfma_f32_16x16x128_f8f6f4 v[54:57], v[26:33], v[210:217], v[54:57]
	v_mfma_f32_16x16x128_f8f6f4 v[50:53], v[182:189], v[210:217], v[50:53]
	v_mfma_f32_16x16x128_f8f6f4 v[58:61], v[182:189], v[202:209], v[58:61]
	v_mfma_f32_16x16x128_f8f6f4 v[62:65], v[26:33], v[202:209], v[62:65]
	s_barrier
	s_setprio 0
	ds_read_b128 v[18:21], v200 offset:32768
	ds_read_b128 v[22:25], v200 offset:33792
	ds_read_b128 v[26:29], v200 offset:34816
	ds_read_b128 v[30:33], v200 offset:35840
	ds_read_b128 v[2:5], v200 offset:49152
	ds_read_b128 v[6:9], v200 offset:50176
	ds_read_b128 v[182:185], v200 offset:51200
	ds_read_b128 v[186:189], v200 offset:52224
	s_add_u32 s82, s82, 0x20000
	s_addc_u32 s83, s83, 0
	s_mov_b32 m0, s86
	v_lshl_add_u64 v[234:235], s[82:83], 0, v[162:163]
	ds_read_b128 v[202:205], v201 offset:32768
	ds_read_b128 v[206:209], v201 offset:33792
	ds_read_b128 v[210:213], v201 offset:34816
	ds_read_b128 v[214:217], v201 offset:35840
	ds_read_b128 v[218:221], v201 offset:36864
	ds_read_b128 v[222:225], v201 offset:37888
	ds_read_b128 v[226:229], v201 offset:38912
	ds_read_b128 v[230:233], v201 offset:39936
	global_load_lds_dwordx4 v[234:235], off
	v_lshl_add_u64 v[234:235], s[82:83], 0, v[166:167]
	s_mov_b32 m0, s87
	s_nop 0
	global_load_lds_dwordx4 v[234:235], off
	s_waitcnt vmcnt(8)
	s_waitcnt lgkmcnt(0)
	s_setprio 1
	s_barrier
	v_mfma_f32_16x16x128_f8f6f4 v[158:161], v[18:25], v[202:209], v[158:161]
	v_mfma_f32_16x16x128_f8f6f4 v[154:157], v[26:33], v[202:209], v[154:157]
	v_mfma_f32_16x16x128_f8f6f4 v[146:149], v[26:33], v[210:217], v[146:149]
	v_mfma_f32_16x16x128_f8f6f4 v[150:153], v[18:25], v[210:217], v[150:153]
	v_mfma_f32_16x16x128_f8f6f4 v[142:145], v[18:25], v[218:225], v[142:145]
	v_mfma_f32_16x16x128_f8f6f4 v[138:141], v[26:33], v[218:225], v[138:141]
	v_mfma_f32_16x16x128_f8f6f4 v[130:133], v[26:33], v[226:233], v[130:133]
	v_mfma_f32_16x16x128_f8f6f4 v[134:137], v[18:25], v[226:233], v[134:137]
	v_mfma_f32_16x16x128_f8f6f4 v[102:105], v[2:9], v[226:233], v[102:105]
	v_mfma_f32_16x16x128_f8f6f4 v[98:101], v[182:189], v[226:233], v[98:101]
	v_mfma_f32_16x16x128_f8f6f4 v[106:109], v[182:189], v[218:225], v[106:109]
	v_mfma_f32_16x16x128_f8f6f4 v[110:113], v[2:9], v[218:225], v[110:113]
	v_mfma_f32_16x16x128_f8f6f4 v[118:121], v[2:9], v[210:217], v[118:121]
	v_mfma_f32_16x16x128_f8f6f4 v[114:117], v[182:189], v[210:217], v[114:117]
	v_mfma_f32_16x16x128_f8f6f4 v[122:125], v[182:189], v[202:209], v[122:125]
	v_mfma_f32_16x16x128_f8f6f4 v[126:129], v[2:9], v[202:209], v[126:129]
	s_barrier
	s_setprio 0
	s_mov_b32 m0, s89
	v_lshl_add_u64 v[10:11], v[10:11], 0, s[42:43]
	s_add_u32 s78, s78, 0x20080
	ds_read_b128 v[202:205], v201 offset:49152
	ds_read_b128 v[206:209], v201 offset:50176
	ds_read_b128 v[210:213], v201 offset:51200
	ds_read_b128 v[214:217], v201 offset:52224
	ds_read_b128 v[218:221], v201 offset:53248
	ds_read_b128 v[222:225], v201 offset:54272
	ds_read_b128 v[226:229], v201 offset:55296
	ds_read_b128 v[230:233], v201 offset:56320
	global_load_lds_dwordx4 v[10:11], off
	v_lshl_add_u64 v[10:11], v[12:13], 0, s[42:43]
	s_mov_b32 m0, s90
	s_addc_u32 s79, s79, 0
	global_load_lds_dwordx4 v[10:11], off
	v_lshl_add_u64 v[10:11], s[78:79], 0, v[164:165]
	s_mov_b32 m0, s93
	s_nop 0
	global_load_lds_dwordx4 v[10:11], off
	v_lshl_add_u64 v[10:11], s[78:79], 0, v[168:169]
	s_mov_b32 m0, s95
	s_nop 0
	global_load_lds_dwordx4 v[10:11], off
	v_lshl_add_u64 v[10:11], v[14:15], 0, s[42:43]
	s_mov_b32 m0, s91
	s_nop 0
	global_load_lds_dwordx4 v[10:11], off
	v_lshl_add_u64 v[10:11], v[16:17], 0, s[42:43]
	s_mov_b32 m0, s92
	s_nop 0
	global_load_lds_dwordx4 v[10:11], off
	s_waitcnt vmcnt(8)
	s_waitcnt lgkmcnt(0)
	s_setprio 1
	s_barrier
	v_mfma_f32_16x16x128_f8f6f4 v[94:97], v[18:25], v[202:209], v[94:97]
	v_mfma_f32_16x16x128_f8f6f4 v[90:93], v[26:33], v[202:209], v[90:93]
	v_mfma_f32_16x16x128_f8f6f4 v[82:85], v[26:33], v[210:217], v[82:85]
	v_mfma_f32_16x16x128_f8f6f4 v[86:89], v[18:25], v[210:217], v[86:89]
	v_mfma_f32_16x16x128_f8f6f4 v[78:81], v[18:25], v[218:225], v[78:81]
	v_mfma_f32_16x16x128_f8f6f4 v[74:77], v[26:33], v[218:225], v[74:77]
	v_mfma_f32_16x16x128_f8f6f4 v[66:69], v[26:33], v[226:233], v[66:69]
	v_mfma_f32_16x16x128_f8f6f4 v[70:73], v[18:25], v[226:233], v[70:73]
	v_mfma_f32_16x16x128_f8f6f4 v[38:41], v[2:9], v[226:233], v[38:41]
	v_mfma_f32_16x16x128_f8f6f4 v[34:37], v[182:189], v[226:233], v[34:37]
	v_mfma_f32_16x16x128_f8f6f4 v[42:45], v[182:189], v[218:225], v[42:45]
	v_mfma_f32_16x16x128_f8f6f4 v[46:49], v[2:9], v[218:225], v[46:49]
	v_mfma_f32_16x16x128_f8f6f4 v[54:57], v[2:9], v[210:217], v[54:57]
	v_mfma_f32_16x16x128_f8f6f4 v[50:53], v[182:189], v[210:217], v[50:53]
	v_mfma_f32_16x16x128_f8f6f4 v[58:61], v[182:189], v[202:209], v[58:61]
	v_mfma_f32_16x16x128_f8f6f4 v[62:65], v[2:9], v[202:209], v[62:65]
	s_barrier
	s_setprio 0
	s_add_i32 s62, s62, 2
	s_add_u32 s80, s80, 0x100
	s_addc_u32 s81, s81, 0
	s_add_u32 s8, s8, 0x100
	s_addc_u32 s9, s9, 0
	s_cmp_gt_u32 s62, 5
	s_cbranch_scc0 .LBB0_601
	s_and_b64 vcc, exec, s[44:45]
	s_cbranch_vccz .LBB0_604
	s_barrier

.LBB0_616:
	ds_read_b128 v[18:21], v188
	ds_read_b128 v[22:25], v188 offset:1024
	ds_read_b128 v[26:29], v188 offset:2048
	ds_read_b128 v[30:33], v188 offset:3072
	ds_read_b128 v[2:5], v188 offset:16384
	ds_read_b128 v[6:9], v188 offset:17408
	ds_read_b128 v[10:13], v188 offset:18432
	ds_read_b128 v[14:17], v188 offset:19456
	s_ashr_i32 s55, s54, 31
	s_lshl_b64 s[62:63], s[54:55], 17
	s_add_u32 s72, s36, s62
	s_addc_u32 s73, s37, s63
	s_and_b64 s[62:63], s[2:3], exec
	s_cselect_b32 s85, s73, s79
	s_cselect_b32 s84, s72, s78
	s_ashr_i32 s53, s52, 31
	s_lshl_b64 s[62:63], s[52:53], 17
	s_add_u32 s74, s94, s62
	v_readlane_b32 s5, v254, 8
	s_addc_u32 s75, s5, s63
	s_and_b64 s[62:63], s[2:3], exec
	s_cselect_b32 s83, s75, s81
	s_cselect_b32 s82, s74, s80
	s_add_u32 s62, s78, 0x10080
	s_addc_u32 s63, s79, 0
	s_mov_b32 m0, s96
	v_lshl_add_u64 v[174:175], s[62:63], 0, v[166:167]
	ds_read_b128 v[196:199], v189
	ds_read_b128 v[200:203], v189 offset:1024
	ds_read_b128 v[204:207], v189 offset:2048
	ds_read_b128 v[208:211], v189 offset:3072
	ds_read_b128 v[212:215], v189 offset:4096
	ds_read_b128 v[216:219], v189 offset:5120
	ds_read_b128 v[220:223], v189 offset:6144
	ds_read_b128 v[224:227], v189 offset:7168
	global_load_lds_dwordx4 v[174:175], off
	v_lshl_add_u64 v[174:175], s[62:63], 0, v[168:169]
	s_mov_b32 m0, s97
	s_nop 0
	global_load_lds_dwordx4 v[174:175], off
	s_waitcnt vmcnt(8)
	s_waitcnt lgkmcnt(0)
	s_setprio 1
	s_barrier
	v_mfma_f32_16x16x128_f8f6f4 v[158:161], v[18:25], v[196:203], 0
	v_mfma_f32_16x16x128_f8f6f4 v[154:157], v[26:33], v[196:203], 0
	v_mfma_f32_16x16x128_f8f6f4 v[146:149], v[26:33], v[204:211], 0
	v_mfma_f32_16x16x128_f8f6f4 v[150:153], v[18:25], v[204:211], 0
	v_mfma_f32_16x16x128_f8f6f4 v[142:145], v[18:25], v[212:219], 0
	v_mfma_f32_16x16x128_f8f6f4 v[138:141], v[26:33], v[212:219], 0
	v_mfma_f32_16x16x128_f8f6f4 v[130:133], v[26:33], v[220:227], 0
	v_mfma_f32_16x16x128_f8f6f4 v[134:137], v[18:25], v[220:227], 0
	v_mfma_f32_16x16x128_f8f6f4 v[102:105], v[2:9], v[220:227], 0
	v_mfma_f32_16x16x128_f8f6f4 v[98:101], v[10:17], v[220:227], 0
	v_mfma_f32_16x16x128_f8f6f4 v[106:109], v[10:17], v[212:219], 0
	v_mfma_f32_16x16x128_f8f6f4 v[110:113], v[2:9], v[212:219], 0
	v_mfma_f32_16x16x128_f8f6f4 v[118:121], v[2:9], v[204:211], 0
	v_mfma_f32_16x16x128_f8f6f4 v[114:117], v[10:17], v[204:211], 0
	v_mfma_f32_16x16x128_f8f6f4 v[122:125], v[10:17], v[196:203], 0
	v_mfma_f32_16x16x128_f8f6f4 v[126:129], v[2:9], v[196:203], 0
	s_barrier
	s_setprio 0
	v_lshl_add_u64 v[174:175], s[80:81], 0, v[162:163]
	s_mov_b32 m0, s61
	v_lshl_add_u64 v[176:177], v[174:175], 0, s[46:47]
	ds_read_b128 v[196:199], v189 offset:16384
	ds_read_b128 v[200:203], v189 offset:17408
	ds_read_b128 v[204:207], v189 offset:18432
	ds_read_b128 v[208:211], v189 offset:19456
	ds_read_b128 v[212:215], v189 offset:20480
	ds_read_b128 v[216:219], v189 offset:21504
	ds_read_b128 v[220:223], v189 offset:22528
	ds_read_b128 v[224:227], v189 offset:23552
	global_load_lds_dwordx4 v[176:177], off
	v_lshl_add_u64 v[176:177], s[80:81], 0, v[164:165]
	s_add_u32 s62, s80, 0x10100
	v_lshl_add_u64 v[182:183], v[176:177], 0, s[46:47]
	s_mov_b32 m0, s68
	s_addc_u32 s63, s81, 0
	global_load_lds_dwordx4 v[182:183], off
	v_lshl_add_u64 v[182:183], s[62:63], 0, v[162:163]
	s_mov_b32 m0, s69
	s_nop 0
	global_load_lds_dwordx4 v[182:183], off
	v_lshl_add_u64 v[182:183], s[62:63], 0, v[164:165]
	s_mov_b32 m0, s77
	s_nop 0
	global_load_lds_dwordx4 v[182:183], off
	v_lshl_add_u64 v[182:183], s[78:79], 0, v[166:167]
	v_lshl_add_u64 v[184:185], v[182:183], 0, s[46:47]
	s_mov_b32 m0, s51
	s_nop 0
	global_load_lds_dwordx4 v[184:185], off
	v_lshl_add_u64 v[184:185], s[78:79], 0, v[168:169]
	v_lshl_add_u64 v[228:229], v[184:185], 0, s[46:47]
	s_mov_b32 m0, s86
	s_nop 0
	global_load_lds_dwordx4 v[228:229], off
	s_waitcnt vmcnt(8)
	s_waitcnt lgkmcnt(0)
	s_setprio 1
	s_barrier
	v_mfma_f32_16x16x128_f8f6f4 v[94:97], v[18:25], v[196:203], 0
	v_mfma_f32_16x16x128_f8f6f4 v[90:93], v[26:33], v[196:203], 0
	v_mfma_f32_16x16x128_f8f6f4 v[82:85], v[26:33], v[204:211], 0
	v_mfma_f32_16x16x128_f8f6f4 v[86:89], v[18:25], v[204:211], 0
	v_mfma_f32_16x16x128_f8f6f4 v[78:81], v[18:25], v[212:219], 0
	v_mfma_f32_16x16x128_f8f6f4 v[74:77], v[26:33], v[212:219], 0
	v_mfma_f32_16x16x128_f8f6f4 v[66:69], v[26:33], v[220:227], 0
	v_mfma_f32_16x16x128_f8f6f4 v[70:73], v[18:25], v[220:227], 0
	v_mfma_f32_16x16x128_f8f6f4 v[38:41], v[2:9], v[220:227], 0
	v_mfma_f32_16x16x128_f8f6f4 v[34:37], v[10:17], v[220:227], 0
	v_mfma_f32_16x16x128_f8f6f4 v[42:45], v[10:17], v[212:219], 0
	v_mfma_f32_16x16x128_f8f6f4 v[46:49], v[2:9], v[212:219], 0
	v_mfma_f32_16x16x128_f8f6f4 v[54:57], v[2:9], v[204:211], 0
	v_mfma_f32_16x16x128_f8f6f4 v[50:53], v[10:17], v[204:211], 0
	v_mfma_f32_16x16x128_f8f6f4 v[58:61], v[10:17], v[196:203], 0
	v_mfma_f32_16x16x128_f8f6f4 v[62:65], v[2:9], v[196:203], 0
	s_barrier
	s_setprio 0
	ds_read_b128 v[2:5], v188 offset:32768
	ds_read_b128 v[6:9], v188 offset:33792
	ds_read_b128 v[10:13], v188 offset:34816
	ds_read_b128 v[14:17], v188 offset:35840
	ds_read_b128 v[18:21], v188 offset:49152
	ds_read_b128 v[22:25], v188 offset:50176
	ds_read_b128 v[26:29], v188 offset:51200
	ds_read_b128 v[30:33], v188 offset:52224
	s_add_u32 s62, s78, 0x10100
	s_addc_u32 s63, s79, 0
	s_mov_b32 m0, s87
	v_lshl_add_u64 v[228:229], s[62:63], 0, v[166:167]
	ds_read_b128 v[196:199], v189 offset:32768
	ds_read_b128 v[200:203], v189 offset:33792
	ds_read_b128 v[204:207], v189 offset:34816
	ds_read_b128 v[208:211], v189 offset:35840
	ds_read_b128 v[212:215], v189 offset:36864
	ds_read_b128 v[216:219], v189 offset:37888
	ds_read_b128 v[220:223], v189 offset:38912
	ds_read_b128 v[224:227], v189 offset:39936
	global_load_lds_dwordx4 v[228:229], off
	v_lshl_add_u64 v[228:229], s[62:63], 0, v[168:169]
	s_mov_b32 m0, s88
	s_nop 0
	global_load_lds_dwordx4 v[228:229], off
	s_waitcnt vmcnt(8)
	s_waitcnt lgkmcnt(0)
	s_setprio 1
	s_barrier
	v_mfma_f32_16x16x128_f8f6f4 v[158:161], v[2:9], v[196:203], v[158:161]
	v_mfma_f32_16x16x128_f8f6f4 v[154:157], v[10:17], v[196:203], v[154:157]
	v_mfma_f32_16x16x128_f8f6f4 v[146:149], v[10:17], v[204:211], v[146:149]
	v_mfma_f32_16x16x128_f8f6f4 v[150:153], v[2:9], v[204:211], v[150:153]
	v_mfma_f32_16x16x128_f8f6f4 v[142:145], v[2:9], v[212:219], v[142:145]
	v_mfma_f32_16x16x128_f8f6f4 v[138:141], v[10:17], v[212:219], v[138:141]
	v_mfma_f32_16x16x128_f8f6f4 v[130:133], v[10:17], v[220:227], v[130:133]
	v_mfma_f32_16x16x128_f8f6f4 v[134:137], v[2:9], v[220:227], v[134:137]
	v_mfma_f32_16x16x128_f8f6f4 v[102:105], v[18:25], v[220:227], v[102:105]
	v_mfma_f32_16x16x128_f8f6f4 v[98:101], v[26:33], v[220:227], v[98:101]
	v_mfma_f32_16x16x128_f8f6f4 v[106:109], v[26:33], v[212:219], v[106:109]
	v_mfma_f32_16x16x128_f8f6f4 v[110:113], v[18:25], v[212:219], v[110:113]
	v_mfma_f32_16x16x128_f8f6f4 v[118:121], v[18:25], v[204:211], v[118:121]
	v_mfma_f32_16x16x128_f8f6f4 v[114:117], v[26:33], v[204:211], v[114:117]
	v_mfma_f32_16x16x128_f8f6f4 v[122:125], v[26:33], v[196:203], v[122:125]
	v_mfma_f32_16x16x128_f8f6f4 v[126:129], v[18:25], v[196:203], v[126:129]
	s_barrier
	s_setprio 0
	s_mov_b32 m0, s89
	v_lshl_add_u64 v[174:175], v[174:175], 0, s[48:49]
	s_add_u32 s62, s80, 0x10180
	ds_read_b128 v[196:199], v189 offset:49152
	ds_read_b128 v[200:203], v189 offset:50176
	ds_read_b128 v[204:207], v189 offset:51200
	ds_read_b128 v[208:211], v189 offset:52224
	ds_read_b128 v[212:215], v189 offset:53248
	ds_read_b128 v[216:219], v189 offset:54272
	ds_read_b128 v[220:223], v189 offset:55296
	ds_read_b128 v[224:227], v189 offset:56320
	global_load_lds_dwordx4 v[174:175], off
	v_lshl_add_u64 v[174:175], v[176:177], 0, s[48:49]
	s_mov_b32 m0, s90
	s_addc_u32 s63, s81, 0
	global_load_lds_dwordx4 v[174:175], off
	v_lshl_add_u64 v[174:175], s[62:63], 0, v[162:163]
	s_mov_b32 m0, s93
	s_nop 0
	global_load_lds_dwordx4 v[174:175], off
	v_lshl_add_u64 v[174:175], s[62:63], 0, v[164:165]
	s_mov_b32 m0, s95
	s_nop 0
	global_load_lds_dwordx4 v[174:175], off
	v_lshl_add_u64 v[174:175], v[182:183], 0, s[48:49]
	s_mov_b32 m0, s91
	s_nop 0
	global_load_lds_dwordx4 v[174:175], off
	v_lshl_add_u64 v[174:175], v[184:185], 0, s[48:49]
	s_mov_b32 m0, s92
	s_nop 0
	global_load_lds_dwordx4 v[174:175], off
	s_waitcnt vmcnt(8)
	s_waitcnt lgkmcnt(0)
	s_setprio 1
	s_barrier
	v_mfma_f32_16x16x128_f8f6f4 v[94:97], v[2:9], v[196:203], v[94:97]
	v_mfma_f32_16x16x128_f8f6f4 v[90:93], v[10:17], v[196:203], v[90:93]
	v_mfma_f32_16x16x128_f8f6f4 v[82:85], v[10:17], v[204:211], v[82:85]
	v_mfma_f32_16x16x128_f8f6f4 v[86:89], v[2:9], v[204:211], v[86:89]
	v_mfma_f32_16x16x128_f8f6f4 v[78:81], v[2:9], v[212:219], v[78:81]
	v_mfma_f32_16x16x128_f8f6f4 v[74:77], v[10:17], v[212:219], v[74:77]
	v_mfma_f32_16x16x128_f8f6f4 v[66:69], v[10:17], v[220:227], v[66:69]
	v_mfma_f32_16x16x128_f8f6f4 v[70:73], v[2:9], v[220:227], v[70:73]
	v_mfma_f32_16x16x128_f8f6f4 v[38:41], v[18:25], v[220:227], v[38:41]
	v_mfma_f32_16x16x128_f8f6f4 v[34:37], v[26:33], v[220:227], v[34:37]
	v_mfma_f32_16x16x128_f8f6f4 v[42:45], v[26:33], v[212:219], v[42:45]
	v_mfma_f32_16x16x128_f8f6f4 v[46:49], v[18:25], v[212:219], v[46:49]
	v_mfma_f32_16x16x128_f8f6f4 v[54:57], v[18:25], v[204:211], v[54:57]
	v_mfma_f32_16x16x128_f8f6f4 v[50:53], v[26:33], v[204:211], v[50:53]
	v_mfma_f32_16x16x128_f8f6f4 v[58:61], v[26:33], v[196:203], v[58:61]
	v_mfma_f32_16x16x128_f8f6f4 v[62:65], v[18:25], v[196:203], v[62:65]
	s_barrier
	s_setprio 0
	ds_read_b128 v[2:5], v188
	ds_read_b128 v[6:9], v188 offset:1024
	ds_read_b128 v[10:13], v188 offset:2048
	ds_read_b128 v[14:17], v188 offset:3072
	ds_read_b128 v[18:21], v188 offset:16384
	ds_read_b128 v[22:25], v188 offset:17408
	ds_read_b128 v[26:29], v188 offset:18432
	ds_read_b128 v[30:33], v188 offset:19456
	s_add_u32 s62, s78, 0x10180
	s_addc_u32 s63, s79, 0
	s_mov_b32 m0, s96
	v_lshl_add_u64 v[174:175], s[62:63], 0, v[166:167]
	ds_read_b128 v[196:199], v189
	ds_read_b128 v[200:203], v189 offset:1024
	ds_read_b128 v[204:207], v189 offset:2048
	ds_read_b128 v[208:211], v189 offset:3072
	ds_read_b128 v[212:215], v189 offset:4096
	ds_read_b128 v[216:219], v189 offset:5120
	ds_read_b128 v[220:223], v189 offset:6144
	ds_read_b128 v[224:227], v189 offset:7168
	global_load_lds_dwordx4 v[174:175], off
	v_lshl_add_u64 v[174:175], s[62:63], 0, v[168:169]
	s_mov_b32 m0, s97
	s_nop 0
	global_load_lds_dwordx4 v[174:175], off
	s_waitcnt vmcnt(8)
	s_waitcnt lgkmcnt(0)
	s_setprio 1
	s_barrier
	v_mfma_f32_16x16x128_f8f6f4 v[158:161], v[2:9], v[196:203], v[158:161]
	v_mfma_f32_16x16x128_f8f6f4 v[154:157], v[10:17], v[196:203], v[154:157]
	v_mfma_f32_16x16x128_f8f6f4 v[146:149], v[10:17], v[204:211], v[146:149]
	v_mfma_f32_16x16x128_f8f6f4 v[150:153], v[2:9], v[204:211], v[150:153]
	v_mfma_f32_16x16x128_f8f6f4 v[142:145], v[2:9], v[212:219], v[142:145]
	v_mfma_f32_16x16x128_f8f6f4 v[138:141], v[10:17], v[212:219], v[138:141]
	v_mfma_f32_16x16x128_f8f6f4 v[130:133], v[10:17], v[220:227], v[130:133]
	v_mfma_f32_16x16x128_f8f6f4 v[134:137], v[2:9], v[220:227], v[134:137]
	v_mfma_f32_16x16x128_f8f6f4 v[102:105], v[18:25], v[220:227], v[102:105]
	v_mfma_f32_16x16x128_f8f6f4 v[98:101], v[26:33], v[220:227], v[98:101]
	v_mfma_f32_16x16x128_f8f6f4 v[106:109], v[26:33], v[212:219], v[106:109]
	v_mfma_f32_16x16x128_f8f6f4 v[110:113], v[18:25], v[212:219], v[110:113]
	v_mfma_f32_16x16x128_f8f6f4 v[118:121], v[18:25], v[204:211], v[118:121]
	v_mfma_f32_16x16x128_f8f6f4 v[114:117], v[26:33], v[204:211], v[114:117]
	v_mfma_f32_16x16x128_f8f6f4 v[122:125], v[26:33], v[196:203], v[122:125]
	v_mfma_f32_16x16x128_f8f6f4 v[126:129], v[18:25], v[196:203], v[126:129]
	s_barrier
	s_setprio 0
	s_mov_b32 m0, s61
	v_lshl_add_u64 v[174:175], s[82:83], 0, v[162:163]
	s_add_u32 s62, s82, 0x10000
	ds_read_b128 v[196:199], v189 offset:16384
	ds_read_b128 v[200:203], v189 offset:17408
	ds_read_b128 v[204:207], v189 offset:18432
	ds_read_b128 v[208:211], v189 offset:19456
	ds_read_b128 v[212:215], v189 offset:20480
	ds_read_b128 v[216:219], v189 offset:21504
	ds_read_b128 v[220:223], v189 offset:22528
	ds_read_b128 v[224:227], v189 offset:23552
	global_load_lds_dwordx4 v[174:175], off
	v_lshl_add_u64 v[176:177], s[82:83], 0, v[164:165]
	s_mov_b32 m0, s68
	s_addc_u32 s63, s83, 0
	global_load_lds_dwordx4 v[176:177], off
	v_lshl_add_u64 v[182:183], s[62:63], 0, v[162:163]
	s_mov_b32 m0, s69
	v_lshl_add_u64 v[184:185], s[84:85], 0, v[168:169]
	global_load_lds_dwordx4 v[182:183], off
	v_lshl_add_u64 v[182:183], s[62:63], 0, v[164:165]
	s_mov_b32 m0, s77
	s_nop 0
	global_load_lds_dwordx4 v[182:183], off
	v_lshl_add_u64 v[182:183], s[84:85], 0, v[166:167]
	s_mov_b32 m0, s51
	s_nop 0
	global_load_lds_dwordx4 v[182:183], off
	s_mov_b32 m0, s86
	s_nop 0
	global_load_lds_dwordx4 v[184:185], off
	s_waitcnt vmcnt(8)
	s_waitcnt lgkmcnt(0)
	s_setprio 1
	s_barrier
	v_mfma_f32_16x16x128_f8f6f4 v[94:97], v[2:9], v[196:203], v[94:97]
	v_mfma_f32_16x16x128_f8f6f4 v[90:93], v[10:17], v[196:203], v[90:93]
	v_mfma_f32_16x16x128_f8f6f4 v[82:85], v[10:17], v[204:211], v[82:85]
	v_mfma_f32_16x16x128_f8f6f4 v[86:89], v[2:9], v[204:211], v[86:89]
	v_mfma_f32_16x16x128_f8f6f4 v[78:81], v[2:9], v[212:219], v[78:81]
	v_mfma_f32_16x16x128_f8f6f4 v[74:77], v[10:17], v[212:219], v[74:77]
	v_mfma_f32_16x16x128_f8f6f4 v[66:69], v[10:17], v[220:227], v[66:69]
	v_mfma_f32_16x16x128_f8f6f4 v[70:73], v[2:9], v[220:227], v[70:73]
	v_mfma_f32_16x16x128_f8f6f4 v[38:41], v[18:25], v[220:227], v[38:41]
	v_mfma_f32_16x16x128_f8f6f4 v[34:37], v[26:33], v[220:227], v[34:37]
	v_mfma_f32_16x16x128_f8f6f4 v[42:45], v[26:33], v[212:219], v[42:45]
	v_mfma_f32_16x16x128_f8f6f4 v[46:49], v[18:25], v[212:219], v[46:49]
	v_mfma_f32_16x16x128_f8f6f4 v[54:57], v[18:25], v[204:211], v[54:57]
	v_mfma_f32_16x16x128_f8f6f4 v[50:53], v[26:33], v[204:211], v[50:53]
	v_mfma_f32_16x16x128_f8f6f4 v[58:61], v[26:33], v[196:203], v[58:61]
	v_mfma_f32_16x16x128_f8f6f4 v[62:65], v[18:25], v[196:203], v[62:65]
	s_barrier
	s_setprio 0
	ds_read_b128 v[2:5], v188 offset:32768
	ds_read_b128 v[6:9], v188 offset:33792
	ds_read_b128 v[10:13], v188 offset:34816
	ds_read_b128 v[14:17], v188 offset:35840
	ds_read_b128 v[18:21], v188 offset:49152
	ds_read_b128 v[22:25], v188 offset:50176
	ds_read_b128 v[26:29], v188 offset:51200
	ds_read_b128 v[30:33], v188 offset:52224
	s_add_u32 s62, s84, 0x10000
	s_addc_u32 s63, s85, 0
	s_mov_b32 m0, s87
	v_lshl_add_u64 v[228:229], s[62:63], 0, v[166:167]
	ds_read_b128 v[196:199], v189 offset:32768
	ds_read_b128 v[200:203], v189 offset:33792
	ds_read_b128 v[204:207], v189 offset:34816
	ds_read_b128 v[208:211], v189 offset:35840
	ds_read_b128 v[212:215], v189 offset:36864
	ds_read_b128 v[216:219], v189 offset:37888
	ds_read_b128 v[220:223], v189 offset:38912
	ds_read_b128 v[224:227], v189 offset:39936
	global_load_lds_dwordx4 v[228:229], off
	v_lshl_add_u64 v[228:229], s[62:63], 0, v[168:169]
	s_mov_b32 m0, s88
	s_nop 0
	global_load_lds_dwordx4 v[228:229], off
	s_waitcnt vmcnt(8)
	s_waitcnt lgkmcnt(0)
	s_setprio 1
	s_barrier
	v_mfma_f32_16x16x128_f8f6f4 v[158:161], v[2:9], v[196:203], v[158:161]
	v_mfma_f32_16x16x128_f8f6f4 v[154:157], v[10:17], v[196:203], v[154:157]
	v_mfma_f32_16x16x128_f8f6f4 v[146:149], v[10:17], v[204:211], v[146:149]
	v_mfma_f32_16x16x128_f8f6f4 v[150:153], v[2:9], v[204:211], v[150:153]
	v_mfma_f32_16x16x128_f8f6f4 v[142:145], v[2:9], v[212:219], v[142:145]
	v_mfma_f32_16x16x128_f8f6f4 v[138:141], v[10:17], v[212:219], v[138:141]
	v_mfma_f32_16x16x128_f8f6f4 v[130:133], v[10:17], v[220:227], v[130:133]
	v_mfma_f32_16x16x128_f8f6f4 v[134:137], v[2:9], v[220:227], v[134:137]
	v_mfma_f32_16x16x128_f8f6f4 v[102:105], v[18:25], v[220:227], v[102:105]
	v_mfma_f32_16x16x128_f8f6f4 v[98:101], v[26:33], v[220:227], v[98:101]
	v_mfma_f32_16x16x128_f8f6f4 v[106:109], v[26:33], v[212:219], v[106:109]
	v_mfma_f32_16x16x128_f8f6f4 v[110:113], v[18:25], v[212:219], v[110:113]
	v_mfma_f32_16x16x128_f8f6f4 v[118:121], v[18:25], v[204:211], v[118:121]
	v_mfma_f32_16x16x128_f8f6f4 v[114:117], v[26:33], v[204:211], v[114:117]
	v_mfma_f32_16x16x128_f8f6f4 v[122:125], v[26:33], v[196:203], v[122:125]
	v_mfma_f32_16x16x128_f8f6f4 v[126:129], v[18:25], v[196:203], v[126:129]
	s_barrier
	s_setprio 0
	s_mov_b32 m0, s89
	v_lshl_add_u64 v[174:175], v[174:175], 0, s[40:41]
	s_add_u32 s62, s82, 0x10080
	ds_read_b128 v[196:199], v189 offset:49152
	ds_read_b128 v[200:203], v189 offset:50176
	ds_read_b128 v[204:207], v189 offset:51200
	ds_read_b128 v[208:211], v189 offset:52224
	ds_read_b128 v[212:215], v189 offset:53248
	ds_read_b128 v[216:219], v189 offset:54272
	ds_read_b128 v[220:223], v189 offset:55296
	ds_read_b128 v[224:227], v189 offset:56320
	global_load_lds_dwordx4 v[174:175], off
	v_lshl_add_u64 v[174:175], v[176:177], 0, s[40:41]
	s_mov_b32 m0, s90
	s_addc_u32 s63, s83, 0
	global_load_lds_dwordx4 v[174:175], off
	v_lshl_add_u64 v[174:175], s[62:63], 0, v[162:163]
	s_mov_b32 m0, s93
	s_nop 0
	global_load_lds_dwordx4 v[174:175], off
	v_lshl_add_u64 v[174:175], s[62:63], 0, v[164:165]
	s_mov_b32 m0, s95
	s_nop 0
	global_load_lds_dwordx4 v[174:175], off
	v_lshl_add_u64 v[174:175], v[182:183], 0, s[40:41]
	s_mov_b32 m0, s91
	s_nop 0
	global_load_lds_dwordx4 v[174:175], off
	v_lshl_add_u64 v[174:175], v[184:185], 0, s[40:41]
	s_mov_b32 m0, s92
	s_nop 0
	global_load_lds_dwordx4 v[174:175], off
	s_waitcnt vmcnt(8)
	s_waitcnt lgkmcnt(0)
	s_setprio 1
	s_barrier
	v_mfma_f32_16x16x128_f8f6f4 v[94:97], v[2:9], v[196:203], v[94:97]
	v_mfma_f32_16x16x128_f8f6f4 v[90:93], v[10:17], v[196:203], v[90:93]
	v_mfma_f32_16x16x128_f8f6f4 v[82:85], v[10:17], v[204:211], v[82:85]
	v_mfma_f32_16x16x128_f8f6f4 v[86:89], v[2:9], v[204:211], v[86:89]
	v_mfma_f32_16x16x128_f8f6f4 v[78:81], v[2:9], v[212:219], v[78:81]
	v_mfma_f32_16x16x128_f8f6f4 v[74:77], v[10:17], v[212:219], v[74:77]
	v_mfma_f32_16x16x128_f8f6f4 v[66:69], v[10:17], v[220:227], v[66:69]
	v_mfma_f32_16x16x128_f8f6f4 v[70:73], v[2:9], v[220:227], v[70:73]
	v_mfma_f32_16x16x128_f8f6f4 v[38:41], v[18:25], v[220:227], v[38:41]
	v_mfma_f32_16x16x128_f8f6f4 v[34:37], v[26:33], v[220:227], v[34:37]
	v_mfma_f32_16x16x128_f8f6f4 v[42:45], v[26:33], v[212:219], v[42:45]
	v_mfma_f32_16x16x128_f8f6f4 v[46:49], v[18:25], v[212:219], v[46:49]
	v_mfma_f32_16x16x128_f8f6f4 v[54:57], v[18:25], v[204:211], v[54:57]
	v_mfma_f32_16x16x128_f8f6f4 v[50:53], v[26:33], v[204:211], v[50:53]
	v_mfma_f32_16x16x128_f8f6f4 v[58:61], v[26:33], v[196:203], v[58:61]
	v_mfma_f32_16x16x128_f8f6f4 v[62:65], v[18:25], v[196:203], v[62:65]
	s_barrier
	s_setprio 0
	s_andn2_b64 vcc, exec, s[42:43]
	s_cbranch_vccnz .LBB0_618
	s_barrier

.LBB0_630:
	s_ashr_i32 s54, s48, 1
	s_ashr_i32 s51, s50, 31
	s_ashr_i32 s55, s54, 31
	s_lshl_b64 s[52:53], s[50:51], 19
	s_lshl_b64 s[54:55], s[54:55], 9
	s_waitcnt vmcnt(0)
	ds_read_b128 v[18:21], v181
	ds_read_b128 v[22:25], v181 offset:1024
	ds_read_b128 v[26:29], v181 offset:2048
	ds_read_b128 v[30:33], v181 offset:3072
	ds_read_b128 v[2:5], v181 offset:16384
	ds_read_b128 v[6:9], v181 offset:17408
	ds_read_b128 v[10:13], v181 offset:18432
	ds_read_b128 v[14:17], v181 offset:19456
	s_add_u32 s5, s26, s52
	s_addc_u32 s33, s27, s53
	s_add_u32 s52, s5, s54
	s_addc_u32 s53, s33, s55
	s_and_b64 s[54:55], s[2:3], exec
	s_cselect_b32 s81, s53, s75
	s_cselect_b32 s80, s52, s74
	s_ashr_i32 s49, s48, 31
	s_lshl_b64 s[54:55], s[48:49], 17
	v_readlane_b32 s5, v254, 9
	s_add_u32 s54, s5, s54
	v_readlane_b32 s5, v254, 10
	s_addc_u32 s55, s5, s55
	s_and_b64 s[62:63], s[2:3], exec
	s_cselect_b32 s79, s55, s77
	s_cselect_b32 s78, s54, s76
	s_add_u32 s62, s74, 0x40080
	s_addc_u32 s63, s75, 0
	s_add_i32 s33, s8, 0xc000
	v_lshl_add_u64 v[174:175], s[62:63], 0, v[166:167]
	s_mov_b32 m0, s33
	s_add_i32 s5, s8, 0xe000
	ds_read_b128 v[190:193], v187
	ds_read_b128 v[194:197], v187 offset:1024
	ds_read_b128 v[198:201], v187 offset:2048
	ds_read_b128 v[202:205], v187 offset:3072
	ds_read_b128 v[206:209], v187 offset:4096
	ds_read_b128 v[210:213], v187 offset:5120
	ds_read_b128 v[214:217], v187 offset:6144
	ds_read_b128 v[218:221], v187 offset:7168
	global_load_lds_dwordx4 v[174:175], off
	v_lshl_add_u64 v[174:175], s[62:63], 0, v[168:169]
	s_mov_b32 m0, s5
	s_nop 0
	global_load_lds_dwordx4 v[174:175], off
	s_waitcnt vmcnt(8)
	s_waitcnt lgkmcnt(0)
	s_setprio 1
	s_barrier
	v_mfma_f32_16x16x128_f8f6f4 v[158:161], v[18:25], v[190:197], 0
	v_mfma_f32_16x16x128_f8f6f4 v[154:157], v[26:33], v[190:197], 0
	v_mfma_f32_16x16x128_f8f6f4 v[146:149], v[26:33], v[198:205], 0
	v_mfma_f32_16x16x128_f8f6f4 v[150:153], v[18:25], v[198:205], 0
	v_mfma_f32_16x16x128_f8f6f4 v[142:145], v[18:25], v[206:213], 0
	v_mfma_f32_16x16x128_f8f6f4 v[138:141], v[26:33], v[206:213], 0
	v_mfma_f32_16x16x128_f8f6f4 v[130:133], v[26:33], v[214:221], 0
	v_mfma_f32_16x16x128_f8f6f4 v[134:137], v[18:25], v[214:221], 0
	v_mfma_f32_16x16x128_f8f6f4 v[102:105], v[2:9], v[214:221], 0
	v_mfma_f32_16x16x128_f8f6f4 v[98:101], v[10:17], v[214:221], 0
	v_mfma_f32_16x16x128_f8f6f4 v[106:109], v[10:17], v[206:213], 0
	v_mfma_f32_16x16x128_f8f6f4 v[110:113], v[2:9], v[206:213], 0
	v_mfma_f32_16x16x128_f8f6f4 v[118:121], v[2:9], v[198:205], 0
	v_mfma_f32_16x16x128_f8f6f4 v[114:117], v[10:17], v[198:205], 0
	v_mfma_f32_16x16x128_f8f6f4 v[122:125], v[10:17], v[190:197], 0
	v_mfma_f32_16x16x128_f8f6f4 v[126:129], v[2:9], v[190:197], 0
	s_barrier
	s_setprio 0
	v_lshl_add_u64 v[174:175], s[76:77], 0, v[162:163]
	s_mov_b32 m0, s9
	v_lshl_add_u64 v[176:177], v[174:175], 0, s[44:45]
	ds_read_b128 v[190:193], v187 offset:16384
	ds_read_b128 v[194:197], v187 offset:17408
	ds_read_b128 v[198:201], v187 offset:18432
	ds_read_b128 v[202:205], v187 offset:19456
	ds_read_b128 v[206:209], v187 offset:20480
	ds_read_b128 v[210:213], v187 offset:21504
	ds_read_b128 v[214:217], v187 offset:22528
	ds_read_b128 v[218:221], v187 offset:23552
	global_load_lds_dwordx4 v[176:177], off
	v_lshl_add_u64 v[176:177], s[76:77], 0, v[164:165]
	s_add_u32 s62, s76, 0x10100
	v_lshl_add_u64 v[182:183], v[176:177], 0, s[44:45]
	s_mov_b32 m0, s61
	s_addc_u32 s63, s77, 0
	global_load_lds_dwordx4 v[182:183], off
	v_lshl_add_u64 v[182:183], s[62:63], 0, v[162:163]
	s_mov_b32 m0, s68
	s_nop 0
	global_load_lds_dwordx4 v[182:183], off
	v_lshl_add_u64 v[182:183], s[62:63], 0, v[164:165]
	s_mov_b32 m0, s69
	s_nop 0
	global_load_lds_dwordx4 v[182:183], off
	v_lshl_add_u64 v[182:183], s[74:75], 0, v[166:167]
	v_lshl_add_u64 v[184:185], v[182:183], 0, s[44:45]
	s_mov_b32 m0, s8
	s_nop 0
	global_load_lds_dwordx4 v[184:185], off
	v_lshl_add_u64 v[184:185], s[74:75], 0, v[168:169]
	v_lshl_add_u64 v[222:223], v[184:185], 0, s[44:45]
	s_mov_b32 m0, s71
	s_nop 0
	global_load_lds_dwordx4 v[222:223], off
	s_waitcnt vmcnt(8)
	s_waitcnt lgkmcnt(0)
	s_setprio 1
	s_barrier
	v_mfma_f32_16x16x128_f8f6f4 v[94:97], v[18:25], v[190:197], 0
	v_mfma_f32_16x16x128_f8f6f4 v[90:93], v[26:33], v[190:197], 0
	v_mfma_f32_16x16x128_f8f6f4 v[82:85], v[26:33], v[198:205], 0
	v_mfma_f32_16x16x128_f8f6f4 v[86:89], v[18:25], v[198:205], 0
	v_mfma_f32_16x16x128_f8f6f4 v[78:81], v[18:25], v[206:213], 0
	v_mfma_f32_16x16x128_f8f6f4 v[74:77], v[26:33], v[206:213], 0
	v_mfma_f32_16x16x128_f8f6f4 v[66:69], v[26:33], v[214:221], 0
	v_mfma_f32_16x16x128_f8f6f4 v[70:73], v[18:25], v[214:221], 0
	v_mfma_f32_16x16x128_f8f6f4 v[38:41], v[2:9], v[214:221], 0
	v_mfma_f32_16x16x128_f8f6f4 v[34:37], v[10:17], v[214:221], 0
	v_mfma_f32_16x16x128_f8f6f4 v[42:45], v[10:17], v[206:213], 0
	v_mfma_f32_16x16x128_f8f6f4 v[46:49], v[2:9], v[206:213], 0
	v_mfma_f32_16x16x128_f8f6f4 v[54:57], v[2:9], v[198:205], 0
	v_mfma_f32_16x16x128_f8f6f4 v[50:53], v[10:17], v[198:205], 0
	v_mfma_f32_16x16x128_f8f6f4 v[58:61], v[10:17], v[190:197], 0
	v_mfma_f32_16x16x128_f8f6f4 v[62:65], v[2:9], v[190:197], 0
	s_barrier
	s_setprio 0
	ds_read_b128 v[2:5], v181 offset:32768
	ds_read_b128 v[6:9], v181 offset:33792
	ds_read_b128 v[10:13], v181 offset:34816
	ds_read_b128 v[14:17], v181 offset:35840
	ds_read_b128 v[18:21], v181 offset:49152
	ds_read_b128 v[22:25], v181 offset:50176
	ds_read_b128 v[26:29], v181 offset:51200
	ds_read_b128 v[30:33], v181 offset:52224
	s_add_u32 s62, s74, 0x40100
	s_addc_u32 s63, s75, 0
	s_mov_b32 m0, s73
	v_lshl_add_u64 v[222:223], s[62:63], 0, v[166:167]
	ds_read_b128 v[190:193], v187 offset:32768
	ds_read_b128 v[194:197], v187 offset:33792
	ds_read_b128 v[198:201], v187 offset:34816
	ds_read_b128 v[202:205], v187 offset:35840
	ds_read_b128 v[206:209], v187 offset:36864
	ds_read_b128 v[210:213], v187 offset:37888
	ds_read_b128 v[214:217], v187 offset:38912
	ds_read_b128 v[218:221], v187 offset:39936
	global_load_lds_dwordx4 v[222:223], off
	v_lshl_add_u64 v[222:223], s[62:63], 0, v[168:169]
	s_mov_b32 m0, s82
	s_nop 0
	global_load_lds_dwordx4 v[222:223], off
	s_waitcnt vmcnt(8)
	s_waitcnt lgkmcnt(0)
	s_setprio 1
	s_barrier
	v_mfma_f32_16x16x128_f8f6f4 v[158:161], v[2:9], v[190:197], v[158:161]
	v_mfma_f32_16x16x128_f8f6f4 v[154:157], v[10:17], v[190:197], v[154:157]
	v_mfma_f32_16x16x128_f8f6f4 v[146:149], v[10:17], v[198:205], v[146:149]
	v_mfma_f32_16x16x128_f8f6f4 v[150:153], v[2:9], v[198:205], v[150:153]
	v_mfma_f32_16x16x128_f8f6f4 v[142:145], v[2:9], v[206:213], v[142:145]
	v_mfma_f32_16x16x128_f8f6f4 v[138:141], v[10:17], v[206:213], v[138:141]
	v_mfma_f32_16x16x128_f8f6f4 v[130:133], v[10:17], v[214:221], v[130:133]
	v_mfma_f32_16x16x128_f8f6f4 v[134:137], v[2:9], v[214:221], v[134:137]
	v_mfma_f32_16x16x128_f8f6f4 v[102:105], v[18:25], v[214:221], v[102:105]
	v_mfma_f32_16x16x128_f8f6f4 v[98:101], v[26:33], v[214:221], v[98:101]
	v_mfma_f32_16x16x128_f8f6f4 v[106:109], v[26:33], v[206:213], v[106:109]
	v_mfma_f32_16x16x128_f8f6f4 v[110:113], v[18:25], v[206:213], v[110:113]
	v_mfma_f32_16x16x128_f8f6f4 v[118:121], v[18:25], v[198:205], v[118:121]
	v_mfma_f32_16x16x128_f8f6f4 v[114:117], v[26:33], v[198:205], v[114:117]
	v_mfma_f32_16x16x128_f8f6f4 v[122:125], v[26:33], v[190:197], v[122:125]
	v_mfma_f32_16x16x128_f8f6f4 v[126:129], v[18:25], v[190:197], v[126:129]
	s_barrier
	s_setprio 0
	s_mov_b32 m0, s83
	v_lshl_add_u64 v[174:175], v[174:175], 0, s[46:47]
	s_add_u32 s62, s76, 0x10180
	ds_read_b128 v[190:193], v187 offset:49152
	ds_read_b128 v[194:197], v187 offset:50176
	ds_read_b128 v[198:201], v187 offset:51200
	ds_read_b128 v[202:205], v187 offset:52224
	ds_read_b128 v[206:209], v187 offset:53248
	ds_read_b128 v[210:213], v187 offset:54272
	ds_read_b128 v[214:217], v187 offset:55296
	ds_read_b128 v[218:221], v187 offset:56320
	global_load_lds_dwordx4 v[174:175], off
	v_lshl_add_u64 v[174:175], v[176:177], 0, s[46:47]
	s_mov_b32 m0, s84
	s_addc_u32 s63, s77, 0
	global_load_lds_dwordx4 v[174:175], off
	v_lshl_add_u64 v[174:175], s[62:63], 0, v[162:163]
	s_mov_b32 m0, s87
	s_nop 0
	global_load_lds_dwordx4 v[174:175], off
	v_lshl_add_u64 v[174:175], s[62:63], 0, v[164:165]
	s_mov_b32 m0, s88
	s_nop 0
	global_load_lds_dwordx4 v[174:175], off
	v_lshl_add_u64 v[174:175], v[182:183], 0, s[46:47]
	s_mov_b32 m0, s85
	s_nop 0
	global_load_lds_dwordx4 v[174:175], off
	v_lshl_add_u64 v[174:175], v[184:185], 0, s[46:47]
	s_mov_b32 m0, s86
	s_nop 0
	global_load_lds_dwordx4 v[174:175], off
	s_waitcnt vmcnt(8)
	s_waitcnt lgkmcnt(0)
	s_setprio 1
	s_barrier
	v_mfma_f32_16x16x128_f8f6f4 v[94:97], v[2:9], v[190:197], v[94:97]
	v_mfma_f32_16x16x128_f8f6f4 v[90:93], v[10:17], v[190:197], v[90:93]
	v_mfma_f32_16x16x128_f8f6f4 v[82:85], v[10:17], v[198:205], v[82:85]
	v_mfma_f32_16x16x128_f8f6f4 v[86:89], v[2:9], v[198:205], v[86:89]
	v_mfma_f32_16x16x128_f8f6f4 v[78:81], v[2:9], v[206:213], v[78:81]
	v_mfma_f32_16x16x128_f8f6f4 v[74:77], v[10:17], v[206:213], v[74:77]
	v_mfma_f32_16x16x128_f8f6f4 v[66:69], v[10:17], v[214:221], v[66:69]
	v_mfma_f32_16x16x128_f8f6f4 v[70:73], v[2:9], v[214:221], v[70:73]
	v_mfma_f32_16x16x128_f8f6f4 v[38:41], v[18:25], v[214:221], v[38:41]
	v_mfma_f32_16x16x128_f8f6f4 v[34:37], v[26:33], v[214:221], v[34:37]
	v_mfma_f32_16x16x128_f8f6f4 v[42:45], v[26:33], v[206:213], v[42:45]
	v_mfma_f32_16x16x128_f8f6f4 v[46:49], v[18:25], v[206:213], v[46:49]
	v_mfma_f32_16x16x128_f8f6f4 v[54:57], v[18:25], v[198:205], v[54:57]
	v_mfma_f32_16x16x128_f8f6f4 v[50:53], v[26:33], v[198:205], v[50:53]
	v_mfma_f32_16x16x128_f8f6f4 v[58:61], v[26:33], v[190:197], v[58:61]
	v_mfma_f32_16x16x128_f8f6f4 v[62:65], v[18:25], v[190:197], v[62:65]
	s_barrier
	s_setprio 0
	ds_read_b128 v[2:5], v181
	ds_read_b128 v[6:9], v181 offset:1024
	ds_read_b128 v[10:13], v181 offset:2048
	ds_read_b128 v[14:17], v181 offset:3072
	ds_read_b128 v[18:21], v181 offset:16384
	ds_read_b128 v[22:25], v181 offset:17408
	ds_read_b128 v[26:29], v181 offset:18432
	ds_read_b128 v[30:33], v181 offset:19456
	s_add_u32 s62, s74, 0x40180
	s_addc_u32 s63, s75, 0
	s_mov_b32 m0, s33
	v_lshl_add_u64 v[174:175], s[62:63], 0, v[166:167]
	ds_read_b128 v[190:193], v187
	ds_read_b128 v[194:197], v187 offset:1024
	ds_read_b128 v[198:201], v187 offset:2048
	ds_read_b128 v[202:205], v187 offset:3072
	ds_read_b128 v[206:209], v187 offset:4096
	ds_read_b128 v[210:213], v187 offset:5120
	ds_read_b128 v[214:217], v187 offset:6144
	ds_read_b128 v[218:221], v187 offset:7168
	global_load_lds_dwordx4 v[174:175], off
	v_lshl_add_u64 v[174:175], s[62:63], 0, v[168:169]
	s_mov_b32 m0, s5
	s_nop 0
	global_load_lds_dwordx4 v[174:175], off
	s_waitcnt vmcnt(8)
	s_waitcnt lgkmcnt(0)
	s_setprio 1
	s_barrier
	v_mfma_f32_16x16x128_f8f6f4 v[158:161], v[2:9], v[190:197], v[158:161]
	v_mfma_f32_16x16x128_f8f6f4 v[154:157], v[10:17], v[190:197], v[154:157]
	v_mfma_f32_16x16x128_f8f6f4 v[146:149], v[10:17], v[198:205], v[146:149]
	v_mfma_f32_16x16x128_f8f6f4 v[150:153], v[2:9], v[198:205], v[150:153]
	v_mfma_f32_16x16x128_f8f6f4 v[142:145], v[2:9], v[206:213], v[142:145]
	v_mfma_f32_16x16x128_f8f6f4 v[138:141], v[10:17], v[206:213], v[138:141]
	v_mfma_f32_16x16x128_f8f6f4 v[130:133], v[10:17], v[214:221], v[130:133]
	v_mfma_f32_16x16x128_f8f6f4 v[134:137], v[2:9], v[214:221], v[134:137]
	v_mfma_f32_16x16x128_f8f6f4 v[102:105], v[18:25], v[214:221], v[102:105]
	v_mfma_f32_16x16x128_f8f6f4 v[98:101], v[26:33], v[214:221], v[98:101]
	v_mfma_f32_16x16x128_f8f6f4 v[106:109], v[26:33], v[206:213], v[106:109]
	v_mfma_f32_16x16x128_f8f6f4 v[110:113], v[18:25], v[206:213], v[110:113]
	v_mfma_f32_16x16x128_f8f6f4 v[118:121], v[18:25], v[198:205], v[118:121]
	v_mfma_f32_16x16x128_f8f6f4 v[114:117], v[26:33], v[198:205], v[114:117]
	v_mfma_f32_16x16x128_f8f6f4 v[122:125], v[26:33], v[190:197], v[122:125]
	v_mfma_f32_16x16x128_f8f6f4 v[126:129], v[18:25], v[190:197], v[126:129]
	s_barrier
	s_setprio 0
	s_mov_b32 m0, s9
	v_lshl_add_u64 v[174:175], s[78:79], 0, v[162:163]
	s_add_u32 s62, s78, 0x10000
	ds_read_b128 v[190:193], v187 offset:16384
	ds_read_b128 v[194:197], v187 offset:17408
	ds_read_b128 v[198:201], v187 offset:18432
	ds_read_b128 v[202:205], v187 offset:19456
	ds_read_b128 v[206:209], v187 offset:20480
	ds_read_b128 v[210:213], v187 offset:21504
	ds_read_b128 v[214:217], v187 offset:22528
	ds_read_b128 v[218:221], v187 offset:23552
	global_load_lds_dwordx4 v[174:175], off
	v_lshl_add_u64 v[176:177], s[78:79], 0, v[164:165]
	s_mov_b32 m0, s61
	s_addc_u32 s63, s79, 0
	global_load_lds_dwordx4 v[176:177], off
	v_lshl_add_u64 v[182:183], s[62:63], 0, v[162:163]
	s_mov_b32 m0, s68
	v_lshl_add_u64 v[184:185], s[80:81], 0, v[168:169]
	global_load_lds_dwordx4 v[182:183], off
	v_lshl_add_u64 v[182:183], s[62:63], 0, v[164:165]
	s_mov_b32 m0, s69
	s_nop 0
	global_load_lds_dwordx4 v[182:183], off
	v_lshl_add_u64 v[182:183], s[80:81], 0, v[166:167]
	s_mov_b32 m0, s8
	s_nop 0
	global_load_lds_dwordx4 v[182:183], off
	s_mov_b32 m0, s71
	s_nop 0
	global_load_lds_dwordx4 v[184:185], off
	s_waitcnt vmcnt(8)
	s_waitcnt lgkmcnt(0)
	s_setprio 1
	s_barrier
	v_mfma_f32_16x16x128_f8f6f4 v[94:97], v[2:9], v[190:197], v[94:97]
	v_mfma_f32_16x16x128_f8f6f4 v[90:93], v[10:17], v[190:197], v[90:93]
	v_mfma_f32_16x16x128_f8f6f4 v[82:85], v[10:17], v[198:205], v[82:85]
	v_mfma_f32_16x16x128_f8f6f4 v[86:89], v[2:9], v[198:205], v[86:89]
	v_mfma_f32_16x16x128_f8f6f4 v[78:81], v[2:9], v[206:213], v[78:81]
	v_mfma_f32_16x16x128_f8f6f4 v[74:77], v[10:17], v[206:213], v[74:77]
	v_mfma_f32_16x16x128_f8f6f4 v[66:69], v[10:17], v[214:221], v[66:69]
	v_mfma_f32_16x16x128_f8f6f4 v[70:73], v[2:9], v[214:221], v[70:73]
	v_mfma_f32_16x16x128_f8f6f4 v[38:41], v[18:25], v[214:221], v[38:41]
	v_mfma_f32_16x16x128_f8f6f4 v[34:37], v[26:33], v[214:221], v[34:37]
	v_mfma_f32_16x16x128_f8f6f4 v[42:45], v[26:33], v[206:213], v[42:45]
	v_mfma_f32_16x16x128_f8f6f4 v[46:49], v[18:25], v[206:213], v[46:49]
	v_mfma_f32_16x16x128_f8f6f4 v[54:57], v[18:25], v[198:205], v[54:57]
	v_mfma_f32_16x16x128_f8f6f4 v[50:53], v[26:33], v[198:205], v[50:53]
	v_mfma_f32_16x16x128_f8f6f4 v[58:61], v[26:33], v[190:197], v[58:61]
	v_mfma_f32_16x16x128_f8f6f4 v[62:65], v[18:25], v[190:197], v[62:65]
	s_barrier
	s_setprio 0
	ds_read_b128 v[2:5], v181 offset:32768
	ds_read_b128 v[6:9], v181 offset:33792
	ds_read_b128 v[10:13], v181 offset:34816
	ds_read_b128 v[14:17], v181 offset:35840
	ds_read_b128 v[18:21], v181 offset:49152
	ds_read_b128 v[22:25], v181 offset:50176
	ds_read_b128 v[26:29], v181 offset:51200
	ds_read_b128 v[30:33], v181 offset:52224
	s_add_u32 s62, s80, 0x40000
	s_addc_u32 s63, s81, 0
	s_mov_b32 m0, s73
	v_lshl_add_u64 v[222:223], s[62:63], 0, v[166:167]
	ds_read_b128 v[190:193], v187 offset:32768
	ds_read_b128 v[194:197], v187 offset:33792
	ds_read_b128 v[198:201], v187 offset:34816
	ds_read_b128 v[202:205], v187 offset:35840
	ds_read_b128 v[206:209], v187 offset:36864
	ds_read_b128 v[210:213], v187 offset:37888
	ds_read_b128 v[214:217], v187 offset:38912
	ds_read_b128 v[218:221], v187 offset:39936
	global_load_lds_dwordx4 v[222:223], off
	v_lshl_add_u64 v[222:223], s[62:63], 0, v[168:169]
	s_mov_b32 m0, s82
	s_nop 0
	global_load_lds_dwordx4 v[222:223], off
	s_waitcnt vmcnt(8)
	s_waitcnt lgkmcnt(0)
	s_setprio 1
	s_barrier
	v_mfma_f32_16x16x128_f8f6f4 v[158:161], v[2:9], v[190:197], v[158:161]
	v_mfma_f32_16x16x128_f8f6f4 v[154:157], v[10:17], v[190:197], v[154:157]
	v_mfma_f32_16x16x128_f8f6f4 v[146:149], v[10:17], v[198:205], v[146:149]
	v_mfma_f32_16x16x128_f8f6f4 v[150:153], v[2:9], v[198:205], v[150:153]
	v_mfma_f32_16x16x128_f8f6f4 v[142:145], v[2:9], v[206:213], v[142:145]
	v_mfma_f32_16x16x128_f8f6f4 v[138:141], v[10:17], v[206:213], v[138:141]
	v_mfma_f32_16x16x128_f8f6f4 v[130:133], v[10:17], v[214:221], v[130:133]
	v_mfma_f32_16x16x128_f8f6f4 v[134:137], v[2:9], v[214:221], v[134:137]
	v_mfma_f32_16x16x128_f8f6f4 v[102:105], v[18:25], v[214:221], v[102:105]
	v_mfma_f32_16x16x128_f8f6f4 v[98:101], v[26:33], v[214:221], v[98:101]
	v_mfma_f32_16x16x128_f8f6f4 v[106:109], v[26:33], v[206:213], v[106:109]
	v_mfma_f32_16x16x128_f8f6f4 v[110:113], v[18:25], v[206:213], v[110:113]
	v_mfma_f32_16x16x128_f8f6f4 v[118:121], v[18:25], v[198:205], v[118:121]
	v_mfma_f32_16x16x128_f8f6f4 v[114:117], v[26:33], v[198:205], v[114:117]
	v_mfma_f32_16x16x128_f8f6f4 v[122:125], v[26:33], v[190:197], v[122:125]
	v_mfma_f32_16x16x128_f8f6f4 v[126:129], v[18:25], v[190:197], v[126:129]
	s_barrier
	s_setprio 0
	s_mov_b32 m0, s83
	v_lshl_add_u64 v[174:175], v[174:175], 0, s[38:39]
	s_add_u32 s62, s78, 0x10080
	ds_read_b128 v[190:193], v187 offset:49152
	ds_read_b128 v[194:197], v187 offset:50176
	ds_read_b128 v[198:201], v187 offset:51200
	ds_read_b128 v[202:205], v187 offset:52224
	ds_read_b128 v[206:209], v187 offset:53248
	ds_read_b128 v[210:213], v187 offset:54272
	ds_read_b128 v[214:217], v187 offset:55296
	ds_read_b128 v[218:221], v187 offset:56320
	global_load_lds_dwordx4 v[174:175], off
	v_lshl_add_u64 v[174:175], v[176:177], 0, s[38:39]
	s_mov_b32 m0, s84
	s_addc_u32 s63, s79, 0
	global_load_lds_dwordx4 v[174:175], off
	v_lshl_add_u64 v[174:175], s[62:63], 0, v[162:163]
	s_mov_b32 m0, s87
	s_nop 0
	global_load_lds_dwordx4 v[174:175], off
	v_lshl_add_u64 v[174:175], s[62:63], 0, v[164:165]
	s_mov_b32 m0, s88
	s_nop 0
	global_load_lds_dwordx4 v[174:175], off
	v_lshl_add_u64 v[174:175], v[182:183], 0, s[38:39]
	s_mov_b32 m0, s85
	s_nop 0
	global_load_lds_dwordx4 v[174:175], off
	v_lshl_add_u64 v[174:175], v[184:185], 0, s[38:39]
	s_mov_b32 m0, s86
	s_nop 0
	global_load_lds_dwordx4 v[174:175], off
	s_waitcnt vmcnt(8)
	s_waitcnt lgkmcnt(0)
	s_setprio 1
	s_barrier
	v_mfma_f32_16x16x128_f8f6f4 v[94:97], v[2:9], v[190:197], v[94:97]
	v_mfma_f32_16x16x128_f8f6f4 v[90:93], v[10:17], v[190:197], v[90:93]
	v_mfma_f32_16x16x128_f8f6f4 v[82:85], v[10:17], v[198:205], v[82:85]
	v_mfma_f32_16x16x128_f8f6f4 v[86:89], v[2:9], v[198:205], v[86:89]
	v_mfma_f32_16x16x128_f8f6f4 v[78:81], v[2:9], v[206:213], v[78:81]
	v_mfma_f32_16x16x128_f8f6f4 v[74:77], v[10:17], v[206:213], v[74:77]
	v_mfma_f32_16x16x128_f8f6f4 v[66:69], v[10:17], v[214:221], v[66:69]
	v_mfma_f32_16x16x128_f8f6f4 v[70:73], v[2:9], v[214:221], v[70:73]
	v_mfma_f32_16x16x128_f8f6f4 v[38:41], v[18:25], v[214:221], v[38:41]
	v_mfma_f32_16x16x128_f8f6f4 v[34:37], v[26:33], v[214:221], v[34:37]
	v_mfma_f32_16x16x128_f8f6f4 v[42:45], v[26:33], v[206:213], v[42:45]
	v_mfma_f32_16x16x128_f8f6f4 v[46:49], v[18:25], v[206:213], v[46:49]
	v_mfma_f32_16x16x128_f8f6f4 v[54:57], v[18:25], v[198:205], v[54:57]
	v_mfma_f32_16x16x128_f8f6f4 v[50:53], v[26:33], v[198:205], v[50:53]
	v_mfma_f32_16x16x128_f8f6f4 v[58:61], v[26:33], v[190:197], v[58:61]
	v_mfma_f32_16x16x128_f8f6f4 v[62:65], v[18:25], v[190:197], v[62:65]
	s_barrier
	s_setprio 0
	s_andn2_b64 vcc, exec, s[40:41]
	s_cbranch_vccnz .LBB0_632
	s_barrier

.LBB0_791:
	ds_read_b128 v[2:5], v189
	ds_read_b128 v[6:9], v189 offset:1024
	ds_read_b128 v[192:195], v189 offset:2048
	ds_read_b128 v[196:199], v189 offset:3072
	ds_read_b128 v[200:203], v189 offset:16384
	ds_read_b128 v[204:207], v189 offset:17408
	ds_read_b128 v[208:211], v189 offset:18432
	ds_read_b128 v[212:215], v189 offset:19456
	s_add_u32 s37, s46, 0x100
	s_addc_u32 s39, s47, 0
	s_and_b64 s[50:51], s[48:49], exec
	s_cselect_b32 s51, s1, s39
	s_cselect_b32 s50, s0, s37
	s_add_u32 s37, s44, 0x100
	s_addc_u32 s39, s45, 0
	s_and_b64 s[48:49], s[48:49], exec
	s_cselect_b32 s49, s5, s39
	s_cselect_b32 s48, s4, s37
	s_add_u32 s88, s46, 0x80080
	s_addc_u32 s89, s47, 0
	s_add_i32 s37, s8, 0xc000
	v_lshl_add_u64 v[174:175], s[88:89], 0, v[154:155]
	s_mov_b32 m0, s37
	s_add_i32 s39, s8, 0xe000
	ds_read_b128 v[216:219], v190
	ds_read_b128 v[220:223], v190 offset:1024
	ds_read_b128 v[224:227], v190 offset:2048
	ds_read_b128 v[228:231], v190 offset:3072
	ds_read_b128 v[242:245], v190 offset:4096
	ds_read_b128 v[246:249], v190 offset:5120
	ds_read_b128 v[232:235], v190 offset:6144
	ds_read_b128 v[236:239], v190 offset:7168
	global_load_lds_dwordx4 v[174:175], off
	v_lshl_add_u64 v[174:175], s[88:89], 0, v[158:159]
	s_mov_b32 m0, s39
	s_nop 0
	global_load_lds_dwordx4 v[174:175], off
	s_waitcnt vmcnt(8)
	s_waitcnt lgkmcnt(0)
	s_setprio 1
	s_barrier
	v_mfma_f32_16x16x128_f8f6f4 v[134:137], v[2:9], v[216:223], 0
	v_mfma_f32_16x16x128_f8f6f4 v[130:133], v[192:199], v[216:223], 0
	v_mfma_f32_16x16x128_f8f6f4 v[122:125], v[192:199], v[224:231], 0
	v_mfma_f32_16x16x128_f8f6f4 v[126:129], v[2:9], v[224:231], 0
	v_mfma_f32_16x16x128_f8f6f4 v[118:121], v[2:9], v[242:249], 0
	v_mfma_f32_16x16x128_f8f6f4 v[114:117], v[192:199], v[242:249], 0
	v_mfma_f32_16x16x128_f8f6f4 v[106:109], v[192:199], v[232:239], 0
	v_mfma_f32_16x16x128_f8f6f4 v[110:113], v[2:9], v[232:239], 0
	v_mfma_f32_16x16x128_f8f6f4 v[78:81], v[200:207], v[232:239], 0
	v_mfma_f32_16x16x128_f8f6f4 v[74:77], v[208:215], v[232:239], 0
	v_mfma_f32_16x16x128_f8f6f4 v[82:85], v[208:215], v[242:249], 0
	v_mfma_f32_16x16x128_f8f6f4 v[86:89], v[200:207], v[242:249], 0
	v_mfma_f32_16x16x128_f8f6f4 v[94:97], v[200:207], v[224:231], 0
	v_mfma_f32_16x16x128_f8f6f4 v[90:93], v[208:215], v[224:231], 0
	v_mfma_f32_16x16x128_f8f6f4 v[98:101], v[208:215], v[216:223], 0
	v_mfma_f32_16x16x128_f8f6f4 v[102:105], v[200:207], v[216:223], 0
	s_barrier
	s_setprio 0
	s_mov_b32 m0, s9
	v_lshl_add_u64 v[174:175], s[48:49], 0, v[156:157]
	s_add_u32 s88, s48, 0x80000
	ds_read_b128 v[216:219], v190 offset:16384
	ds_read_b128 v[220:223], v190 offset:17408
	ds_read_b128 v[224:227], v190 offset:18432
	ds_read_b128 v[228:231], v190 offset:19456
	ds_read_b128 v[232:235], v190 offset:20480
	ds_read_b128 v[236:239], v190 offset:21504
	ds_read_b128 v[242:245], v190 offset:22528
	ds_read_b128 v[246:249], v190 offset:23552
	global_load_lds_dwordx4 v[174:175], off
	v_lshl_add_u64 v[176:177], s[48:49], 0, v[160:161]
	s_mov_b32 m0, s27
	s_addc_u32 s89, s49, 0
	global_load_lds_dwordx4 v[176:177], off
	v_lshl_add_u64 v[182:183], s[88:89], 0, v[156:157]
	s_mov_b32 m0, s33
	v_lshl_add_u64 v[184:185], s[50:51], 0, v[158:159]
	global_load_lds_dwordx4 v[182:183], off
	v_lshl_add_u64 v[182:183], s[88:89], 0, v[160:161]
	s_mov_b32 m0, s35
	s_nop 0
	global_load_lds_dwordx4 v[182:183], off
	v_lshl_add_u64 v[182:183], s[50:51], 0, v[154:155]
	s_mov_b32 m0, s8
	s_nop 0
	global_load_lds_dwordx4 v[182:183], off
	s_mov_b32 m0, s43
	s_nop 0
	global_load_lds_dwordx4 v[184:185], off
	s_waitcnt vmcnt(8)
	s_waitcnt lgkmcnt(0)
	s_setprio 1
	s_barrier
	v_mfma_f32_16x16x128_f8f6f4 v[70:73], v[2:9], v[216:223], 0
	v_mfma_f32_16x16x128_f8f6f4 v[66:69], v[192:199], v[216:223], 0
	v_mfma_f32_16x16x128_f8f6f4 v[58:61], v[192:199], v[224:231], 0
	v_mfma_f32_16x16x128_f8f6f4 v[62:65], v[2:9], v[224:231], 0
	v_mfma_f32_16x16x128_f8f6f4 v[54:57], v[2:9], v[232:239], 0
	v_mfma_f32_16x16x128_f8f6f4 v[50:53], v[192:199], v[232:239], 0
	v_mfma_f32_16x16x128_f8f6f4 v[42:45], v[192:199], v[242:249], 0
	v_mfma_f32_16x16x128_f8f6f4 v[46:49], v[2:9], v[242:249], 0
	v_mfma_f32_16x16x128_f8f6f4 v[14:17], v[200:207], v[242:249], 0
	v_mfma_f32_16x16x128_f8f6f4 v[10:13], v[208:215], v[242:249], 0
	v_mfma_f32_16x16x128_f8f6f4 v[18:21], v[208:215], v[232:239], 0
	v_mfma_f32_16x16x128_f8f6f4 v[22:25], v[200:207], v[232:239], 0
	v_mfma_f32_16x16x128_f8f6f4 v[30:33], v[200:207], v[224:231], 0
	v_mfma_f32_16x16x128_f8f6f4 v[26:29], v[208:215], v[224:231], 0
	v_mfma_f32_16x16x128_f8f6f4 v[34:37], v[208:215], v[216:223], 0
	v_mfma_f32_16x16x128_f8f6f4 v[38:41], v[200:207], v[216:223], 0
	s_barrier
	s_setprio 0
	ds_read_b128 v[2:5], v189 offset:32768
	ds_read_b128 v[6:9], v189 offset:33792
	ds_read_b128 v[192:195], v189 offset:34816
	ds_read_b128 v[196:199], v189 offset:35840
	ds_read_b128 v[200:203], v189 offset:49152
	ds_read_b128 v[204:207], v189 offset:50176
	ds_read_b128 v[208:211], v189 offset:51200
	ds_read_b128 v[212:215], v189 offset:52224
	s_add_u32 s50, s50, 0x80000
	s_addc_u32 s51, s51, 0
	s_mov_b32 m0, s52
	v_lshl_add_u64 v[186:187], s[50:51], 0, v[154:155]
	ds_read_b128 v[216:219], v190 offset:32768
	ds_read_b128 v[220:223], v190 offset:33792
	ds_read_b128 v[224:227], v190 offset:34816
	ds_read_b128 v[228:231], v190 offset:35840
	ds_read_b128 v[232:235], v190 offset:36864
	ds_read_b128 v[236:239], v190 offset:37888
	ds_read_b128 v[242:245], v190 offset:38912
	ds_read_b128 v[246:249], v190 offset:39936
	global_load_lds_dwordx4 v[186:187], off
	v_lshl_add_u64 v[186:187], s[50:51], 0, v[158:159]
	s_mov_b32 m0, s53
	s_nop 0
	global_load_lds_dwordx4 v[186:187], off
	s_waitcnt vmcnt(8)
	s_waitcnt lgkmcnt(0)
	s_setprio 1
	s_barrier
	v_mfma_f32_16x16x128_f8f6f4 v[134:137], v[2:9], v[216:223], v[134:137]
	v_mfma_f32_16x16x128_f8f6f4 v[130:133], v[192:199], v[216:223], v[130:133]
	v_mfma_f32_16x16x128_f8f6f4 v[122:125], v[192:199], v[224:231], v[122:125]
	v_mfma_f32_16x16x128_f8f6f4 v[126:129], v[2:9], v[224:231], v[126:129]
	v_mfma_f32_16x16x128_f8f6f4 v[118:121], v[2:9], v[232:239], v[118:121]
	v_mfma_f32_16x16x128_f8f6f4 v[114:117], v[192:199], v[232:239], v[114:117]
	v_mfma_f32_16x16x128_f8f6f4 v[106:109], v[192:199], v[242:249], v[106:109]
	v_mfma_f32_16x16x128_f8f6f4 v[110:113], v[2:9], v[242:249], v[110:113]
	v_mfma_f32_16x16x128_f8f6f4 v[78:81], v[200:207], v[242:249], v[78:81]
	v_mfma_f32_16x16x128_f8f6f4 v[74:77], v[208:215], v[242:249], v[74:77]
	v_mfma_f32_16x16x128_f8f6f4 v[82:85], v[208:215], v[232:239], v[82:85]
	v_mfma_f32_16x16x128_f8f6f4 v[86:89], v[200:207], v[232:239], v[86:89]
	v_mfma_f32_16x16x128_f8f6f4 v[94:97], v[200:207], v[224:231], v[94:97]
	v_mfma_f32_16x16x128_f8f6f4 v[90:93], v[208:215], v[224:231], v[90:93]
	v_mfma_f32_16x16x128_f8f6f4 v[98:101], v[208:215], v[216:223], v[98:101]
	v_mfma_f32_16x16x128_f8f6f4 v[102:105], v[200:207], v[216:223], v[102:105]
	s_barrier
	s_setprio 0
	s_mov_b32 m0, s70
	v_lshl_add_u64 v[174:175], v[174:175], 0, s[18:19]
	s_add_u32 s48, s48, 0x80080
	ds_read_b128 v[216:219], v190 offset:49152
	ds_read_b128 v[220:223], v190 offset:50176
	ds_read_b128 v[224:227], v190 offset:51200
	ds_read_b128 v[228:231], v190 offset:52224
	ds_read_b128 v[232:235], v190 offset:53248
	ds_read_b128 v[236:239], v190 offset:54272
	ds_read_b128 v[242:245], v190 offset:55296
	ds_read_b128 v[246:249], v190 offset:56320
	global_load_lds_dwordx4 v[174:175], off
	v_lshl_add_u64 v[174:175], v[176:177], 0, s[18:19]
	s_mov_b32 m0, s71
	s_addc_u32 s49, s49, 0
	global_load_lds_dwordx4 v[174:175], off
	v_lshl_add_u64 v[174:175], s[48:49], 0, v[156:157]
	s_mov_b32 m0, s74
	s_nop 0
	global_load_lds_dwordx4 v[174:175], off
	v_lshl_add_u64 v[174:175], s[48:49], 0, v[160:161]
	s_mov_b32 m0, s75
	s_nop 0
	global_load_lds_dwordx4 v[174:175], off
	v_lshl_add_u64 v[174:175], v[182:183], 0, s[18:19]
	s_mov_b32 m0, s72
	s_nop 0
	global_load_lds_dwordx4 v[174:175], off
	v_lshl_add_u64 v[174:175], v[184:185], 0, s[18:19]
	s_mov_b32 m0, s73
	s_nop 0
	global_load_lds_dwordx4 v[174:175], off
	s_waitcnt vmcnt(8)
	s_waitcnt lgkmcnt(0)
	s_setprio 1
	s_barrier
	v_mfma_f32_16x16x128_f8f6f4 v[70:73], v[2:9], v[216:223], v[70:73]
	v_mfma_f32_16x16x128_f8f6f4 v[66:69], v[192:199], v[216:223], v[66:69]
	v_mfma_f32_16x16x128_f8f6f4 v[58:61], v[192:199], v[224:231], v[58:61]
	v_mfma_f32_16x16x128_f8f6f4 v[62:65], v[2:9], v[224:231], v[62:65]
	v_mfma_f32_16x16x128_f8f6f4 v[54:57], v[2:9], v[232:239], v[54:57]
	v_mfma_f32_16x16x128_f8f6f4 v[50:53], v[192:199], v[232:239], v[50:53]
	v_mfma_f32_16x16x128_f8f6f4 v[42:45], v[192:199], v[242:249], v[42:45]
	v_mfma_f32_16x16x128_f8f6f4 v[46:49], v[2:9], v[242:249], v[46:49]
	v_mfma_f32_16x16x128_f8f6f4 v[14:17], v[200:207], v[242:249], v[14:17]
	v_mfma_f32_16x16x128_f8f6f4 v[10:13], v[208:215], v[242:249], v[10:13]
	v_mfma_f32_16x16x128_f8f6f4 v[18:21], v[208:215], v[232:239], v[18:21]
	v_mfma_f32_16x16x128_f8f6f4 v[22:25], v[200:207], v[232:239], v[22:25]
	v_mfma_f32_16x16x128_f8f6f4 v[30:33], v[200:207], v[224:231], v[30:33]
	v_mfma_f32_16x16x128_f8f6f4 v[26:29], v[208:215], v[224:231], v[26:29]
	v_mfma_f32_16x16x128_f8f6f4 v[34:37], v[208:215], v[216:223], v[34:37]
	v_mfma_f32_16x16x128_f8f6f4 v[38:41], v[200:207], v[216:223], v[38:41]
	s_barrier
	s_setprio 0
	s_cmp_lt_u32 s86, 3
	s_cbranch_scc1 .LBB0_796
	s_add_u32 s48, s55, s62
	s_addc_u32 s49, s61, s41
	s_add_u32 s46, s46, 0x80180
	s_addc_u32 s47, s47, 0
	s_add_u32 s41, s44, 0x200
	v_lshl_add_u64 v[174:175], v[172:173], 2, s[48:49]
	s_addc_u32 s50, s45, 0
	s_mov_b32 s51, 4
	s_cmp_eq_u32 s86, s51
	s_cselect_b64 s[44:45], -1, 0
	s_cmp_lg_u32 s86, s51
	s_cbranch_scc1 .LBB0_794

.LBB0_794:
	ds_read_b128 v[2:5], v189
	ds_read_b128 v[6:9], v189 offset:1024
	ds_read_b128 v[192:195], v189 offset:2048
	ds_read_b128 v[196:199], v189 offset:3072
	ds_read_b128 v[200:203], v189 offset:16384
	ds_read_b128 v[204:207], v189 offset:17408
	ds_read_b128 v[208:211], v189 offset:18432
	ds_read_b128 v[212:215], v189 offset:19456
	s_add_u32 s48, s46, 0xfff80080
	s_addc_u32 s49, s47, -1
	s_and_b64 s[44:45], s[44:45], exec
	s_cselect_b32 s44, s4, s41
	s_cselect_b32 s49, s1, s49
	s_cselect_b32 s48, s0, s48
	s_cselect_b32 s45, s5, s50
	s_mov_b32 m0, s37
	v_lshl_add_u64 v[176:177], s[46:47], 0, v[162:163]
	ds_read_b128 v[216:219], v190
	ds_read_b128 v[220:223], v190 offset:1024
	ds_read_b128 v[224:227], v190 offset:2048
	ds_read_b128 v[228:231], v190 offset:3072
	ds_read_b128 v[232:235], v190 offset:4096
	ds_read_b128 v[236:239], v190 offset:5120
	ds_read_b128 v[242:245], v190 offset:6144
	ds_read_b128 v[246:249], v190 offset:7168
	global_load_lds_dwordx4 v[176:177], off
	v_lshl_add_u64 v[176:177], s[46:47], 0, v[164:165]
	s_mov_b32 m0, s39
	s_nop 0
	global_load_lds_dwordx4 v[176:177], off
	s_waitcnt vmcnt(8)
	s_waitcnt lgkmcnt(0)
	s_setprio 1
	s_barrier
	v_mfma_f32_16x16x128_f8f6f4 v[134:137], v[2:9], v[216:223], v[134:137]
	v_mfma_f32_16x16x128_f8f6f4 v[130:133], v[192:199], v[216:223], v[130:133]
	v_mfma_f32_16x16x128_f8f6f4 v[122:125], v[192:199], v[224:231], v[122:125]
	v_mfma_f32_16x16x128_f8f6f4 v[126:129], v[2:9], v[224:231], v[126:129]
	v_mfma_f32_16x16x128_f8f6f4 v[118:121], v[2:9], v[232:239], v[118:121]
	v_mfma_f32_16x16x128_f8f6f4 v[114:117], v[192:199], v[232:239], v[114:117]
	v_mfma_f32_16x16x128_f8f6f4 v[106:109], v[192:199], v[242:249], v[106:109]
	v_mfma_f32_16x16x128_f8f6f4 v[110:113], v[2:9], v[242:249], v[110:113]
	v_mfma_f32_16x16x128_f8f6f4 v[78:81], v[200:207], v[242:249], v[78:81]
	v_mfma_f32_16x16x128_f8f6f4 v[74:77], v[208:215], v[242:249], v[74:77]
	v_mfma_f32_16x16x128_f8f6f4 v[82:85], v[208:215], v[232:239], v[82:85]
	v_mfma_f32_16x16x128_f8f6f4 v[86:89], v[200:207], v[232:239], v[86:89]
	v_mfma_f32_16x16x128_f8f6f4 v[94:97], v[200:207], v[224:231], v[94:97]
	v_mfma_f32_16x16x128_f8f6f4 v[90:93], v[208:215], v[224:231], v[90:93]
	v_mfma_f32_16x16x128_f8f6f4 v[98:101], v[208:215], v[216:223], v[98:101]
	v_mfma_f32_16x16x128_f8f6f4 v[102:105], v[200:207], v[216:223], v[102:105]
	s_barrier
	s_setprio 0
	s_mov_b32 m0, s9
	v_lshl_add_u64 v[176:177], s[44:45], 0, v[156:157]
	s_add_u32 s62, s44, 0x80000
	ds_read_b128 v[216:219], v190 offset:16384
	ds_read_b128 v[220:223], v190 offset:17408
	ds_read_b128 v[224:227], v190 offset:18432
	ds_read_b128 v[228:231], v190 offset:19456
	ds_read_b128 v[232:235], v190 offset:20480
	ds_read_b128 v[236:239], v190 offset:21504
	ds_read_b128 v[242:245], v190 offset:22528
	ds_read_b128 v[246:249], v190 offset:23552
	global_load_lds_dwordx4 v[176:177], off
	v_lshl_add_u64 v[182:183], s[44:45], 0, v[160:161]
	s_mov_b32 m0, s27
	s_addc_u32 s63, s45, 0
	global_load_lds_dwordx4 v[182:183], off
	v_lshl_add_u64 v[184:185], s[62:63], 0, v[156:157]
	s_mov_b32 m0, s33
	v_lshl_add_u64 v[186:187], s[48:49], 0, v[158:159]
	global_load_lds_dwordx4 v[184:185], off
	v_lshl_add_u64 v[184:185], s[62:63], 0, v[160:161]
	s_mov_b32 m0, s35
	s_nop 0
	global_load_lds_dwordx4 v[184:185], off
	v_lshl_add_u64 v[184:185], s[48:49], 0, v[154:155]
	s_mov_b32 m0, s8
	s_nop 0
	global_load_lds_dwordx4 v[184:185], off
	s_mov_b32 m0, s43
	s_nop 0
	global_load_lds_dwordx4 v[186:187], off
	s_waitcnt vmcnt(8)
	s_waitcnt lgkmcnt(0)
	s_setprio 1
	s_barrier
	v_mfma_f32_16x16x128_f8f6f4 v[70:73], v[2:9], v[216:223], v[70:73]
	v_mfma_f32_16x16x128_f8f6f4 v[66:69], v[192:199], v[216:223], v[66:69]
	v_mfma_f32_16x16x128_f8f6f4 v[58:61], v[192:199], v[224:231], v[58:61]
	v_mfma_f32_16x16x128_f8f6f4 v[62:65], v[2:9], v[224:231], v[62:65]
	v_mfma_f32_16x16x128_f8f6f4 v[54:57], v[2:9], v[232:239], v[54:57]
	v_mfma_f32_16x16x128_f8f6f4 v[50:53], v[192:199], v[232:239], v[50:53]
	v_mfma_f32_16x16x128_f8f6f4 v[42:45], v[192:199], v[242:249], v[42:45]
	v_mfma_f32_16x16x128_f8f6f4 v[46:49], v[2:9], v[242:249], v[46:49]
	v_mfma_f32_16x16x128_f8f6f4 v[14:17], v[200:207], v[242:249], v[14:17]
	v_mfma_f32_16x16x128_f8f6f4 v[10:13], v[208:215], v[242:249], v[10:13]
	v_mfma_f32_16x16x128_f8f6f4 v[18:21], v[208:215], v[232:239], v[18:21]
	v_mfma_f32_16x16x128_f8f6f4 v[22:25], v[200:207], v[232:239], v[22:25]
	v_mfma_f32_16x16x128_f8f6f4 v[30:33], v[200:207], v[224:231], v[30:33]
	v_mfma_f32_16x16x128_f8f6f4 v[26:29], v[208:215], v[224:231], v[26:29]
	v_mfma_f32_16x16x128_f8f6f4 v[34:37], v[208:215], v[216:223], v[34:37]
	v_mfma_f32_16x16x128_f8f6f4 v[38:41], v[200:207], v[216:223], v[38:41]
	s_barrier
	s_setprio 0
	ds_read_b128 v[192:195], v189 offset:32768
	ds_read_b128 v[196:199], v189 offset:33792
	ds_read_b128 v[200:203], v189 offset:34816
	ds_read_b128 v[204:207], v189 offset:35840
	ds_read_b128 v[2:5], v189 offset:49152
	ds_read_b128 v[6:9], v189 offset:50176
	ds_read_b128 v[208:211], v189 offset:51200
	ds_read_b128 v[212:215], v189 offset:52224
	s_add_u32 s48, s48, 0x80000
	s_addc_u32 s49, s49, 0
	s_mov_b32 m0, s52
	v_lshl_add_u64 v[252:253], s[48:49], 0, v[154:155]
	ds_read_b128 v[216:219], v190 offset:32768
	ds_read_b128 v[220:223], v190 offset:33792
	ds_read_b128 v[224:227], v190 offset:34816
	ds_read_b128 v[228:231], v190 offset:35840
	ds_read_b128 v[232:235], v190 offset:36864
	ds_read_b128 v[236:239], v190 offset:37888
	ds_read_b128 v[242:245], v190 offset:38912
	ds_read_b128 v[246:249], v190 offset:39936
	global_load_lds_dwordx4 v[252:253], off
	v_lshl_add_u64 v[252:253], s[48:49], 0, v[158:159]
	s_mov_b32 m0, s53
	s_nop 0
	global_load_lds_dwordx4 v[252:253], off
	s_waitcnt vmcnt(8)
	s_waitcnt lgkmcnt(0)
	s_setprio 1
	s_barrier
	v_mfma_f32_16x16x128_f8f6f4 v[134:137], v[192:199], v[216:223], v[134:137]
	v_mfma_f32_16x16x128_f8f6f4 v[130:133], v[200:207], v[216:223], v[130:133]
	v_mfma_f32_16x16x128_f8f6f4 v[122:125], v[200:207], v[224:231], v[122:125]
	v_mfma_f32_16x16x128_f8f6f4 v[126:129], v[192:199], v[224:231], v[126:129]
	v_mfma_f32_16x16x128_f8f6f4 v[118:121], v[192:199], v[232:239], v[118:121]
	v_mfma_f32_16x16x128_f8f6f4 v[114:117], v[200:207], v[232:239], v[114:117]
	v_mfma_f32_16x16x128_f8f6f4 v[106:109], v[200:207], v[242:249], v[106:109]
	v_mfma_f32_16x16x128_f8f6f4 v[110:113], v[192:199], v[242:249], v[110:113]
	v_mfma_f32_16x16x128_f8f6f4 v[78:81], v[2:9], v[242:249], v[78:81]
	v_mfma_f32_16x16x128_f8f6f4 v[74:77], v[208:215], v[242:249], v[74:77]
	v_mfma_f32_16x16x128_f8f6f4 v[82:85], v[208:215], v[232:239], v[82:85]
	v_mfma_f32_16x16x128_f8f6f4 v[86:89], v[2:9], v[232:239], v[86:89]
	v_mfma_f32_16x16x128_f8f6f4 v[94:97], v[2:9], v[224:231], v[94:97]
	v_mfma_f32_16x16x128_f8f6f4 v[90:93], v[208:215], v[224:231], v[90:93]
	v_mfma_f32_16x16x128_f8f6f4 v[98:101], v[208:215], v[216:223], v[98:101]
	v_mfma_f32_16x16x128_f8f6f4 v[102:105], v[2:9], v[216:223], v[102:105]
	s_barrier
	s_setprio 0
	s_mov_b32 m0, s70
	v_lshl_add_u64 v[176:177], v[176:177], 0, s[18:19]
	s_add_u32 s44, s44, 0x80080
	ds_read_b128 v[216:219], v190 offset:49152
	ds_read_b128 v[220:223], v190 offset:50176
	ds_read_b128 v[224:227], v190 offset:51200
	ds_read_b128 v[228:231], v190 offset:52224
	ds_read_b128 v[232:235], v190 offset:53248
	ds_read_b128 v[236:239], v190 offset:54272
	ds_read_b128 v[242:245], v190 offset:55296
	ds_read_b128 v[246:249], v190 offset:56320
	global_load_lds_dwordx4 v[176:177], off
	v_lshl_add_u64 v[176:177], v[182:183], 0, s[18:19]
	s_mov_b32 m0, s71
	s_addc_u32 s45, s45, 0
	global_load_lds_dwordx4 v[176:177], off
	v_lshl_add_u64 v[176:177], s[44:45], 0, v[156:157]
	s_mov_b32 m0, s74
	s_nop 0
	global_load_lds_dwordx4 v[176:177], off
	v_lshl_add_u64 v[176:177], s[44:45], 0, v[160:161]
	s_mov_b32 m0, s75
	s_nop 0
	global_load_lds_dwordx4 v[176:177], off
	v_lshl_add_u64 v[176:177], v[184:185], 0, s[18:19]
	s_mov_b32 m0, s72
	s_nop 0
	global_load_lds_dwordx4 v[176:177], off
	v_lshl_add_u64 v[176:177], v[186:187], 0, s[18:19]
	s_mov_b32 m0, s73
	s_nop 0
	global_load_lds_dwordx4 v[176:177], off
	s_waitcnt vmcnt(8)
	s_waitcnt lgkmcnt(0)
	s_setprio 1
	s_barrier
	v_mfma_f32_16x16x128_f8f6f4 v[70:73], v[192:199], v[216:223], v[70:73]
	v_mfma_f32_16x16x128_f8f6f4 v[66:69], v[200:207], v[216:223], v[66:69]
	v_mfma_f32_16x16x128_f8f6f4 v[58:61], v[200:207], v[224:231], v[58:61]
	v_mfma_f32_16x16x128_f8f6f4 v[62:65], v[192:199], v[224:231], v[62:65]
	v_mfma_f32_16x16x128_f8f6f4 v[54:57], v[192:199], v[232:239], v[54:57]
	v_mfma_f32_16x16x128_f8f6f4 v[50:53], v[200:207], v[232:239], v[50:53]
	v_mfma_f32_16x16x128_f8f6f4 v[42:45], v[200:207], v[242:249], v[42:45]
	v_mfma_f32_16x16x128_f8f6f4 v[46:49], v[192:199], v[242:249], v[46:49]
	v_mfma_f32_16x16x128_f8f6f4 v[14:17], v[2:9], v[242:249], v[14:17]
	v_mfma_f32_16x16x128_f8f6f4 v[10:13], v[208:215], v[242:249], v[10:13]
	v_mfma_f32_16x16x128_f8f6f4 v[18:21], v[208:215], v[232:239], v[18:21]
	v_mfma_f32_16x16x128_f8f6f4 v[22:25], v[2:9], v[232:239], v[22:25]
	v_mfma_f32_16x16x128_f8f6f4 v[30:33], v[2:9], v[224:231], v[30:33]
	v_mfma_f32_16x16x128_f8f6f4 v[26:29], v[208:215], v[224:231], v[26:29]
	v_mfma_f32_16x16x128_f8f6f4 v[34:37], v[208:215], v[216:223], v[34:37]
	v_mfma_f32_16x16x128_f8f6f4 v[38:41], v[2:9], v[216:223], v[38:41]
	s_barrier
	s_setprio 0
	s_add_i32 s44, s51, 2
	s_add_u32 s46, s46, 0x100
	s_addc_u32 s47, s47, 0
	s_add_u32 s41, s41, 0x100
	s_addc_u32 s50, s50, 0
	s_cmp_ge_i32 s51, s86
	s_cbranch_scc1 .LBB0_796
	s_mov_b32 s51, s44
	s_cmp_eq_u32 s86, s51
	s_cselect_b64 s[44:45], -1, 0
	s_cmp_lg_u32 s86, s51
	s_cbranch_scc0 .LBB0_793
	s_branch .LBB0_794

.LBB0_946:
	s_ashr_i32 s37, s36, 31
	ds_read_b128 v[18:21], v192
	ds_read_b128 v[22:25], v192 offset:1024
	ds_read_b128 v[26:29], v192 offset:2048
	ds_read_b128 v[30:33], v192 offset:3072
	ds_read_b128 v[2:5], v192 offset:16384
	ds_read_b128 v[6:9], v192 offset:17408
	ds_read_b128 v[10:13], v192 offset:18432
	ds_read_b128 v[14:17], v192 offset:19456
	s_lshl_b64 s[38:39], s[36:37], 20
	s_add_u32 s38, s22, s38
	s_addc_u32 s39, s23, s39
	s_and_b64 s[40:41], s[2:3], exec
	s_cselect_b32 s37, s39, s47
	s_cselect_b32 s84, s38, s46
	s_ashr_i32 s27, s26, 31
	s_lshl_b64 s[40:41], s[26:27], 20
	s_add_u32 s40, s25, s40
	s_addc_u32 s41, s35, s41
	s_and_b64 s[48:49], s[2:3], exec
	s_cselect_b32 s27, s41, s45
	s_cselect_b32 s85, s40, s44
	s_add_u32 s48, s46, 0x80080
	s_addc_u32 s49, s47, 0
	s_mov_b32 m0, s80
	v_lshl_add_u64 v[218:219], s[48:49], 0, v[164:165]
	ds_read_b128 v[184:187], v193
	ds_read_b128 v[188:191], v193 offset:1024
	ds_read_b128 v[194:197], v193 offset:2048
	ds_read_b128 v[198:201], v193 offset:3072
	ds_read_b128 v[202:205], v193 offset:4096
	ds_read_b128 v[206:209], v193 offset:5120
	ds_read_b128 v[210:213], v193 offset:6144
	ds_read_b128 v[214:217], v193 offset:7168
	global_load_lds_dwordx4 v[218:219], off
	v_lshl_add_u64 v[218:219], s[48:49], 0, v[168:169]
	s_mov_b32 m0, s81
	s_nop 0
	global_load_lds_dwordx4 v[218:219], off
	s_waitcnt vmcnt(8)
	s_waitcnt lgkmcnt(0)
	s_setprio 1
	s_barrier
	v_mfma_f32_16x16x128_f8f6f4 v[158:161], v[18:25], v[184:191], 0
	v_mfma_f32_16x16x128_f8f6f4 v[154:157], v[26:33], v[184:191], 0
	v_mfma_f32_16x16x128_f8f6f4 v[146:149], v[26:33], v[194:201], 0
	v_mfma_f32_16x16x128_f8f6f4 v[150:153], v[18:25], v[194:201], 0
	v_mfma_f32_16x16x128_f8f6f4 v[142:145], v[18:25], v[202:209], 0
	v_mfma_f32_16x16x128_f8f6f4 v[138:141], v[26:33], v[202:209], 0
	v_mfma_f32_16x16x128_f8f6f4 v[130:133], v[26:33], v[210:217], 0
	v_mfma_f32_16x16x128_f8f6f4 v[134:137], v[18:25], v[210:217], 0
	v_mfma_f32_16x16x128_f8f6f4 v[102:105], v[2:9], v[210:217], 0
	v_mfma_f32_16x16x128_f8f6f4 v[98:101], v[10:17], v[210:217], 0
	v_mfma_f32_16x16x128_f8f6f4 v[106:109], v[10:17], v[202:209], 0
	v_mfma_f32_16x16x128_f8f6f4 v[110:113], v[2:9], v[202:209], 0
	v_mfma_f32_16x16x128_f8f6f4 v[118:121], v[2:9], v[194:201], 0
	v_mfma_f32_16x16x128_f8f6f4 v[114:117], v[10:17], v[194:201], 0
	v_mfma_f32_16x16x128_f8f6f4 v[122:125], v[10:17], v[184:191], 0
	v_mfma_f32_16x16x128_f8f6f4 v[126:129], v[2:9], v[184:191], 0
	s_barrier
	s_setprio 0
	v_lshl_add_u64 v[184:185], s[44:45], 0, v[166:167]
	s_mov_b32 m0, s52
	v_lshl_add_u64 v[186:187], v[184:185], 0, s[14:15]
	ds_read_b128 v[194:197], v193 offset:16384
	ds_read_b128 v[198:201], v193 offset:17408
	ds_read_b128 v[202:205], v193 offset:18432
	ds_read_b128 v[206:209], v193 offset:19456
	ds_read_b128 v[210:213], v193 offset:20480
	ds_read_b128 v[214:217], v193 offset:21504
	ds_read_b128 v[218:221], v193 offset:22528
	ds_read_b128 v[222:225], v193 offset:23552
	global_load_lds_dwordx4 v[186:187], off
	v_lshl_add_u64 v[186:187], s[44:45], 0, v[170:171]
	s_add_u32 s48, s44, 0x80100
	v_lshl_add_u64 v[188:189], v[186:187], 0, s[14:15]
	s_mov_b32 m0, s53
	s_addc_u32 s49, s45, 0
	global_load_lds_dwordx4 v[188:189], off
	v_lshl_add_u64 v[188:189], s[48:49], 0, v[166:167]
	s_mov_b32 m0, s54
	s_nop 0
	global_load_lds_dwordx4 v[188:189], off
	v_lshl_add_u64 v[188:189], s[48:49], 0, v[170:171]
	s_mov_b32 m0, s55
	s_nop 0
	global_load_lds_dwordx4 v[188:189], off
	v_lshl_add_u64 v[188:189], s[46:47], 0, v[164:165]
	v_lshl_add_u64 v[190:191], v[188:189], 0, s[14:15]
	s_mov_b32 m0, s43
	s_nop 0
	global_load_lds_dwordx4 v[190:191], off
	v_lshl_add_u64 v[190:191], s[46:47], 0, v[168:169]
	v_lshl_add_u64 v[226:227], v[190:191], 0, s[14:15]
	s_mov_b32 m0, s61
	s_nop 0
	global_load_lds_dwordx4 v[226:227], off
	s_waitcnt vmcnt(8)
	s_waitcnt lgkmcnt(0)
	s_setprio 1
	s_barrier
	v_mfma_f32_16x16x128_f8f6f4 v[94:97], v[18:25], v[194:201], 0
	v_mfma_f32_16x16x128_f8f6f4 v[90:93], v[26:33], v[194:201], 0
	v_mfma_f32_16x16x128_f8f6f4 v[82:85], v[26:33], v[202:209], 0
	v_mfma_f32_16x16x128_f8f6f4 v[86:89], v[18:25], v[202:209], 0
	v_mfma_f32_16x16x128_f8f6f4 v[78:81], v[18:25], v[210:217], 0
	v_mfma_f32_16x16x128_f8f6f4 v[74:77], v[26:33], v[210:217], 0
	v_mfma_f32_16x16x128_f8f6f4 v[66:69], v[26:33], v[218:225], 0
	v_mfma_f32_16x16x128_f8f6f4 v[70:73], v[18:25], v[218:225], 0
	v_mfma_f32_16x16x128_f8f6f4 v[38:41], v[2:9], v[218:225], 0
	v_mfma_f32_16x16x128_f8f6f4 v[34:37], v[10:17], v[218:225], 0
	v_mfma_f32_16x16x128_f8f6f4 v[42:45], v[10:17], v[210:217], 0
	v_mfma_f32_16x16x128_f8f6f4 v[46:49], v[2:9], v[210:217], 0
	v_mfma_f32_16x16x128_f8f6f4 v[54:57], v[2:9], v[202:209], 0
	v_mfma_f32_16x16x128_f8f6f4 v[50:53], v[10:17], v[202:209], 0
	v_mfma_f32_16x16x128_f8f6f4 v[58:61], v[10:17], v[194:201], 0
	v_mfma_f32_16x16x128_f8f6f4 v[62:65], v[2:9], v[194:201], 0
	s_barrier
	s_setprio 0
	ds_read_b128 v[18:21], v192 offset:32768
	ds_read_b128 v[22:25], v192 offset:33792
	ds_read_b128 v[26:29], v192 offset:34816
	ds_read_b128 v[30:33], v192 offset:35840
	ds_read_b128 v[2:5], v192 offset:49152
	ds_read_b128 v[6:9], v192 offset:50176
	ds_read_b128 v[10:13], v192 offset:51200
	ds_read_b128 v[14:17], v192 offset:52224
	s_add_u32 s48, s46, 0x80100
	s_addc_u32 s49, s47, 0
	s_mov_b32 m0, s68
	v_lshl_add_u64 v[226:227], s[48:49], 0, v[164:165]
	ds_read_b128 v[194:197], v193 offset:32768
	ds_read_b128 v[198:201], v193 offset:33792
	ds_read_b128 v[202:205], v193 offset:34816
	ds_read_b128 v[206:209], v193 offset:35840
	ds_read_b128 v[210:213], v193 offset:36864
	ds_read_b128 v[214:217], v193 offset:37888
	ds_read_b128 v[218:221], v193 offset:38912
	ds_read_b128 v[222:225], v193 offset:39936
	global_load_lds_dwordx4 v[226:227], off
	v_lshl_add_u64 v[226:227], s[48:49], 0, v[168:169]
	s_mov_b32 m0, s69
	s_nop 0
	global_load_lds_dwordx4 v[226:227], off
	s_waitcnt vmcnt(8)
	s_waitcnt lgkmcnt(0)
	s_setprio 1
	s_barrier
	v_mfma_f32_16x16x128_f8f6f4 v[158:161], v[18:25], v[194:201], v[158:161]
	v_mfma_f32_16x16x128_f8f6f4 v[154:157], v[26:33], v[194:201], v[154:157]
	v_mfma_f32_16x16x128_f8f6f4 v[146:149], v[26:33], v[202:209], v[146:149]
	v_mfma_f32_16x16x128_f8f6f4 v[150:153], v[18:25], v[202:209], v[150:153]
	v_mfma_f32_16x16x128_f8f6f4 v[142:145], v[18:25], v[210:217], v[142:145]
	v_mfma_f32_16x16x128_f8f6f4 v[138:141], v[26:33], v[210:217], v[138:141]
	v_mfma_f32_16x16x128_f8f6f4 v[130:133], v[26:33], v[218:225], v[130:133]
	v_mfma_f32_16x16x128_f8f6f4 v[134:137], v[18:25], v[218:225], v[134:137]
	v_mfma_f32_16x16x128_f8f6f4 v[102:105], v[2:9], v[218:225], v[102:105]
	v_mfma_f32_16x16x128_f8f6f4 v[98:101], v[10:17], v[218:225], v[98:101]
	v_mfma_f32_16x16x128_f8f6f4 v[106:109], v[10:17], v[210:217], v[106:109]
	v_mfma_f32_16x16x128_f8f6f4 v[110:113], v[2:9], v[210:217], v[110:113]
	v_mfma_f32_16x16x128_f8f6f4 v[118:121], v[2:9], v[202:209], v[118:121]
	v_mfma_f32_16x16x128_f8f6f4 v[114:117], v[10:17], v[202:209], v[114:117]
	v_mfma_f32_16x16x128_f8f6f4 v[122:125], v[10:17], v[194:201], v[122:125]
	v_mfma_f32_16x16x128_f8f6f4 v[126:129], v[2:9], v[194:201], v[126:129]
	s_barrier
	s_setprio 0
	s_mov_b32 m0, s74
	v_lshl_add_u64 v[184:185], v[184:185], 0, s[18:19]
	s_add_u32 s48, s44, 0x80180
	ds_read_b128 v[194:197], v193 offset:49152
	ds_read_b128 v[198:201], v193 offset:50176
	ds_read_b128 v[202:205], v193 offset:51200
	ds_read_b128 v[206:209], v193 offset:52224
	ds_read_b128 v[210:213], v193 offset:53248
	ds_read_b128 v[214:217], v193 offset:54272
	ds_read_b128 v[218:221], v193 offset:55296
	ds_read_b128 v[222:225], v193 offset:56320
	global_load_lds_dwordx4 v[184:185], off
	v_lshl_add_u64 v[184:185], v[186:187], 0, s[18:19]
	s_mov_b32 m0, s75
	s_addc_u32 s49, s45, 0
	global_load_lds_dwordx4 v[184:185], off
	v_lshl_add_u64 v[184:185], s[48:49], 0, v[166:167]
	s_mov_b32 m0, s78
	s_nop 0
	global_load_lds_dwordx4 v[184:185], off
	v_lshl_add_u64 v[184:185], s[48:49], 0, v[170:171]
	s_mov_b32 m0, s79
	s_nop 0
	global_load_lds_dwordx4 v[184:185], off
	v_lshl_add_u64 v[184:185], v[188:189], 0, s[18:19]
	s_mov_b32 m0, s76
	s_nop 0
	global_load_lds_dwordx4 v[184:185], off
	v_lshl_add_u64 v[184:185], v[190:191], 0, s[18:19]
	s_mov_b32 m0, s77
	s_nop 0
	global_load_lds_dwordx4 v[184:185], off
	s_waitcnt vmcnt(8)
	s_waitcnt lgkmcnt(0)
	s_setprio 1
	s_barrier
	v_mfma_f32_16x16x128_f8f6f4 v[94:97], v[18:25], v[194:201], v[94:97]
	v_mfma_f32_16x16x128_f8f6f4 v[90:93], v[26:33], v[194:201], v[90:93]
	v_mfma_f32_16x16x128_f8f6f4 v[82:85], v[26:33], v[202:209], v[82:85]
	v_mfma_f32_16x16x128_f8f6f4 v[86:89], v[18:25], v[202:209], v[86:89]
	v_mfma_f32_16x16x128_f8f6f4 v[78:81], v[18:25], v[210:217], v[78:81]
	v_mfma_f32_16x16x128_f8f6f4 v[74:77], v[26:33], v[210:217], v[74:77]
	v_mfma_f32_16x16x128_f8f6f4 v[66:69], v[26:33], v[218:225], v[66:69]
	v_mfma_f32_16x16x128_f8f6f4 v[70:73], v[18:25], v[218:225], v[70:73]
	v_mfma_f32_16x16x128_f8f6f4 v[38:41], v[2:9], v[218:225], v[38:41]
	v_mfma_f32_16x16x128_f8f6f4 v[34:37], v[10:17], v[218:225], v[34:37]
	v_mfma_f32_16x16x128_f8f6f4 v[42:45], v[10:17], v[210:217], v[42:45]
	v_mfma_f32_16x16x128_f8f6f4 v[46:49], v[2:9], v[210:217], v[46:49]
	v_mfma_f32_16x16x128_f8f6f4 v[54:57], v[2:9], v[202:209], v[54:57]
	v_mfma_f32_16x16x128_f8f6f4 v[50:53], v[10:17], v[202:209], v[50:53]
	v_mfma_f32_16x16x128_f8f6f4 v[58:61], v[10:17], v[194:201], v[58:61]
	v_mfma_f32_16x16x128_f8f6f4 v[62:65], v[2:9], v[194:201], v[62:65]
	s_barrier
	s_setprio 0
	s_add_u32 s46, s46, 0x80180
	s_addc_u32 s47, s47, 0
	s_add_u32 s62, s44, 0x200
	s_addc_u32 s63, s45, 0
	s_mov_b32 s86, 0
.LBB0_947:
	ds_read_b128 v[2:5], v192
	ds_read_b128 v[6:9], v192 offset:1024
	ds_read_b128 v[18:21], v192 offset:2048
	ds_read_b128 v[22:25], v192 offset:3072
	ds_read_b128 v[26:29], v192 offset:16384
	ds_read_b128 v[30:33], v192 offset:17408
	ds_read_b128 v[184:187], v192 offset:18432
	ds_read_b128 v[188:191], v192 offset:19456
	s_add_u32 s44, s46, 0xfff80080
	s_addc_u32 s45, s47, -1
	s_cmp_eq_u32 s86, 28
	s_cselect_b32 s49, s37, s45
	s_cselect_b32 s48, s84, s44
	s_cselect_b32 s45, s27, s63
	s_cselect_b32 s44, s85, s62
	s_mov_b32 m0, s80
	v_lshl_add_u64 v[218:219], s[46:47], 0, v[172:173]
	ds_read_b128 v[10:13], v193
	ds_read_b128 v[14:17], v193 offset:1024
	ds_read_b128 v[194:197], v193 offset:2048
	ds_read_b128 v[198:201], v193 offset:3072
	ds_read_b128 v[202:205], v193 offset:4096
	ds_read_b128 v[206:209], v193 offset:5120
	ds_read_b128 v[210:213], v193 offset:6144
	ds_read_b128 v[214:217], v193 offset:7168
	global_load_lds_dwordx4 v[218:219], off
	v_lshl_add_u64 v[218:219], s[46:47], 0, v[174:175]
	s_mov_b32 m0, s81
	s_nop 0
	global_load_lds_dwordx4 v[218:219], off
	s_waitcnt vmcnt(8)
	s_waitcnt lgkmcnt(0)
	s_setprio 1
	s_barrier
	v_mfma_f32_16x16x128_f8f6f4 v[158:161], v[2:9], v[10:17], v[158:161]
	v_mfma_f32_16x16x128_f8f6f4 v[154:157], v[18:25], v[10:17], v[154:157]
	v_mfma_f32_16x16x128_f8f6f4 v[146:149], v[18:25], v[194:201], v[146:149]
	v_mfma_f32_16x16x128_f8f6f4 v[150:153], v[2:9], v[194:201], v[150:153]
	v_mfma_f32_16x16x128_f8f6f4 v[142:145], v[2:9], v[202:209], v[142:145]
	v_mfma_f32_16x16x128_f8f6f4 v[138:141], v[18:25], v[202:209], v[138:141]
	v_mfma_f32_16x16x128_f8f6f4 v[130:133], v[18:25], v[210:217], v[130:133]
	v_mfma_f32_16x16x128_f8f6f4 v[134:137], v[2:9], v[210:217], v[134:137]
	v_mfma_f32_16x16x128_f8f6f4 v[102:105], v[26:33], v[210:217], v[102:105]
	v_mfma_f32_16x16x128_f8f6f4 v[98:101], v[184:191], v[210:217], v[98:101]
	v_mfma_f32_16x16x128_f8f6f4 v[106:109], v[184:191], v[202:209], v[106:109]
	v_mfma_f32_16x16x128_f8f6f4 v[110:113], v[26:33], v[202:209], v[110:113]
	v_mfma_f32_16x16x128_f8f6f4 v[118:121], v[26:33], v[194:201], v[118:121]
	v_mfma_f32_16x16x128_f8f6f4 v[114:117], v[184:191], v[194:201], v[114:117]
	v_mfma_f32_16x16x128_f8f6f4 v[122:125], v[184:191], v[10:17], v[122:125]
	v_mfma_f32_16x16x128_f8f6f4 v[126:129], v[26:33], v[10:17], v[126:129]
	s_barrier
	s_setprio 0
	s_mov_b32 m0, s52
	v_lshl_add_u64 v[10:11], s[44:45], 0, v[166:167]
	s_add_u32 s88, s44, 0x80000
	ds_read_b128 v[194:197], v193 offset:16384
	ds_read_b128 v[198:201], v193 offset:17408
	ds_read_b128 v[202:205], v193 offset:18432
	ds_read_b128 v[206:209], v193 offset:19456
	ds_read_b128 v[210:213], v193 offset:20480
	ds_read_b128 v[214:217], v193 offset:21504
	ds_read_b128 v[218:221], v193 offset:22528
	ds_read_b128 v[222:225], v193 offset:23552
	global_load_lds_dwordx4 v[10:11], off
	v_lshl_add_u64 v[12:13], s[44:45], 0, v[170:171]
	s_mov_b32 m0, s53
	s_addc_u32 s89, s45, 0
	global_load_lds_dwordx4 v[12:13], off
	v_lshl_add_u64 v[14:15], s[88:89], 0, v[166:167]
	s_mov_b32 m0, s54
	v_lshl_add_u64 v[16:17], s[48:49], 0, v[168:169]
	global_load_lds_dwordx4 v[14:15], off
	v_lshl_add_u64 v[14:15], s[88:89], 0, v[170:171]
	s_mov_b32 m0, s55
	s_nop 0
	global_load_lds_dwordx4 v[14:15], off
	v_lshl_add_u64 v[14:15], s[48:49], 0, v[164:165]
	s_mov_b32 m0, s43
	s_nop 0
	global_load_lds_dwordx4 v[14:15], off
	s_mov_b32 m0, s61
	s_nop 0
	global_load_lds_dwordx4 v[16:17], off
	s_waitcnt vmcnt(8)
	s_waitcnt lgkmcnt(0)
	s_setprio 1
	s_barrier
	v_mfma_f32_16x16x128_f8f6f4 v[94:97], v[2:9], v[194:201], v[94:97]
	v_mfma_f32_16x16x128_f8f6f4 v[90:93], v[18:25], v[194:201], v[90:93]
	v_mfma_f32_16x16x128_f8f6f4 v[82:85], v[18:25], v[202:209], v[82:85]
	v_mfma_f32_16x16x128_f8f6f4 v[86:89], v[2:9], v[202:209], v[86:89]
	v_mfma_f32_16x16x128_f8f6f4 v[78:81], v[2:9], v[210:217], v[78:81]
	v_mfma_f32_16x16x128_f8f6f4 v[74:77], v[18:25], v[210:217], v[74:77]
	v_mfma_f32_16x16x128_f8f6f4 v[66:69], v[18:25], v[218:225], v[66:69]
	v_mfma_f32_16x16x128_f8f6f4 v[70:73], v[2:9], v[218:225], v[70:73]
	v_mfma_f32_16x16x128_f8f6f4 v[38:41], v[26:33], v[218:225], v[38:41]
	v_mfma_f32_16x16x128_f8f6f4 v[34:37], v[184:191], v[218:225], v[34:37]
	v_mfma_f32_16x16x128_f8f6f4 v[42:45], v[184:191], v[210:217], v[42:45]
	v_mfma_f32_16x16x128_f8f6f4 v[46:49], v[26:33], v[210:217], v[46:49]
	v_mfma_f32_16x16x128_f8f6f4 v[54:57], v[26:33], v[202:209], v[54:57]
	v_mfma_f32_16x16x128_f8f6f4 v[50:53], v[184:191], v[202:209], v[50:53]
	v_mfma_f32_16x16x128_f8f6f4 v[58:61], v[184:191], v[194:201], v[58:61]
	v_mfma_f32_16x16x128_f8f6f4 v[62:65], v[26:33], v[194:201], v[62:65]
	s_barrier
	s_setprio 0
	ds_read_b128 v[18:21], v192 offset:32768
	ds_read_b128 v[22:25], v192 offset:33792
	ds_read_b128 v[26:29], v192 offset:34816
	ds_read_b128 v[30:33], v192 offset:35840
	ds_read_b128 v[2:5], v192 offset:49152
	ds_read_b128 v[6:9], v192 offset:50176
	ds_read_b128 v[184:187], v192 offset:51200
	ds_read_b128 v[188:191], v192 offset:52224
	s_add_u32 s48, s48, 0x80000
	s_addc_u32 s49, s49, 0
	s_mov_b32 m0, s68
	v_lshl_add_u64 v[226:227], s[48:49], 0, v[164:165]
	ds_read_b128 v[194:197], v193 offset:32768
	ds_read_b128 v[198:201], v193 offset:33792
	ds_read_b128 v[202:205], v193 offset:34816
	ds_read_b128 v[206:209], v193 offset:35840
	ds_read_b128 v[210:213], v193 offset:36864
	ds_read_b128 v[214:217], v193 offset:37888
	ds_read_b128 v[218:221], v193 offset:38912
	ds_read_b128 v[222:225], v193 offset:39936
	global_load_lds_dwordx4 v[226:227], off
	v_lshl_add_u64 v[226:227], s[48:49], 0, v[168:169]
	s_mov_b32 m0, s69
	s_nop 0
	global_load_lds_dwordx4 v[226:227], off
	s_waitcnt vmcnt(8)
	s_waitcnt lgkmcnt(0)
	s_setprio 1
	s_barrier
	v_mfma_f32_16x16x128_f8f6f4 v[158:161], v[18:25], v[194:201], v[158:161]
	v_mfma_f32_16x16x128_f8f6f4 v[154:157], v[26:33], v[194:201], v[154:157]
	v_mfma_f32_16x16x128_f8f6f4 v[146:149], v[26:33], v[202:209], v[146:149]
	v_mfma_f32_16x16x128_f8f6f4 v[150:153], v[18:25], v[202:209], v[150:153]
	v_mfma_f32_16x16x128_f8f6f4 v[142:145], v[18:25], v[210:217], v[142:145]
	v_mfma_f32_16x16x128_f8f6f4 v[138:141], v[26:33], v[210:217], v[138:141]
	v_mfma_f32_16x16x128_f8f6f4 v[130:133], v[26:33], v[218:225], v[130:133]
	v_mfma_f32_16x16x128_f8f6f4 v[134:137], v[18:25], v[218:225], v[134:137]
	v_mfma_f32_16x16x128_f8f6f4 v[102:105], v[2:9], v[218:225], v[102:105]
	v_mfma_f32_16x16x128_f8f6f4 v[98:101], v[184:191], v[218:225], v[98:101]
	v_mfma_f32_16x16x128_f8f6f4 v[106:109], v[184:191], v[210:217], v[106:109]
	v_mfma_f32_16x16x128_f8f6f4 v[110:113], v[2:9], v[210:217], v[110:113]
	v_mfma_f32_16x16x128_f8f6f4 v[118:121], v[2:9], v[202:209], v[118:121]
	v_mfma_f32_16x16x128_f8f6f4 v[114:117], v[184:191], v[202:209], v[114:117]
	v_mfma_f32_16x16x128_f8f6f4 v[122:125], v[184:191], v[194:201], v[122:125]
	v_mfma_f32_16x16x128_f8f6f4 v[126:129], v[2:9], v[194:201], v[126:129]
	s_barrier
	s_setprio 0
	s_mov_b32 m0, s74
	v_lshl_add_u64 v[10:11], v[10:11], 0, s[4:5]
	s_add_u32 s44, s44, 0x80080
	ds_read_b128 v[194:197], v193 offset:49152
	ds_read_b128 v[198:201], v193 offset:50176
	ds_read_b128 v[202:205], v193 offset:51200
	ds_read_b128 v[206:209], v193 offset:52224
	ds_read_b128 v[210:213], v193 offset:53248
	ds_read_b128 v[214:217], v193 offset:54272
	ds_read_b128 v[218:221], v193 offset:55296
	ds_read_b128 v[222:225], v193 offset:56320
	global_load_lds_dwordx4 v[10:11], off
	v_lshl_add_u64 v[10:11], v[12:13], 0, s[4:5]
	s_mov_b32 m0, s75
	s_addc_u32 s45, s45, 0
	global_load_lds_dwordx4 v[10:11], off
	v_lshl_add_u64 v[10:11], s[44:45], 0, v[166:167]
	s_mov_b32 m0, s78
	s_nop 0
	global_load_lds_dwordx4 v[10:11], off
	v_lshl_add_u64 v[10:11], s[44:45], 0, v[170:171]
	s_mov_b32 m0, s79
	s_nop 0
	global_load_lds_dwordx4 v[10:11], off
	v_lshl_add_u64 v[10:11], v[14:15], 0, s[4:5]
	s_mov_b32 m0, s76
	s_nop 0
	global_load_lds_dwordx4 v[10:11], off
	v_lshl_add_u64 v[10:11], v[16:17], 0, s[4:5]
	s_mov_b32 m0, s77
	s_nop 0
	global_load_lds_dwordx4 v[10:11], off
	s_waitcnt vmcnt(8)
	s_waitcnt lgkmcnt(0)
	s_setprio 1
	s_barrier
	v_mfma_f32_16x16x128_f8f6f4 v[94:97], v[18:25], v[194:201], v[94:97]
	v_mfma_f32_16x16x128_f8f6f4 v[90:93], v[26:33], v[194:201], v[90:93]
	v_mfma_f32_16x16x128_f8f6f4 v[82:85], v[26:33], v[202:209], v[82:85]
	v_mfma_f32_16x16x128_f8f6f4 v[86:89], v[18:25], v[202:209], v[86:89]
	v_mfma_f32_16x16x128_f8f6f4 v[78:81], v[18:25], v[210:217], v[78:81]
	v_mfma_f32_16x16x128_f8f6f4 v[74:77], v[26:33], v[210:217], v[74:77]
	v_mfma_f32_16x16x128_f8f6f4 v[66:69], v[26:33], v[218:225], v[66:69]
	v_mfma_f32_16x16x128_f8f6f4 v[70:73], v[18:25], v[218:225], v[70:73]
	v_mfma_f32_16x16x128_f8f6f4 v[38:41], v[2:9], v[218:225], v[38:41]
	v_mfma_f32_16x16x128_f8f6f4 v[34:37], v[184:191], v[218:225], v[34:37]
	v_mfma_f32_16x16x128_f8f6f4 v[42:45], v[184:191], v[210:217], v[42:45]
	v_mfma_f32_16x16x128_f8f6f4 v[46:49], v[2:9], v[210:217], v[46:49]
	v_mfma_f32_16x16x128_f8f6f4 v[54:57], v[2:9], v[202:209], v[54:57]
	v_mfma_f32_16x16x128_f8f6f4 v[50:53], v[184:191], v[202:209], v[50:53]
	v_mfma_f32_16x16x128_f8f6f4 v[58:61], v[184:191], v[194:201], v[58:61]
	v_mfma_f32_16x16x128_f8f6f4 v[62:65], v[2:9], v[194:201], v[62:65]
	s_barrier
	s_setprio 0
	s_add_i32 s86, s86, 2
	s_add_u32 s46, s46, 0x100
	s_addc_u32 s47, s47, 0
	s_add_u32 s62, s62, 0x100
	s_addc_u32 s63, s63, 0
	s_cmp_gt_u32 s86, 29
	s_cbranch_scc0 .LBB0_947
	s_and_b64 vcc, exec, s[6:7]
	s_cbranch_vccz .LBB0_950
	s_barrier

.LBB0_1031:
	ds_read_b128 v[2:5], v189
	ds_read_b128 v[6:9], v189 offset:1024
	ds_read_b128 v[192:195], v189 offset:2048
	ds_read_b128 v[196:199], v189 offset:3072
	ds_read_b128 v[200:203], v189 offset:16384
	ds_read_b128 v[204:207], v189 offset:17408
	ds_read_b128 v[208:211], v189 offset:18432
	ds_read_b128 v[212:215], v189 offset:19456
	s_add_u32 s25, s36, 0x100
	s_addc_u32 s83, s37, 0
	s_and_b64 s[40:41], s[38:39], exec
	s_cselect_b32 s41, s1, s83
	s_cselect_b32 s40, s0, s25
	s_add_u32 s25, s26, 0x100
	s_addc_u32 s83, s27, 0
	s_and_b64 s[38:39], s[38:39], exec
	s_cselect_b32 s39, s5, s83
	s_cselect_b32 s38, s4, s25
	s_add_u32 s84, s36, 0x158080
	s_addc_u32 s85, s37, 0
	s_add_i32 s25, s23, 0xc000
	v_lshl_add_u64 v[174:175], s[84:85], 0, v[154:155]
	s_mov_b32 m0, s25
	s_add_i32 s83, s23, 0xe000
	ds_read_b128 v[216:219], v190
	ds_read_b128 v[220:223], v190 offset:1024
	ds_read_b128 v[224:227], v190 offset:2048
	ds_read_b128 v[228:231], v190 offset:3072
	ds_read_b128 v[232:235], v190 offset:4096
	ds_read_b128 v[236:239], v190 offset:5120
	ds_read_b128 v[240:243], v190 offset:6144
	ds_read_b128 v[244:247], v190 offset:7168
	global_load_lds_dwordx4 v[174:175], off
	v_lshl_add_u64 v[174:175], s[84:85], 0, v[158:159]
	s_mov_b32 m0, s83
	s_nop 0
	global_load_lds_dwordx4 v[174:175], off
	s_waitcnt vmcnt(8)
	s_waitcnt lgkmcnt(0)
	s_setprio 1
	s_barrier
	v_mfma_f32_16x16x128_f8f6f4 v[134:137], v[2:9], v[216:223], 0
	v_mfma_f32_16x16x128_f8f6f4 v[130:133], v[192:199], v[216:223], 0
	v_mfma_f32_16x16x128_f8f6f4 v[122:125], v[192:199], v[224:231], 0
	v_mfma_f32_16x16x128_f8f6f4 v[126:129], v[2:9], v[224:231], 0
	v_mfma_f32_16x16x128_f8f6f4 v[118:121], v[2:9], v[232:239], 0
	v_mfma_f32_16x16x128_f8f6f4 v[114:117], v[192:199], v[232:239], 0
	v_mfma_f32_16x16x128_f8f6f4 v[106:109], v[192:199], v[240:247], 0
	v_mfma_f32_16x16x128_f8f6f4 v[110:113], v[2:9], v[240:247], 0
	v_mfma_f32_16x16x128_f8f6f4 v[78:81], v[200:207], v[240:247], 0
	v_mfma_f32_16x16x128_f8f6f4 v[74:77], v[208:215], v[240:247], 0
	v_mfma_f32_16x16x128_f8f6f4 v[82:85], v[208:215], v[232:239], 0
	v_mfma_f32_16x16x128_f8f6f4 v[86:89], v[200:207], v[232:239], 0
	v_mfma_f32_16x16x128_f8f6f4 v[94:97], v[200:207], v[224:231], 0
	v_mfma_f32_16x16x128_f8f6f4 v[90:93], v[208:215], v[224:231], 0
	v_mfma_f32_16x16x128_f8f6f4 v[98:101], v[208:215], v[216:223], 0
	v_mfma_f32_16x16x128_f8f6f4 v[102:105], v[200:207], v[216:223], 0
	s_barrier
	s_setprio 0
	s_mov_b32 m0, s33
	v_lshl_add_u64 v[174:175], s[38:39], 0, v[156:157]
	s_add_u32 s84, s38, 0x158000
	ds_read_b128 v[216:219], v190 offset:16384
	ds_read_b128 v[220:223], v190 offset:17408
	ds_read_b128 v[224:227], v190 offset:18432
	ds_read_b128 v[228:231], v190 offset:19456
	ds_read_b128 v[232:235], v190 offset:20480
	ds_read_b128 v[236:239], v190 offset:21504
	ds_read_b128 v[240:243], v190 offset:22528
	ds_read_b128 v[244:247], v190 offset:23552
	global_load_lds_dwordx4 v[174:175], off
	v_lshl_add_u64 v[176:177], s[38:39], 0, v[160:161]
	s_mov_b32 m0, s35
	s_addc_u32 s85, s39, 0
	global_load_lds_dwordx4 v[176:177], off
	v_lshl_add_u64 v[182:183], s[84:85], 0, v[156:157]
	s_mov_b32 m0, s42
	v_lshl_add_u64 v[184:185], s[40:41], 0, v[158:159]
	global_load_lds_dwordx4 v[182:183], off
	v_lshl_add_u64 v[182:183], s[84:85], 0, v[160:161]
	s_mov_b32 m0, s43
	s_nop 0
	global_load_lds_dwordx4 v[182:183], off
	v_lshl_add_u64 v[182:183], s[40:41], 0, v[154:155]
	s_mov_b32 m0, s23
	s_nop 0
	global_load_lds_dwordx4 v[182:183], off
	s_mov_b32 m0, s44
	s_nop 0
	global_load_lds_dwordx4 v[184:185], off
	s_waitcnt vmcnt(8)
	s_waitcnt lgkmcnt(0)
	s_setprio 1
	s_barrier
	v_mfma_f32_16x16x128_f8f6f4 v[70:73], v[2:9], v[216:223], 0
	v_mfma_f32_16x16x128_f8f6f4 v[66:69], v[192:199], v[216:223], 0
	v_mfma_f32_16x16x128_f8f6f4 v[58:61], v[192:199], v[224:231], 0
	v_mfma_f32_16x16x128_f8f6f4 v[62:65], v[2:9], v[224:231], 0
	v_mfma_f32_16x16x128_f8f6f4 v[54:57], v[2:9], v[232:239], 0
	v_mfma_f32_16x16x128_f8f6f4 v[50:53], v[192:199], v[232:239], 0
	v_mfma_f32_16x16x128_f8f6f4 v[42:45], v[192:199], v[240:247], 0
	v_mfma_f32_16x16x128_f8f6f4 v[46:49], v[2:9], v[240:247], 0
	v_mfma_f32_16x16x128_f8f6f4 v[14:17], v[200:207], v[240:247], 0
	v_mfma_f32_16x16x128_f8f6f4 v[10:13], v[208:215], v[240:247], 0
	v_mfma_f32_16x16x128_f8f6f4 v[18:21], v[208:215], v[232:239], 0
	v_mfma_f32_16x16x128_f8f6f4 v[22:25], v[200:207], v[232:239], 0
	v_mfma_f32_16x16x128_f8f6f4 v[30:33], v[200:207], v[224:231], 0
	v_mfma_f32_16x16x128_f8f6f4 v[26:29], v[208:215], v[224:231], 0
	v_mfma_f32_16x16x128_f8f6f4 v[34:37], v[208:215], v[216:223], 0
	v_mfma_f32_16x16x128_f8f6f4 v[38:41], v[200:207], v[216:223], 0
	s_barrier
	s_setprio 0
	ds_read_b128 v[2:5], v189 offset:32768
	ds_read_b128 v[6:9], v189 offset:33792
	ds_read_b128 v[192:195], v189 offset:34816
	ds_read_b128 v[196:199], v189 offset:35840
	ds_read_b128 v[200:203], v189 offset:49152
	ds_read_b128 v[204:207], v189 offset:50176
	ds_read_b128 v[208:211], v189 offset:51200
	ds_read_b128 v[212:215], v189 offset:52224
	s_add_u32 s40, s40, 0x158000
	s_addc_u32 s41, s41, 0
	s_mov_b32 m0, s45
	v_lshl_add_u64 v[186:187], s[40:41], 0, v[154:155]
	ds_read_b128 v[216:219], v190 offset:32768
	ds_read_b128 v[220:223], v190 offset:33792
	ds_read_b128 v[224:227], v190 offset:34816
	ds_read_b128 v[228:231], v190 offset:35840
	ds_read_b128 v[232:235], v190 offset:36864
	ds_read_b128 v[236:239], v190 offset:37888
	ds_read_b128 v[240:243], v190 offset:38912
	ds_read_b128 v[244:247], v190 offset:39936
	global_load_lds_dwordx4 v[186:187], off
	v_lshl_add_u64 v[186:187], s[40:41], 0, v[158:159]
	s_mov_b32 m0, s46
	s_nop 0
	global_load_lds_dwordx4 v[186:187], off
	s_waitcnt vmcnt(8)
	s_waitcnt lgkmcnt(0)
	s_setprio 1
	s_barrier
	v_mfma_f32_16x16x128_f8f6f4 v[134:137], v[2:9], v[216:223], v[134:137]
	v_mfma_f32_16x16x128_f8f6f4 v[130:133], v[192:199], v[216:223], v[130:133]
	v_mfma_f32_16x16x128_f8f6f4 v[122:125], v[192:199], v[224:231], v[122:125]
	v_mfma_f32_16x16x128_f8f6f4 v[126:129], v[2:9], v[224:231], v[126:129]
	v_mfma_f32_16x16x128_f8f6f4 v[118:121], v[2:9], v[232:239], v[118:121]
	v_mfma_f32_16x16x128_f8f6f4 v[114:117], v[192:199], v[232:239], v[114:117]
	v_mfma_f32_16x16x128_f8f6f4 v[106:109], v[192:199], v[240:247], v[106:109]
	v_mfma_f32_16x16x128_f8f6f4 v[110:113], v[2:9], v[240:247], v[110:113]
	v_mfma_f32_16x16x128_f8f6f4 v[78:81], v[200:207], v[240:247], v[78:81]
	v_mfma_f32_16x16x128_f8f6f4 v[74:77], v[208:215], v[240:247], v[74:77]
	v_mfma_f32_16x16x128_f8f6f4 v[82:85], v[208:215], v[232:239], v[82:85]
	v_mfma_f32_16x16x128_f8f6f4 v[86:89], v[200:207], v[232:239], v[86:89]
	v_mfma_f32_16x16x128_f8f6f4 v[94:97], v[200:207], v[224:231], v[94:97]
	v_mfma_f32_16x16x128_f8f6f4 v[90:93], v[208:215], v[224:231], v[90:93]
	v_mfma_f32_16x16x128_f8f6f4 v[98:101], v[208:215], v[216:223], v[98:101]
	v_mfma_f32_16x16x128_f8f6f4 v[102:105], v[200:207], v[216:223], v[102:105]
	s_barrier
	s_setprio 0
	s_mov_b32 m0, s52
	v_lshl_add_u64 v[174:175], v[174:175], 0, s[14:15]
	s_add_u32 s38, s38, 0x158080
	ds_read_b128 v[216:219], v190 offset:49152
	ds_read_b128 v[220:223], v190 offset:50176
	ds_read_b128 v[224:227], v190 offset:51200
	ds_read_b128 v[228:231], v190 offset:52224
	ds_read_b128 v[232:235], v190 offset:53248
	ds_read_b128 v[236:239], v190 offset:54272
	ds_read_b128 v[240:243], v190 offset:55296
	ds_read_b128 v[244:247], v190 offset:56320
	global_load_lds_dwordx4 v[174:175], off
	v_lshl_add_u64 v[174:175], v[176:177], 0, s[14:15]
	s_mov_b32 m0, s53
	s_addc_u32 s39, s39, 0
	global_load_lds_dwordx4 v[174:175], off
	v_lshl_add_u64 v[174:175], s[38:39], 0, v[156:157]
	s_mov_b32 m0, s56
	s_nop 0
	global_load_lds_dwordx4 v[174:175], off
	v_lshl_add_u64 v[174:175], s[38:39], 0, v[160:161]
	s_mov_b32 m0, s57
	s_nop 0
	global_load_lds_dwordx4 v[174:175], off
	v_lshl_add_u64 v[174:175], v[182:183], 0, s[14:15]
	s_mov_b32 m0, s54
	s_nop 0
	global_load_lds_dwordx4 v[174:175], off
	v_lshl_add_u64 v[174:175], v[184:185], 0, s[14:15]
	s_mov_b32 m0, s55
	s_nop 0
	global_load_lds_dwordx4 v[174:175], off
	s_waitcnt vmcnt(8)
	s_waitcnt lgkmcnt(0)
	s_setprio 1
	s_barrier
	v_mfma_f32_16x16x128_f8f6f4 v[70:73], v[2:9], v[216:223], v[70:73]
	v_mfma_f32_16x16x128_f8f6f4 v[66:69], v[192:199], v[216:223], v[66:69]
	v_mfma_f32_16x16x128_f8f6f4 v[58:61], v[192:199], v[224:231], v[58:61]
	v_mfma_f32_16x16x128_f8f6f4 v[62:65], v[2:9], v[224:231], v[62:65]
	v_mfma_f32_16x16x128_f8f6f4 v[54:57], v[2:9], v[232:239], v[54:57]
	v_mfma_f32_16x16x128_f8f6f4 v[50:53], v[192:199], v[232:239], v[50:53]
	v_mfma_f32_16x16x128_f8f6f4 v[42:45], v[192:199], v[240:247], v[42:45]
	v_mfma_f32_16x16x128_f8f6f4 v[46:49], v[2:9], v[240:247], v[46:49]
	v_mfma_f32_16x16x128_f8f6f4 v[14:17], v[200:207], v[240:247], v[14:17]
	v_mfma_f32_16x16x128_f8f6f4 v[10:13], v[208:215], v[240:247], v[10:13]
	v_mfma_f32_16x16x128_f8f6f4 v[18:21], v[208:215], v[232:239], v[18:21]
	v_mfma_f32_16x16x128_f8f6f4 v[22:25], v[200:207], v[232:239], v[22:25]
	v_mfma_f32_16x16x128_f8f6f4 v[30:33], v[200:207], v[224:231], v[30:33]
	v_mfma_f32_16x16x128_f8f6f4 v[26:29], v[208:215], v[224:231], v[26:29]
	v_mfma_f32_16x16x128_f8f6f4 v[34:37], v[208:215], v[216:223], v[34:37]
	v_mfma_f32_16x16x128_f8f6f4 v[38:41], v[200:207], v[216:223], v[38:41]
	s_barrier
	s_setprio 0
	s_cmp_lt_u32 s82, 3
	s_cbranch_scc1 .LBB0_1036
	s_add_u32 s38, s48, s63
	s_addc_u32 s39, s49, s62
	s_add_u32 s36, s36, 0x158180
	s_addc_u32 s37, s37, 0
	s_add_u32 s40, s26, 0x200
	v_lshl_add_u64 v[174:175], v[172:173], 2, s[38:39]
	s_addc_u32 s41, s27, 0
	s_mov_b32 s84, 4
	s_cmp_eq_u32 s82, s84
	s_cselect_b64 s[26:27], -1, 0
	s_cmp_lg_u32 s82, s84
	s_cbranch_scc1 .LBB0_1034

.LBB0_1034:
	ds_read_b128 v[2:5], v189
	ds_read_b128 v[6:9], v189 offset:1024
	ds_read_b128 v[192:195], v189 offset:2048
	ds_read_b128 v[196:199], v189 offset:3072
	ds_read_b128 v[200:203], v189 offset:16384
	ds_read_b128 v[204:207], v189 offset:17408
	ds_read_b128 v[208:211], v189 offset:18432
	ds_read_b128 v[212:215], v189 offset:19456
	s_add_u32 s38, s36, 0xffea8080
	s_addc_u32 s39, s37, -1
	s_and_b64 s[26:27], s[26:27], exec
	s_cselect_b32 s26, s4, s40
	s_cselect_b32 s39, s1, s39
	s_cselect_b32 s38, s0, s38
	s_cselect_b32 s27, s5, s41
	s_mov_b32 m0, s25
	v_lshl_add_u64 v[176:177], s[36:37], 0, v[162:163]
	ds_read_b128 v[216:219], v190
	ds_read_b128 v[220:223], v190 offset:1024
	ds_read_b128 v[224:227], v190 offset:2048
	ds_read_b128 v[228:231], v190 offset:3072
	ds_read_b128 v[232:235], v190 offset:4096
	ds_read_b128 v[236:239], v190 offset:5120
	ds_read_b128 v[240:243], v190 offset:6144
	ds_read_b128 v[244:247], v190 offset:7168
	global_load_lds_dwordx4 v[176:177], off
	v_lshl_add_u64 v[176:177], s[36:37], 0, v[164:165]
	s_mov_b32 m0, s83
	s_nop 0
	global_load_lds_dwordx4 v[176:177], off
	s_waitcnt vmcnt(8)
	s_waitcnt lgkmcnt(0)
	s_setprio 1
	s_barrier
	v_mfma_f32_16x16x128_f8f6f4 v[134:137], v[2:9], v[216:223], v[134:137]
	v_mfma_f32_16x16x128_f8f6f4 v[130:133], v[192:199], v[216:223], v[130:133]
	v_mfma_f32_16x16x128_f8f6f4 v[122:125], v[192:199], v[224:231], v[122:125]
	v_mfma_f32_16x16x128_f8f6f4 v[126:129], v[2:9], v[224:231], v[126:129]
	v_mfma_f32_16x16x128_f8f6f4 v[118:121], v[2:9], v[232:239], v[118:121]
	v_mfma_f32_16x16x128_f8f6f4 v[114:117], v[192:199], v[232:239], v[114:117]
	v_mfma_f32_16x16x128_f8f6f4 v[106:109], v[192:199], v[240:247], v[106:109]
	v_mfma_f32_16x16x128_f8f6f4 v[110:113], v[2:9], v[240:247], v[110:113]
	v_mfma_f32_16x16x128_f8f6f4 v[78:81], v[200:207], v[240:247], v[78:81]
	v_mfma_f32_16x16x128_f8f6f4 v[74:77], v[208:215], v[240:247], v[74:77]
	v_mfma_f32_16x16x128_f8f6f4 v[82:85], v[208:215], v[232:239], v[82:85]
	v_mfma_f32_16x16x128_f8f6f4 v[86:89], v[200:207], v[232:239], v[86:89]
	v_mfma_f32_16x16x128_f8f6f4 v[94:97], v[200:207], v[224:231], v[94:97]
	v_mfma_f32_16x16x128_f8f6f4 v[90:93], v[208:215], v[224:231], v[90:93]
	v_mfma_f32_16x16x128_f8f6f4 v[98:101], v[208:215], v[216:223], v[98:101]
	v_mfma_f32_16x16x128_f8f6f4 v[102:105], v[200:207], v[216:223], v[102:105]
	s_barrier
	s_setprio 0
	s_mov_b32 m0, s33
	v_lshl_add_u64 v[176:177], s[26:27], 0, v[156:157]
	s_add_u32 s62, s26, 0x158000
	ds_read_b128 v[216:219], v190 offset:16384
	ds_read_b128 v[220:223], v190 offset:17408
	ds_read_b128 v[224:227], v190 offset:18432
	ds_read_b128 v[228:231], v190 offset:19456
	ds_read_b128 v[232:235], v190 offset:20480
	ds_read_b128 v[236:239], v190 offset:21504
	ds_read_b128 v[240:243], v190 offset:22528
	ds_read_b128 v[244:247], v190 offset:23552
	global_load_lds_dwordx4 v[176:177], off
	v_lshl_add_u64 v[182:183], s[26:27], 0, v[160:161]
	s_mov_b32 m0, s35
	s_addc_u32 s63, s27, 0
	global_load_lds_dwordx4 v[182:183], off
	v_lshl_add_u64 v[184:185], s[62:63], 0, v[156:157]
	s_mov_b32 m0, s42
	v_lshl_add_u64 v[186:187], s[38:39], 0, v[158:159]
	global_load_lds_dwordx4 v[184:185], off
	v_lshl_add_u64 v[184:185], s[62:63], 0, v[160:161]
	s_mov_b32 m0, s43
	s_nop 0
	global_load_lds_dwordx4 v[184:185], off
	v_lshl_add_u64 v[184:185], s[38:39], 0, v[154:155]
	s_mov_b32 m0, s23
	s_nop 0
	global_load_lds_dwordx4 v[184:185], off
	s_mov_b32 m0, s44
	s_nop 0
	global_load_lds_dwordx4 v[186:187], off
	s_waitcnt vmcnt(8)
	s_waitcnt lgkmcnt(0)
	s_setprio 1
	s_barrier
	v_mfma_f32_16x16x128_f8f6f4 v[70:73], v[2:9], v[216:223], v[70:73]
	v_mfma_f32_16x16x128_f8f6f4 v[66:69], v[192:199], v[216:223], v[66:69]
	v_mfma_f32_16x16x128_f8f6f4 v[58:61], v[192:199], v[224:231], v[58:61]
	v_mfma_f32_16x16x128_f8f6f4 v[62:65], v[2:9], v[224:231], v[62:65]
	v_mfma_f32_16x16x128_f8f6f4 v[54:57], v[2:9], v[232:239], v[54:57]
	v_mfma_f32_16x16x128_f8f6f4 v[50:53], v[192:199], v[232:239], v[50:53]
	v_mfma_f32_16x16x128_f8f6f4 v[42:45], v[192:199], v[240:247], v[42:45]
	v_mfma_f32_16x16x128_f8f6f4 v[46:49], v[2:9], v[240:247], v[46:49]
	v_mfma_f32_16x16x128_f8f6f4 v[14:17], v[200:207], v[240:247], v[14:17]
	v_mfma_f32_16x16x128_f8f6f4 v[10:13], v[208:215], v[240:247], v[10:13]
	v_mfma_f32_16x16x128_f8f6f4 v[18:21], v[208:215], v[232:239], v[18:21]
	v_mfma_f32_16x16x128_f8f6f4 v[22:25], v[200:207], v[232:239], v[22:25]
	v_mfma_f32_16x16x128_f8f6f4 v[30:33], v[200:207], v[224:231], v[30:33]
	v_mfma_f32_16x16x128_f8f6f4 v[26:29], v[208:215], v[224:231], v[26:29]
	v_mfma_f32_16x16x128_f8f6f4 v[34:37], v[208:215], v[216:223], v[34:37]
	v_mfma_f32_16x16x128_f8f6f4 v[38:41], v[200:207], v[216:223], v[38:41]
	s_barrier
	s_setprio 0
	ds_read_b128 v[192:195], v189 offset:32768
	ds_read_b128 v[196:199], v189 offset:33792
	ds_read_b128 v[200:203], v189 offset:34816
	ds_read_b128 v[204:207], v189 offset:35840
	ds_read_b128 v[2:5], v189 offset:49152
	ds_read_b128 v[6:9], v189 offset:50176
	ds_read_b128 v[208:211], v189 offset:51200
	ds_read_b128 v[212:215], v189 offset:52224
	s_add_u32 s38, s38, 0x158000
	s_addc_u32 s39, s39, 0
	s_mov_b32 m0, s45
	v_lshl_add_u64 v[248:249], s[38:39], 0, v[154:155]
	ds_read_b128 v[216:219], v190 offset:32768
	ds_read_b128 v[220:223], v190 offset:33792
	ds_read_b128 v[224:227], v190 offset:34816
	ds_read_b128 v[228:231], v190 offset:35840
	ds_read_b128 v[232:235], v190 offset:36864
	ds_read_b128 v[236:239], v190 offset:37888
	ds_read_b128 v[240:243], v190 offset:38912
	ds_read_b128 v[244:247], v190 offset:39936
	global_load_lds_dwordx4 v[248:249], off
	v_lshl_add_u64 v[248:249], s[38:39], 0, v[158:159]
	s_mov_b32 m0, s46
	s_nop 0
	global_load_lds_dwordx4 v[248:249], off
	s_waitcnt vmcnt(8)
	s_waitcnt lgkmcnt(0)
	s_setprio 1
	s_barrier
	v_mfma_f32_16x16x128_f8f6f4 v[134:137], v[192:199], v[216:223], v[134:137]
	v_mfma_f32_16x16x128_f8f6f4 v[130:133], v[200:207], v[216:223], v[130:133]
	v_mfma_f32_16x16x128_f8f6f4 v[122:125], v[200:207], v[224:231], v[122:125]
	v_mfma_f32_16x16x128_f8f6f4 v[126:129], v[192:199], v[224:231], v[126:129]
	v_mfma_f32_16x16x128_f8f6f4 v[118:121], v[192:199], v[232:239], v[118:121]
	v_mfma_f32_16x16x128_f8f6f4 v[114:117], v[200:207], v[232:239], v[114:117]
	v_mfma_f32_16x16x128_f8f6f4 v[106:109], v[200:207], v[240:247], v[106:109]
	v_mfma_f32_16x16x128_f8f6f4 v[110:113], v[192:199], v[240:247], v[110:113]
	v_mfma_f32_16x16x128_f8f6f4 v[78:81], v[2:9], v[240:247], v[78:81]
	v_mfma_f32_16x16x128_f8f6f4 v[74:77], v[208:215], v[240:247], v[74:77]
	v_mfma_f32_16x16x128_f8f6f4 v[82:85], v[208:215], v[232:239], v[82:85]
	v_mfma_f32_16x16x128_f8f6f4 v[86:89], v[2:9], v[232:239], v[86:89]
	v_mfma_f32_16x16x128_f8f6f4 v[94:97], v[2:9], v[224:231], v[94:97]
	v_mfma_f32_16x16x128_f8f6f4 v[90:93], v[208:215], v[224:231], v[90:93]
	v_mfma_f32_16x16x128_f8f6f4 v[98:101], v[208:215], v[216:223], v[98:101]
	v_mfma_f32_16x16x128_f8f6f4 v[102:105], v[2:9], v[216:223], v[102:105]
	s_barrier
	s_setprio 0
	s_mov_b32 m0, s52
	v_lshl_add_u64 v[176:177], v[176:177], 0, s[14:15]
	s_add_u32 s26, s26, 0x158080
	ds_read_b128 v[216:219], v190 offset:49152
	ds_read_b128 v[220:223], v190 offset:50176
	ds_read_b128 v[224:227], v190 offset:51200
	ds_read_b128 v[228:231], v190 offset:52224
	ds_read_b128 v[232:235], v190 offset:53248
	ds_read_b128 v[236:239], v190 offset:54272
	ds_read_b128 v[240:243], v190 offset:55296
	ds_read_b128 v[244:247], v190 offset:56320
	global_load_lds_dwordx4 v[176:177], off
	v_lshl_add_u64 v[176:177], v[182:183], 0, s[14:15]
	s_mov_b32 m0, s53
	s_addc_u32 s27, s27, 0
	global_load_lds_dwordx4 v[176:177], off
	v_lshl_add_u64 v[176:177], s[26:27], 0, v[156:157]
	s_mov_b32 m0, s56
	s_nop 0
	global_load_lds_dwordx4 v[176:177], off
	v_lshl_add_u64 v[176:177], s[26:27], 0, v[160:161]
	s_mov_b32 m0, s57
	s_nop 0
	global_load_lds_dwordx4 v[176:177], off
	v_lshl_add_u64 v[176:177], v[184:185], 0, s[14:15]
	s_mov_b32 m0, s54
	s_nop 0
	global_load_lds_dwordx4 v[176:177], off
	v_lshl_add_u64 v[176:177], v[186:187], 0, s[14:15]
	s_mov_b32 m0, s55
	s_nop 0
	global_load_lds_dwordx4 v[176:177], off
	s_waitcnt vmcnt(8)
	s_waitcnt lgkmcnt(0)
	s_setprio 1
	s_barrier
	v_mfma_f32_16x16x128_f8f6f4 v[70:73], v[192:199], v[216:223], v[70:73]
	v_mfma_f32_16x16x128_f8f6f4 v[66:69], v[200:207], v[216:223], v[66:69]
	v_mfma_f32_16x16x128_f8f6f4 v[58:61], v[200:207], v[224:231], v[58:61]
	v_mfma_f32_16x16x128_f8f6f4 v[62:65], v[192:199], v[224:231], v[62:65]
	v_mfma_f32_16x16x128_f8f6f4 v[54:57], v[192:199], v[232:239], v[54:57]
	v_mfma_f32_16x16x128_f8f6f4 v[50:53], v[200:207], v[232:239], v[50:53]
	v_mfma_f32_16x16x128_f8f6f4 v[42:45], v[200:207], v[240:247], v[42:45]
	v_mfma_f32_16x16x128_f8f6f4 v[46:49], v[192:199], v[240:247], v[46:49]
	v_mfma_f32_16x16x128_f8f6f4 v[14:17], v[2:9], v[240:247], v[14:17]
	v_mfma_f32_16x16x128_f8f6f4 v[10:13], v[208:215], v[240:247], v[10:13]
	v_mfma_f32_16x16x128_f8f6f4 v[18:21], v[208:215], v[232:239], v[18:21]
	v_mfma_f32_16x16x128_f8f6f4 v[22:25], v[2:9], v[232:239], v[22:25]
	v_mfma_f32_16x16x128_f8f6f4 v[30:33], v[2:9], v[224:231], v[30:33]
	v_mfma_f32_16x16x128_f8f6f4 v[26:29], v[208:215], v[224:231], v[26:29]
	v_mfma_f32_16x16x128_f8f6f4 v[34:37], v[208:215], v[216:223], v[34:37]
	v_mfma_f32_16x16x128_f8f6f4 v[38:41], v[2:9], v[216:223], v[38:41]
	s_barrier
	s_setprio 0
	s_add_i32 s26, s84, 2
	s_add_u32 s36, s36, 0x100
	s_addc_u32 s37, s37, 0
	s_add_u32 s40, s40, 0x100
	s_addc_u32 s41, s41, 0
	s_cmp_ge_i32 s84, s82
	s_cbranch_scc1 .LBB0_1036
	s_mov_b32 s84, s26
	s_cmp_eq_u32 s82, s84
	s_cselect_b64 s[26:27], -1, 0
	s_cmp_lg_u32 s82, s84
	s_cbranch_scc0 .LBB0_1033
	s_branch .LBB0_1034
